# EpiRes f32-source ring, attention score-row prefetch, stats-load hoist in EpiRaw/EpiRawT/EpiSgu epilogues
# speedup vs baseline: 1.0415x; 1.0075x over previous
; __device__ __forceinline__ unsigned fkey(float f) { const unsigned u = __float_as_uint(f); return (u & 0x80000000u) ? ~u : (u | 0x80000000u); }
; __device__ __forceinline__ void attn_phase(const int TID, const int BID, PP p, LAS unsigned char* lds) {
;     ...
;             const _Float16* srow = Sc + (size_t)tok * SEQ;
; #pragma unroll
;             for (int i = 0; i < 16; ++i) {
;                 const int k0 = i * 256 + 4 * ln;
;                 if (k0 < Nk) { typedef _Float16 h16x4 __attribute__((ext_vector_type(4))); const h16x4 hv = *(const h16x4*)(srow + k0); const f32x4 v = (f32x4){(float)hv[0], (float)hv[1], (float)hv[2], (float)hv[3]};
; #pragma unroll
;                     for (int e = 0; e < 4; ++e) key[4 * i + e] = fkey(v[e]); }
;                 else {
; #pragma unroll
;                     for (int e = 0; e < 4; ++e) key[4 * i + e] = 0u; }
;             }
.LBB0_103:
	s_and_b32 s87, s66, 0xfc0
	s_add_i32 s72, s87, 64
	s_cmpk_gt_u32 s87, 0xc0
	s_mov_b64 s[10:11], -1
	s_cbranch_scc0 .LBB0_685
	s_ashr_i32 s67, s66, 31
	v_mov_b32_e32 v0, v83
	s_lshl_b64 s[0:1], s[66:67], 13
	s_add_u32 s10, s64, s0
	v_lshlrev_b32_e32 v16, 2, v0
	s_addc_u32 s11, s74, s1
	v_lshlrev_b32_e32 v241, 1, v16
	v_add_u32_e32 v242, 0x1000, v241
	global_load_dwordx2 v[208:209], v241, s[10:11]
	s_cmpk_le_u32 s72, 0x100
	s_cbranch_scc1 .Lkeys_issued
	v_add_u32_e32 v240, 0x100, v16
	v_cmp_gt_i32_e32 vcc, s72, v240
	s_and_saveexec_b64 s[12:13], vcc
	global_load_dwordx2 v[210:211], v241, s[10:11] offset:512
	s_mov_b64 exec, s[12:13]
	s_cmpk_le_u32 s72, 0x200
	s_cbranch_scc1 .Lkeys_issued
	v_add_u32_e32 v240, 0x200, v16
	v_cmp_gt_i32_e32 vcc, s72, v240
	s_and_saveexec_b64 s[12:13], vcc
	global_load_dwordx2 v[212:213], v241, s[10:11] offset:1024
	s_mov_b64 exec, s[12:13]
	s_cmpk_le_u32 s72, 0x300
	s_cbranch_scc1 .Lkeys_issued
	v_add_u32_e32 v240, 0x300, v16
	v_cmp_gt_i32_e32 vcc, s72, v240
	s_and_saveexec_b64 s[12:13], vcc
	global_load_dwordx2 v[214:215], v241, s[10:11] offset:1536
	s_mov_b64 exec, s[12:13]
	s_cmpk_le_u32 s72, 0x400
	s_cbranch_scc1 .Lkeys_issued
	v_add_u32_e32 v240, 0x400, v16
	v_cmp_gt_i32_e32 vcc, s72, v240
	s_and_saveexec_b64 s[12:13], vcc
	global_load_dwordx2 v[216:217], v241, s[10:11] offset:2048
	s_mov_b64 exec, s[12:13]
	s_cmpk_le_u32 s72, 0x500
	s_cbranch_scc1 .Lkeys_issued
	v_add_u32_e32 v240, 0x500, v16
	v_cmp_gt_i32_e32 vcc, s72, v240
	s_and_saveexec_b64 s[12:13], vcc
	global_load_dwordx2 v[218:219], v241, s[10:11] offset:2560
	s_mov_b64 exec, s[12:13]
	s_cmpk_le_u32 s72, 0x600
	s_cbranch_scc1 .Lkeys_issued
	v_add_u32_e32 v240, 0x600, v16
	v_cmp_gt_i32_e32 vcc, s72, v240
	s_and_saveexec_b64 s[12:13], vcc
	global_load_dwordx2 v[220:221], v241, s[10:11] offset:3072
	s_mov_b64 exec, s[12:13]
	s_cmpk_le_u32 s72, 0x700
	s_cbranch_scc1 .Lkeys_issued
	v_add_u32_e32 v240, 0x700, v16
	v_cmp_gt_i32_e32 vcc, s72, v240
	s_and_saveexec_b64 s[12:13], vcc
	global_load_dwordx2 v[222:223], v241, s[10:11] offset:3584
	s_mov_b64 exec, s[12:13]
	s_cmpk_le_u32 s72, 0x800
	s_cbranch_scc1 .Lkeys_issued
	v_add_u32_e32 v240, 0x800, v16
	v_cmp_gt_i32_e32 vcc, s72, v240
	s_and_saveexec_b64 s[12:13], vcc
	global_load_dwordx2 v[224:225], v242, s[10:11]
	s_mov_b64 exec, s[12:13]
	s_cmpk_le_u32 s72, 0x900
	s_cbranch_scc1 .Lkeys_issued
	v_add_u32_e32 v240, 0x900, v16
	v_cmp_gt_i32_e32 vcc, s72, v240
	s_and_saveexec_b64 s[12:13], vcc
	global_load_dwordx2 v[226:227], v242, s[10:11] offset:512
	s_mov_b64 exec, s[12:13]
	s_cmpk_le_u32 s72, 0xa00
	s_cbranch_scc1 .Lkeys_issued
	v_add_u32_e32 v240, 0xa00, v16
	v_cmp_gt_i32_e32 vcc, s72, v240
	s_and_saveexec_b64 s[12:13], vcc
	global_load_dwordx2 v[228:229], v242, s[10:11] offset:1024
	s_mov_b64 exec, s[12:13]
	s_cmpk_le_u32 s72, 0xb00
	s_cbranch_scc1 .Lkeys_issued
	v_add_u32_e32 v240, 0xb00, v16
	v_cmp_gt_i32_e32 vcc, s72, v240
	s_and_saveexec_b64 s[12:13], vcc
	global_load_dwordx2 v[230:231], v242, s[10:11] offset:1536
	s_mov_b64 exec, s[12:13]
	s_cmpk_le_u32 s72, 0xc00
	s_cbranch_scc1 .Lkeys_issued
	v_add_u32_e32 v240, 0xc00, v16
	v_cmp_gt_i32_e32 vcc, s72, v240
	s_and_saveexec_b64 s[12:13], vcc
	global_load_dwordx2 v[232:233], v242, s[10:11] offset:2048
	s_mov_b64 exec, s[12:13]
	s_cmpk_le_u32 s72, 0xd00
	s_cbranch_scc1 .Lkeys_issued
	v_add_u32_e32 v240, 0xd00, v16
	v_cmp_gt_i32_e32 vcc, s72, v240
	s_and_saveexec_b64 s[12:13], vcc
	global_load_dwordx2 v[234:235], v242, s[10:11] offset:2560
	s_mov_b64 exec, s[12:13]
	s_cmpk_le_u32 s72, 0xe00
	s_cbranch_scc1 .Lkeys_issued
	v_add_u32_e32 v240, 0xe00, v16
	v_cmp_gt_i32_e32 vcc, s72, v240
	s_and_saveexec_b64 s[12:13], vcc
	global_load_dwordx2 v[236:237], v242, s[10:11] offset:3072
	s_mov_b64 exec, s[12:13]
	s_cmpk_le_u32 s72, 0xf00
	s_cbranch_scc1 .Lkeys_issued
	v_add_u32_e32 v240, 0xf00, v16
	v_cmp_gt_i32_e32 vcc, s72, v240
	s_and_saveexec_b64 s[12:13], vcc
	global_load_dwordx2 v[238:239], v242, s[10:11] offset:3584
	s_mov_b64 exec, s[12:13]
.Lkeys_issued:
	v_cmp_gt_i32_e32 vcc, s72, v16
	v_mov_b32_e32 v71, 0
	v_ashrrev_i32_e32 v17, 31, v16
	v_mov_b32_e32 v78, 0
	v_mov_b32_e32 v76, 0
	v_mov_b32_e32 v86, 0
	v_mov_b32_e32 v79, 0
	s_and_saveexec_b64 s[12:13], vcc
	s_cbranch_execz .LBB0_106
	s_waitcnt vmcnt(0)
	v_mov_b64_e32 v[0:1], v[208:209]
	v_cvt_f32_f16_sdwa v4, v0 dst_sel:DWORD dst_unused:UNUSED_PAD src0_sel:WORD_1
	v_cvt_f32_f16_e32 v5, v0
	v_cvt_f32_f16_e32 v6, v1
	v_cvt_f32_f16_sdwa v7, v1 dst_sel:DWORD dst_unused:UNUSED_PAD src0_sel:WORD_1
	v_and_b32_e32 v1, 0x7fffffff, v4
	v_and_b32_e32 v0, 0x7fffffff, v5
	v_xor_b32_e32 v9, -1, v5
	v_pk_add_f32 v[0:1], v[0:1], 0 neg_lo:[1,1] neg_hi:[1,1]
	v_cmp_gt_i32_e32 vcc, 0, v5
	v_xor_b32_e32 v8, -1, v4
	v_and_b32_e32 v2, 0x7fffffff, v6
	v_and_b32_e32 v3, 0x7fffffff, v7
	v_cndmask_b32_e32 v86, v0, v9, vcc
	v_cmp_gt_i32_e32 vcc, 0, v4
	v_xor_b32_e32 v11, -1, v6
	v_pk_add_f32 v[2:3], v[2:3], 0 neg_lo:[1,1] neg_hi:[1,1]
	v_cndmask_b32_e32 v79, v1, v8, vcc
	v_cmp_gt_i32_e32 vcc, 0, v6
	v_xor_b32_e32 v10, -1, v7
	s_nop 0
	v_cndmask_b32_e32 v78, v2, v11, vcc
	v_cmp_gt_i32_e32 vcc, 0, v7
	s_nop 1
	v_cndmask_b32_e32 v76, v3, v10, vcc
; __device__ __forceinline__ unsigned fkey(float f) { const unsigned u = __float_as_uint(f); return (u & 0x80000000u) ? ~u : (u | 0x80000000u); }
; __device__ __forceinline__ void attn_phase(const int TID, const int BID, PP p, LAS unsigned char* lds) {
;     ...
;             for (int i = 0; i < 16; ++i) {
;                 const int k0 = i * 256 + 4 * ln;
;                 if (k0 < Nk) { typedef _Float16 h16x4 __attribute__((ext_vector_type(4))); const h16x4 hv = *(const h16x4*)(srow + k0); const f32x4 v = (f32x4){(float)hv[0], (float)hv[1], (float)hv[2], (float)hv[3]};
; #pragma unroll
;                     for (int e = 0; e < 4; ++e) key[4 * i + e] = fkey(v[e]); }
;                 else {
; #pragma unroll
;                     for (int e = 0; e < 4; ++e) key[4 * i + e] = 0u; }
;             }
.LBB0_106:
	s_or_b64 exec, exec, s[12:13]
	v_add_u32_e32 v70, 0x100, v16
	v_cmp_gt_i32_e32 vcc, s72, v70
	v_mov_b32_e32 v73, 0
	v_mov_b32_e32 v77, 0
	v_mov_b32_e32 v75, 0
	s_and_saveexec_b64 s[12:13], vcc
	s_cbranch_execz .LBB0_108
	v_mov_b64_e32 v[0:1], v[210:211]
	v_cvt_f32_f16_sdwa v4, v0 dst_sel:DWORD dst_unused:UNUSED_PAD src0_sel:WORD_1
	v_cvt_f32_f16_e32 v5, v0
	v_cvt_f32_f16_e32 v6, v1
	v_cvt_f32_f16_sdwa v7, v1 dst_sel:DWORD dst_unused:UNUSED_PAD src0_sel:WORD_1
	v_and_b32_e32 v1, 0x7fffffff, v4
	v_and_b32_e32 v0, 0x7fffffff, v5
	v_xor_b32_e32 v9, -1, v5
	v_pk_add_f32 v[0:1], v[0:1], 0 neg_lo:[1,1] neg_hi:[1,1]
	v_cmp_gt_i32_e32 vcc, 0, v5
	v_xor_b32_e32 v8, -1, v4
	v_and_b32_e32 v2, 0x7fffffff, v6
	v_and_b32_e32 v3, 0x7fffffff, v7
	v_cndmask_b32_e32 v77, v0, v9, vcc
	v_cmp_gt_i32_e32 vcc, 0, v4
	v_xor_b32_e32 v11, -1, v6
	v_pk_add_f32 v[2:3], v[2:3], 0 neg_lo:[1,1] neg_hi:[1,1]
	v_cndmask_b32_e32 v75, v1, v8, vcc
	v_cmp_gt_i32_e32 vcc, 0, v6
	v_xor_b32_e32 v10, -1, v7
	s_nop 0
	v_cndmask_b32_e32 v71, v2, v11, vcc
	v_cmp_gt_i32_e32 vcc, 0, v7
	s_nop 1
	v_cndmask_b32_e32 v73, v3, v10, vcc
.LBB0_108:
	s_or_b64 exec, exec, s[12:13]
	v_add_u32_e32 v65, 0x200, v16
	v_cmp_gt_i32_e32 vcc, s72, v65
	v_mov_b32_e32 v59, 0
	v_mov_b32_e32 v69, 0
	v_mov_b32_e32 v68, 0
	v_mov_b32_e32 v74, 0
	v_mov_b32_e32 v72, 0
	s_and_saveexec_b64 s[12:13], vcc
	s_cbranch_execz .LBB0_110
	v_mov_b64_e32 v[0:1], v[212:213]
	v_cvt_f32_f16_sdwa v4, v0 dst_sel:DWORD dst_unused:UNUSED_PAD src0_sel:WORD_1
	v_cvt_f32_f16_e32 v5, v0
	v_cvt_f32_f16_e32 v6, v1
	v_cvt_f32_f16_sdwa v7, v1 dst_sel:DWORD dst_unused:UNUSED_PAD src0_sel:WORD_1
	v_and_b32_e32 v1, 0x7fffffff, v4
	v_and_b32_e32 v0, 0x7fffffff, v5
	v_xor_b32_e32 v9, -1, v5
	v_pk_add_f32 v[0:1], v[0:1], 0 neg_lo:[1,1] neg_hi:[1,1]
	v_cmp_gt_i32_e32 vcc, 0, v5
	v_xor_b32_e32 v8, -1, v4
	v_and_b32_e32 v2, 0x7fffffff, v6
	v_and_b32_e32 v3, 0x7fffffff, v7
	v_cndmask_b32_e32 v74, v0, v9, vcc
	v_cmp_gt_i32_e32 vcc, 0, v4
	v_xor_b32_e32 v11, -1, v6
	v_pk_add_f32 v[2:3], v[2:3], 0 neg_lo:[1,1] neg_hi:[1,1]
	v_cndmask_b32_e32 v72, v1, v8, vcc
	v_cmp_gt_i32_e32 vcc, 0, v6
	v_xor_b32_e32 v10, -1, v7
	s_nop 0
	v_cndmask_b32_e32 v69, v2, v11, vcc
	v_cmp_gt_i32_e32 vcc, 0, v7
	s_nop 1
	v_cndmask_b32_e32 v68, v3, v10, vcc
.LBB0_110:
	s_or_b64 exec, exec, s[12:13]
	v_add_u32_e32 v61, 0x300, v16
	v_cmp_gt_i32_e32 vcc, s72, v61
	v_mov_b32_e32 v63, 0
	v_mov_b32_e32 v67, 0
	v_mov_b32_e32 v66, 0
	s_and_saveexec_b64 s[12:13], vcc
	s_cbranch_execz .LBB0_112
	v_mov_b64_e32 v[0:1], v[214:215]
	v_cvt_f32_f16_sdwa v4, v0 dst_sel:DWORD dst_unused:UNUSED_PAD src0_sel:WORD_1
	v_cvt_f32_f16_e32 v5, v0
	v_cvt_f32_f16_e32 v6, v1
	v_cvt_f32_f16_sdwa v7, v1 dst_sel:DWORD dst_unused:UNUSED_PAD src0_sel:WORD_1
	v_and_b32_e32 v1, 0x7fffffff, v4
	v_and_b32_e32 v0, 0x7fffffff, v5
	v_xor_b32_e32 v9, -1, v5
	v_pk_add_f32 v[0:1], v[0:1], 0 neg_lo:[1,1] neg_hi:[1,1]
	v_cmp_gt_i32_e32 vcc, 0, v5
	v_xor_b32_e32 v8, -1, v4
	v_and_b32_e32 v2, 0x7fffffff, v6
	v_and_b32_e32 v3, 0x7fffffff, v7
	v_cndmask_b32_e32 v67, v0, v9, vcc
	v_cmp_gt_i32_e32 vcc, 0, v4
	v_xor_b32_e32 v11, -1, v6
	v_pk_add_f32 v[2:3], v[2:3], 0 neg_lo:[1,1] neg_hi:[1,1]
	v_cndmask_b32_e32 v66, v1, v8, vcc
	v_cmp_gt_i32_e32 vcc, 0, v6
	v_xor_b32_e32 v10, -1, v7
	s_nop 0
	v_cndmask_b32_e32 v59, v2, v11, vcc
	v_cmp_gt_i32_e32 vcc, 0, v7
	s_nop 1
	v_cndmask_b32_e32 v63, v3, v10, vcc
.LBB0_112:
	s_or_b64 exec, exec, s[12:13]
	v_add_u32_e32 v55, 0x400, v16
	v_cmp_gt_i32_e32 vcc, s72, v55
	v_mov_b32_e32 v50, 0
	v_mov_b32_e32 v60, 0
	v_mov_b32_e32 v58, 0
	v_mov_b32_e32 v64, 0
	v_mov_b32_e32 v62, 0
	s_and_saveexec_b64 s[12:13], vcc
	s_cbranch_execz .LBB0_114
	v_mov_b64_e32 v[0:1], v[216:217]
	v_cvt_f32_f16_sdwa v4, v0 dst_sel:DWORD dst_unused:UNUSED_PAD src0_sel:WORD_1
	v_cvt_f32_f16_e32 v5, v0
	v_cvt_f32_f16_e32 v6, v1
	v_cvt_f32_f16_sdwa v7, v1 dst_sel:DWORD dst_unused:UNUSED_PAD src0_sel:WORD_1
	v_and_b32_e32 v1, 0x7fffffff, v4
	v_and_b32_e32 v0, 0x7fffffff, v5
	v_xor_b32_e32 v9, -1, v5
	v_pk_add_f32 v[0:1], v[0:1], 0 neg_lo:[1,1] neg_hi:[1,1]
	v_cmp_gt_i32_e32 vcc, 0, v5
	v_xor_b32_e32 v8, -1, v4
	v_and_b32_e32 v2, 0x7fffffff, v6
	v_and_b32_e32 v3, 0x7fffffff, v7
	v_cndmask_b32_e32 v64, v0, v9, vcc
	v_cmp_gt_i32_e32 vcc, 0, v4
	v_xor_b32_e32 v11, -1, v6
	v_pk_add_f32 v[2:3], v[2:3], 0 neg_lo:[1,1] neg_hi:[1,1]
	v_cndmask_b32_e32 v62, v1, v8, vcc
	v_cmp_gt_i32_e32 vcc, 0, v6
	v_xor_b32_e32 v10, -1, v7
	s_nop 0
	v_cndmask_b32_e32 v60, v2, v11, vcc
	v_cmp_gt_i32_e32 vcc, 0, v7
	s_nop 1
	v_cndmask_b32_e32 v58, v3, v10, vcc
.LBB0_114:
	s_or_b64 exec, exec, s[12:13]
	v_add_u32_e32 v52, 0x500, v16
	v_cmp_gt_i32_e32 vcc, s72, v52
	v_mov_b32_e32 v54, 0
	v_mov_b32_e32 v57, 0
	v_mov_b32_e32 v56, 0
	s_and_saveexec_b64 s[12:13], vcc
	s_cbranch_execz .LBB0_116
	v_mov_b64_e32 v[0:1], v[218:219]
	v_cvt_f32_f16_sdwa v4, v0 dst_sel:DWORD dst_unused:UNUSED_PAD src0_sel:WORD_1
	v_cvt_f32_f16_e32 v5, v0
	v_cvt_f32_f16_e32 v6, v1
	v_cvt_f32_f16_sdwa v7, v1 dst_sel:DWORD dst_unused:UNUSED_PAD src0_sel:WORD_1
	v_and_b32_e32 v1, 0x7fffffff, v4
	v_and_b32_e32 v0, 0x7fffffff, v5
	v_xor_b32_e32 v9, -1, v5
	v_pk_add_f32 v[0:1], v[0:1], 0 neg_lo:[1,1] neg_hi:[1,1]
	v_cmp_gt_i32_e32 vcc, 0, v5
	v_xor_b32_e32 v8, -1, v4
	v_and_b32_e32 v2, 0x7fffffff, v6
	v_and_b32_e32 v3, 0x7fffffff, v7
	v_cndmask_b32_e32 v57, v0, v9, vcc
	v_cmp_gt_i32_e32 vcc, 0, v4
	v_xor_b32_e32 v11, -1, v6
	v_pk_add_f32 v[2:3], v[2:3], 0 neg_lo:[1,1] neg_hi:[1,1]
	v_cndmask_b32_e32 v56, v1, v8, vcc
	v_cmp_gt_i32_e32 vcc, 0, v6
	v_xor_b32_e32 v10, -1, v7
	s_nop 0
	v_cndmask_b32_e32 v50, v2, v11, vcc
	v_cmp_gt_i32_e32 vcc, 0, v7
	s_nop 1
	v_cndmask_b32_e32 v54, v3, v10, vcc
; __device__ __forceinline__ unsigned fkey(float f) { const unsigned u = __float_as_uint(f); return (u & 0x80000000u) ? ~u : (u | 0x80000000u); }
; __device__ __forceinline__ void attn_phase(const int TID, const int BID, PP p, LAS unsigned char* lds) {
;     ...
;             for (int i = 0; i < 16; ++i) {
;                 const int k0 = i * 256 + 4 * ln;
;                 if (k0 < Nk) { typedef _Float16 h16x4 __attribute__((ext_vector_type(4))); const h16x4 hv = *(const h16x4*)(srow + k0); const f32x4 v = (f32x4){(float)hv[0], (float)hv[1], (float)hv[2], (float)hv[3]};
; #pragma unroll
;                     for (int e = 0; e < 4; ++e) key[4 * i + e] = fkey(v[e]); }
;                 else {
; #pragma unroll
;                     for (int e = 0; e < 4; ++e) key[4 * i + e] = 0u; }
;             }
.LBB0_116:
	s_or_b64 exec, exec, s[12:13]
	v_add_u32_e32 v46, 0x600, v16
	v_cmp_gt_i32_e32 vcc, s72, v46
	v_mov_b32_e32 v42, 0
	v_mov_b32_e32 v49, 0
	v_mov_b32_e32 v48, 0
	v_mov_b32_e32 v53, 0
	v_mov_b32_e32 v51, 0
	s_and_saveexec_b64 s[12:13], vcc
	s_cbranch_execz .LBB0_118
	v_mov_b64_e32 v[0:1], v[220:221]
	v_cvt_f32_f16_sdwa v4, v0 dst_sel:DWORD dst_unused:UNUSED_PAD src0_sel:WORD_1
	v_cvt_f32_f16_e32 v5, v0
	v_cvt_f32_f16_e32 v6, v1
	v_cvt_f32_f16_sdwa v7, v1 dst_sel:DWORD dst_unused:UNUSED_PAD src0_sel:WORD_1
	v_and_b32_e32 v1, 0x7fffffff, v4
	v_and_b32_e32 v0, 0x7fffffff, v5
	v_xor_b32_e32 v9, -1, v5
	v_pk_add_f32 v[0:1], v[0:1], 0 neg_lo:[1,1] neg_hi:[1,1]
	v_cmp_gt_i32_e32 vcc, 0, v5
	v_xor_b32_e32 v8, -1, v4
	v_and_b32_e32 v2, 0x7fffffff, v6
	v_and_b32_e32 v3, 0x7fffffff, v7
	v_cndmask_b32_e32 v53, v0, v9, vcc
	v_cmp_gt_i32_e32 vcc, 0, v4
	v_xor_b32_e32 v11, -1, v6
	v_pk_add_f32 v[2:3], v[2:3], 0 neg_lo:[1,1] neg_hi:[1,1]
	v_cndmask_b32_e32 v51, v1, v8, vcc
	v_cmp_gt_i32_e32 vcc, 0, v6
	v_xor_b32_e32 v10, -1, v7
	s_nop 0
	v_cndmask_b32_e32 v49, v2, v11, vcc
	v_cmp_gt_i32_e32 vcc, 0, v7
	s_nop 1
	v_cndmask_b32_e32 v48, v3, v10, vcc
.LBB0_118:
	s_or_b64 exec, exec, s[12:13]
	v_add_u32_e32 v41, 0x700, v16
	v_cmp_gt_i32_e32 vcc, s72, v41
	v_mov_b32_e32 v44, 0
	v_mov_b32_e32 v47, 0
	v_mov_b32_e32 v45, 0
	s_and_saveexec_b64 s[12:13], vcc
	s_cbranch_execz .LBB0_120
	v_mov_b64_e32 v[0:1], v[222:223]
	v_cvt_f32_f16_sdwa v4, v0 dst_sel:DWORD dst_unused:UNUSED_PAD src0_sel:WORD_1
	v_cvt_f32_f16_e32 v5, v0
	v_cvt_f32_f16_e32 v6, v1
	v_cvt_f32_f16_sdwa v7, v1 dst_sel:DWORD dst_unused:UNUSED_PAD src0_sel:WORD_1
	v_and_b32_e32 v1, 0x7fffffff, v4
	v_and_b32_e32 v0, 0x7fffffff, v5
	v_xor_b32_e32 v9, -1, v5
	v_pk_add_f32 v[0:1], v[0:1], 0 neg_lo:[1,1] neg_hi:[1,1]
	v_cmp_gt_i32_e32 vcc, 0, v5
	v_xor_b32_e32 v8, -1, v4
	v_and_b32_e32 v2, 0x7fffffff, v6
	v_and_b32_e32 v3, 0x7fffffff, v7
	v_cndmask_b32_e32 v47, v0, v9, vcc
	v_cmp_gt_i32_e32 vcc, 0, v4
	v_xor_b32_e32 v11, -1, v6
	v_pk_add_f32 v[2:3], v[2:3], 0 neg_lo:[1,1] neg_hi:[1,1]
	v_cndmask_b32_e32 v45, v1, v8, vcc
	v_cmp_gt_i32_e32 vcc, 0, v6
	v_xor_b32_e32 v10, -1, v7
	s_nop 0
	v_cndmask_b32_e32 v42, v2, v11, vcc
	v_cmp_gt_i32_e32 vcc, 0, v7
	s_nop 1
	v_cndmask_b32_e32 v44, v3, v10, vcc
.LBB0_120:
	s_or_b64 exec, exec, s[12:13]
	v_add_u32_e32 v14, 0x800, v16
	v_cmp_gt_i32_e32 vcc, s72, v14
	v_mov_b32_e32 v33, 0
	v_mov_b32_e32 v39, 0
	v_mov_b32_e32 v38, 0
	v_mov_b32_e32 v43, 0
	v_mov_b32_e32 v40, 0
	s_and_saveexec_b64 s[12:13], vcc
	s_cbranch_execz .LBB0_122
	v_ashrrev_i32_e32 v15, 31, v14
	v_mov_b64_e32 v[0:1], v[224:225]
	v_cvt_f32_f16_sdwa v4, v0 dst_sel:DWORD dst_unused:UNUSED_PAD src0_sel:WORD_1
	v_cvt_f32_f16_e32 v5, v0
	v_cvt_f32_f16_e32 v6, v1
	v_cvt_f32_f16_sdwa v7, v1 dst_sel:DWORD dst_unused:UNUSED_PAD src0_sel:WORD_1
	v_and_b32_e32 v1, 0x7fffffff, v4
	v_and_b32_e32 v0, 0x7fffffff, v5
	v_xor_b32_e32 v9, -1, v5
	v_pk_add_f32 v[0:1], v[0:1], 0 neg_lo:[1,1] neg_hi:[1,1]
	v_cmp_gt_i32_e32 vcc, 0, v5
	v_xor_b32_e32 v8, -1, v4
	v_and_b32_e32 v2, 0x7fffffff, v6
	v_and_b32_e32 v3, 0x7fffffff, v7
	v_cndmask_b32_e32 v43, v0, v9, vcc
	v_cmp_gt_i32_e32 vcc, 0, v4
	v_xor_b32_e32 v11, -1, v6
	v_pk_add_f32 v[2:3], v[2:3], 0 neg_lo:[1,1] neg_hi:[1,1]
	v_cndmask_b32_e32 v40, v1, v8, vcc
	v_cmp_gt_i32_e32 vcc, 0, v6
	v_xor_b32_e32 v10, -1, v7
	s_nop 0
	v_cndmask_b32_e32 v39, v2, v11, vcc
	v_cmp_gt_i32_e32 vcc, 0, v7
	s_nop 1
	v_cndmask_b32_e32 v38, v3, v10, vcc
.LBB0_122:
	s_or_b64 exec, exec, s[12:13]
	v_add_u32_e32 v12, 0x900, v16
	v_cmp_gt_i32_e32 vcc, s72, v12
	v_mov_b32_e32 v35, 0
	v_mov_b32_e32 v37, 0
	v_mov_b32_e32 v36, 0
	s_and_saveexec_b64 s[12:13], vcc
	s_cbranch_execz .LBB0_124
	v_ashrrev_i32_e32 v13, 31, v12
	v_mov_b64_e32 v[0:1], v[226:227]
	v_cvt_f32_f16_sdwa v4, v0 dst_sel:DWORD dst_unused:UNUSED_PAD src0_sel:WORD_1
	v_cvt_f32_f16_e32 v5, v0
	v_cvt_f32_f16_e32 v6, v1
	v_cvt_f32_f16_sdwa v7, v1 dst_sel:DWORD dst_unused:UNUSED_PAD src0_sel:WORD_1
	v_and_b32_e32 v1, 0x7fffffff, v4
	v_and_b32_e32 v0, 0x7fffffff, v5
	v_xor_b32_e32 v9, -1, v5
	v_pk_add_f32 v[0:1], v[0:1], 0 neg_lo:[1,1] neg_hi:[1,1]
	v_cmp_gt_i32_e32 vcc, 0, v5
	v_xor_b32_e32 v8, -1, v4
	v_and_b32_e32 v2, 0x7fffffff, v6
	v_and_b32_e32 v3, 0x7fffffff, v7
	v_cndmask_b32_e32 v37, v0, v9, vcc
	v_cmp_gt_i32_e32 vcc, 0, v4
	v_xor_b32_e32 v11, -1, v6
	v_pk_add_f32 v[2:3], v[2:3], 0 neg_lo:[1,1] neg_hi:[1,1]
	v_cndmask_b32_e32 v36, v1, v8, vcc
	v_cmp_gt_i32_e32 vcc, 0, v6
	v_xor_b32_e32 v10, -1, v7
	s_nop 0
	v_cndmask_b32_e32 v33, v2, v11, vcc
	v_cmp_gt_i32_e32 vcc, 0, v7
	s_nop 1
	v_cndmask_b32_e32 v35, v3, v10, vcc
.LBB0_124:
	s_or_b64 exec, exec, s[12:13]
	v_add_u32_e32 v10, 0xa00, v16
	v_cmp_gt_i32_e32 vcc, s72, v10
	v_mov_b32_e32 v25, 0
	v_mov_b32_e32 v31, 0
	v_mov_b32_e32 v30, 0
	v_mov_b32_e32 v34, 0
	v_mov_b32_e32 v32, 0
	s_and_saveexec_b64 s[12:13], vcc
	s_cbranch_execz .LBB0_126
	v_ashrrev_i32_e32 v11, 31, v10
	v_mov_b64_e32 v[0:1], v[228:229]
	v_cvt_f32_f16_sdwa v4, v0 dst_sel:DWORD dst_unused:UNUSED_PAD src0_sel:WORD_1
	v_cvt_f32_f16_e32 v5, v0
	v_cvt_f32_f16_e32 v6, v1
	v_cvt_f32_f16_sdwa v7, v1 dst_sel:DWORD dst_unused:UNUSED_PAD src0_sel:WORD_1
	v_and_b32_e32 v1, 0x7fffffff, v4
	v_and_b32_e32 v0, 0x7fffffff, v5
	v_xor_b32_e32 v9, -1, v5
	v_pk_add_f32 v[0:1], v[0:1], 0 neg_lo:[1,1] neg_hi:[1,1]
	v_cmp_gt_i32_e32 vcc, 0, v5
	v_xor_b32_e32 v8, -1, v4
	v_and_b32_e32 v2, 0x7fffffff, v6
	v_and_b32_e32 v3, 0x7fffffff, v7
	v_cndmask_b32_e32 v34, v0, v9, vcc
	v_cmp_gt_i32_e32 vcc, 0, v4
	v_xor_b32_e32 v13, -1, v6
	v_pk_add_f32 v[2:3], v[2:3], 0 neg_lo:[1,1] neg_hi:[1,1]
	v_cndmask_b32_e32 v32, v1, v8, vcc
	v_cmp_gt_i32_e32 vcc, 0, v6
	v_xor_b32_e32 v11, -1, v7
	s_nop 0
	v_cndmask_b32_e32 v31, v2, v13, vcc
	v_cmp_gt_i32_e32 vcc, 0, v7
	s_nop 1
	v_cndmask_b32_e32 v30, v3, v11, vcc
; __device__ __forceinline__ unsigned fkey(float f) { const unsigned u = __float_as_uint(f); return (u & 0x80000000u) ? ~u : (u | 0x80000000u); }
; __device__ __forceinline__ void attn_phase(const int TID, const int BID, PP p, LAS unsigned char* lds) {
;     ...
;             for (int i = 0; i < 16; ++i) {
;                 const int k0 = i * 256 + 4 * ln;
;                 if (k0 < Nk) { typedef _Float16 h16x4 __attribute__((ext_vector_type(4))); const h16x4 hv = *(const h16x4*)(srow + k0); const f32x4 v = (f32x4){(float)hv[0], (float)hv[1], (float)hv[2], (float)hv[3]};
; #pragma unroll
;                     for (int e = 0; e < 4; ++e) key[4 * i + e] = fkey(v[e]); }
;                 else {
; #pragma unroll
;                     for (int e = 0; e < 4; ++e) key[4 * i + e] = 0u; }
;             }
.LBB0_126:
	s_or_b64 exec, exec, s[12:13]
	v_add_u32_e32 v8, 0xb00, v16
	v_cmp_gt_i32_e32 vcc, s72, v8
	v_mov_b32_e32 v27, 0
	v_mov_b32_e32 v29, 0
	v_mov_b32_e32 v28, 0
	s_and_saveexec_b64 s[12:13], vcc
	s_cbranch_execz .LBB0_128
	v_ashrrev_i32_e32 v9, 31, v8
	v_mov_b64_e32 v[0:1], v[230:231]
	v_cvt_f32_f16_sdwa v4, v0 dst_sel:DWORD dst_unused:UNUSED_PAD src0_sel:WORD_1
	v_cvt_f32_f16_e32 v5, v0
	v_cvt_f32_f16_e32 v6, v1
	v_cvt_f32_f16_sdwa v7, v1 dst_sel:DWORD dst_unused:UNUSED_PAD src0_sel:WORD_1
	v_and_b32_e32 v1, 0x7fffffff, v4
	v_and_b32_e32 v0, 0x7fffffff, v5
	v_xor_b32_e32 v11, -1, v5
	v_pk_add_f32 v[0:1], v[0:1], 0 neg_lo:[1,1] neg_hi:[1,1]
	v_cmp_gt_i32_e32 vcc, 0, v5
	v_xor_b32_e32 v9, -1, v4
	v_and_b32_e32 v2, 0x7fffffff, v6
	v_and_b32_e32 v3, 0x7fffffff, v7
	v_cndmask_b32_e32 v29, v0, v11, vcc
	v_cmp_gt_i32_e32 vcc, 0, v4
	v_xor_b32_e32 v15, -1, v6
	v_pk_add_f32 v[2:3], v[2:3], 0 neg_lo:[1,1] neg_hi:[1,1]
	v_cndmask_b32_e32 v28, v1, v9, vcc
	v_cmp_gt_i32_e32 vcc, 0, v6
	v_xor_b32_e32 v13, -1, v7
	s_nop 0
	v_cndmask_b32_e32 v25, v2, v15, vcc
	v_cmp_gt_i32_e32 vcc, 0, v7
	s_nop 1
	v_cndmask_b32_e32 v27, v3, v13, vcc
.LBB0_128:
	s_or_b64 exec, exec, s[12:13]
	v_add_u32_e32 v6, 0xc00, v16
	v_cmp_gt_i32_e32 vcc, s72, v6
	v_mov_b32_e32 v17, 0
	v_mov_b32_e32 v23, 0
	v_mov_b32_e32 v22, 0
	v_mov_b32_e32 v26, 0
	v_mov_b32_e32 v24, 0
	s_and_saveexec_b64 s[12:13], vcc
	s_cbranch_execz .LBB0_130
	v_ashrrev_i32_e32 v7, 31, v6
	v_mov_b64_e32 v[0:1], v[232:233]
	v_cvt_f32_f16_sdwa v4, v0 dst_sel:DWORD dst_unused:UNUSED_PAD src0_sel:WORD_1
	v_cvt_f32_f16_e32 v5, v0
	v_cvt_f32_f16_e32 v7, v1
	v_cvt_f32_f16_sdwa v9, v1 dst_sel:DWORD dst_unused:UNUSED_PAD src0_sel:WORD_1
	v_and_b32_e32 v1, 0x7fffffff, v4
	v_and_b32_e32 v0, 0x7fffffff, v5
	v_xor_b32_e32 v13, -1, v5
	v_pk_add_f32 v[0:1], v[0:1], 0 neg_lo:[1,1] neg_hi:[1,1]
	v_cmp_gt_i32_e32 vcc, 0, v5
	v_xor_b32_e32 v11, -1, v4
	v_and_b32_e32 v2, 0x7fffffff, v7
	v_and_b32_e32 v3, 0x7fffffff, v9
	v_cndmask_b32_e32 v26, v0, v13, vcc
	v_cmp_gt_i32_e32 vcc, 0, v4
	v_xor_b32_e32 v18, -1, v7
	v_pk_add_f32 v[2:3], v[2:3], 0 neg_lo:[1,1] neg_hi:[1,1]
	v_cndmask_b32_e32 v24, v1, v11, vcc
	v_cmp_gt_i32_e32 vcc, 0, v7
	v_xor_b32_e32 v15, -1, v9
	s_nop 0
	v_cndmask_b32_e32 v23, v2, v18, vcc
	v_cmp_gt_i32_e32 vcc, 0, v9
	s_nop 1
	v_cndmask_b32_e32 v22, v3, v15, vcc
.LBB0_130:
	s_or_b64 exec, exec, s[12:13]
	v_add_u32_e32 v4, 0xd00, v16
	v_cmp_gt_i32_e32 vcc, s72, v4
	v_mov_b32_e32 v18, 0
	v_mov_b32_e32 v21, 0
	v_mov_b32_e32 v20, 0
	s_and_saveexec_b64 s[12:13], vcc
	s_cbranch_execz .LBB0_132
	v_ashrrev_i32_e32 v5, 31, v4
	v_mov_b64_e32 v[0:1], v[234:235]
	v_cvt_f32_f16_sdwa v5, v0 dst_sel:DWORD dst_unused:UNUSED_PAD src0_sel:WORD_1
	v_cvt_f32_f16_e32 v7, v0
	v_cvt_f32_f16_e32 v9, v1
	v_cvt_f32_f16_sdwa v11, v1 dst_sel:DWORD dst_unused:UNUSED_PAD src0_sel:WORD_1
	v_and_b32_e32 v1, 0x7fffffff, v5
	v_and_b32_e32 v0, 0x7fffffff, v7
	v_xor_b32_e32 v15, -1, v7
	v_pk_add_f32 v[0:1], v[0:1], 0 neg_lo:[1,1] neg_hi:[1,1]
	v_cmp_gt_i32_e32 vcc, 0, v7
	v_xor_b32_e32 v13, -1, v5
	v_and_b32_e32 v2, 0x7fffffff, v9
	v_and_b32_e32 v3, 0x7fffffff, v11
	v_cndmask_b32_e32 v21, v0, v15, vcc
	v_cmp_gt_i32_e32 vcc, 0, v5
	v_xor_b32_e32 v17, -1, v9
	v_pk_add_f32 v[2:3], v[2:3], 0 neg_lo:[1,1] neg_hi:[1,1]
	v_cndmask_b32_e32 v20, v1, v13, vcc
	v_cmp_gt_i32_e32 vcc, 0, v9
	v_xor_b32_e32 v18, -1, v11
	s_nop 0
	v_cndmask_b32_e32 v17, v2, v17, vcc
	v_cmp_gt_i32_e32 vcc, 0, v11
	s_nop 1
	v_cndmask_b32_e32 v18, v3, v18, vcc
.LBB0_132:
	s_or_b64 exec, exec, s[12:13]
	v_add_u32_e32 v2, 0xe00, v16
	v_cmp_gt_i32_e32 vcc, s72, v2
	v_mov_b32_e32 v1, 0
	v_mov_b32_e32 v13, 0
	v_mov_b32_e32 v11, 0
	v_mov_b32_e32 v19, 0
	v_mov_b32_e32 v15, 0
	s_and_saveexec_b64 s[12:13], vcc
	s_cbranch_execz .LBB0_134
	v_ashrrev_i32_e32 v3, 31, v2
	v_mov_b64_e32 v[88:89], v[236:237]
	v_cvt_f32_f16_sdwa v0, v88 dst_sel:DWORD dst_unused:UNUSED_PAD src0_sel:WORD_1
	v_cvt_f32_f16_e32 v3, v88
	v_cvt_f32_f16_e32 v5, v89
	v_cvt_f32_f16_sdwa v7, v89 dst_sel:DWORD dst_unused:UNUSED_PAD src0_sel:WORD_1
	v_and_b32_e32 v89, 0x7fffffff, v0
	v_and_b32_e32 v88, 0x7fffffff, v3
	v_xor_b32_e32 v11, -1, v3
	v_pk_add_f32 v[88:89], v[88:89], 0 neg_lo:[1,1] neg_hi:[1,1]
	v_cmp_gt_i32_e32 vcc, 0, v3
	v_xor_b32_e32 v9, -1, v0
	v_and_b32_e32 v90, 0x7fffffff, v5
	v_and_b32_e32 v91, 0x7fffffff, v7
	v_cndmask_b32_e32 v19, v88, v11, vcc
	v_cmp_gt_i32_e32 vcc, 0, v0
	v_xor_b32_e32 v13, -1, v5
	v_pk_add_f32 v[90:91], v[90:91], 0 neg_lo:[1,1] neg_hi:[1,1]
	v_cndmask_b32_e32 v15, v89, v9, vcc
	v_cmp_gt_i32_e32 vcc, 0, v5
	v_xor_b32_e32 v87, -1, v7
	s_nop 0
	v_cndmask_b32_e32 v13, v90, v13, vcc
	v_cmp_gt_i32_e32 vcc, 0, v7
	s_nop 1
	v_cndmask_b32_e32 v11, v91, v87, vcc
.LBB0_134:
	s_or_b64 exec, exec, s[12:13]
	v_add_u32_e32 v0, 0xf00, v16
	v_cmp_gt_i32_e32 vcc, s72, v0
	v_mov_b32_e32 v3, 0
	v_mov_b32_e32 v9, 0
	v_mov_b32_e32 v7, 0
	s_and_saveexec_b64 s[12:13], vcc
	s_cbranch_execz .LBB0_136
	v_ashrrev_i32_e32 v1, 31, v0
	v_mov_b64_e32 v[88:89], v[238:239]
	v_cvt_f32_f16_sdwa v1, v88 dst_sel:DWORD dst_unused:UNUSED_PAD src0_sel:WORD_1
	v_cvt_f32_f16_e32 v3, v88
	v_cvt_f32_f16_e32 v5, v89
	v_cvt_f32_f16_sdwa v87, v89 dst_sel:DWORD dst_unused:UNUSED_PAD src0_sel:WORD_1
	v_and_b32_e32 v89, 0x7fffffff, v1
	v_and_b32_e32 v88, 0x7fffffff, v3
	v_xor_b32_e32 v9, -1, v3
	v_pk_add_f32 v[88:89], v[88:89], 0 neg_lo:[1,1] neg_hi:[1,1]
	v_cmp_gt_i32_e32 vcc, 0, v3
	v_xor_b32_e32 v7, -1, v1
	v_and_b32_e32 v90, 0x7fffffff, v5
	v_and_b32_e32 v91, 0x7fffffff, v87
	v_cndmask_b32_e32 v9, v88, v9, vcc
	v_cmp_gt_i32_e32 vcc, 0, v1
	v_xor_b32_e32 v93, -1, v5
	v_pk_add_f32 v[90:91], v[90:91], 0 neg_lo:[1,1] neg_hi:[1,1]
	v_cndmask_b32_e32 v7, v89, v7, vcc
	v_cmp_gt_i32_e32 vcc, 0, v5
	v_xor_b32_e32 v92, -1, v87
	s_nop 0
	v_cndmask_b32_e32 v1, v90, v93, vcc
	v_cmp_gt_i32_e32 vcc, 0, v87
	s_nop 1
	v_cndmask_b32_e32 v3, v91, v92, vcc

; #define PG8_STAGE(bufoff, gbase, voff) do { _Pragma("unroll") for (int _i = 0; _i < 2; ++_i) \
;         __builtin_amdgcn_global_load_lds((const unsigned*)((const char*)(gbase) + (voff)[_i]), (LAS unsigned*)(lds + (bufoff) + ldsw + _i * 8192), 16, 0, 0); } while (0)
; #define PG8_LDA(dst, b, h) do { _Pragma("unroll") for (int m = 0; m < 4; ++m) _Pragma("unroll") for (int k = 0; k < 2; ++k) dst[m][k] = *(const LAS bf16x8*)(lds + PG8_SA(b, h) + aoff + m * 2048 + k * 1024); } while (0)
; #define PG8_LDB(dst, b, h) do { _Pragma("unroll") for (int n = 0; n < 2; ++n) _Pragma("unroll") for (int k = 0; k < 2; ++k) dst[n][k] = *(const LAS bf16x8*)(lds + PG8_SB(b, h) + boff + n * 2048 + k * 1024); } while (0)
; #define PG8_MMA(ai, bj, At, Bt) do { __builtin_amdgcn_s_setprio(1); _Pragma("unroll") for (int m = 0; m < 4; ++m) _Pragma("unroll") for (int n = 0; n < 2; ++n) _Pragma("unroll") for (int k = 0; k < 2; ++k) \
;         acc[ai][bj][m][n] = __builtin_amdgcn_mfma_f32_16x16x32_bf16(Bt[n][k], At[m][k], acc[ai][bj][m][n], 0, 0, 0); __builtin_amdgcn_s_setprio(0); } while (0)
; #define PG8_WAIT_L(n) asm volatile("s_waitcnt lgkmcnt(" #n ")" ::: "memory")
; #define PG8_BAR __builtin_amdgcn_s_barrier()
; #define PG8_SCHED __builtin_amdgcn_sched_barrier(0)
; template <class Epi>
; __device__ __forceinline__ void gemm_phase(const int TID, const int BID, LAS unsigned char* lds, const Gemm g, const StaticOrder& S, const Epi& E) {
;     ...
;             PG8_LDB(B0, 0, 0); PG8_SCHED; PG8_LDA(At, 0, 0); PG8_STAGE(PG8_SA(1, 1), a1 + hstepA, voffA);
;             PG8_WAIT_L(8); PG8_BAR; PG8_WAIT_L(0); PG8_MMA(0, 0, At, B0); PG8_BAR; PG8_SCHED;
;             PG8_LDB(B1, 0, 1); PG8_STAGE(PG8_SB(0, 0), b2, voffB);
;             PG8_BAR; PG8_WAIT_L(0); PG8_MMA(0, 1, At, B1); PG8_BAR;
;             PG8_LDA(At, 0, 1); PG8_STAGE(PG8_SA(0, 0), a2, voffA);
;             PG8_BAR; PG8_WAIT_L(0); PG8_MMA(1, 0, At, B0); PG8_BAR; PG8_SCHED;
.LBB0_799:
	v_add_u32_e32 v173, s23, v170
	ds_read_b128 v[138:141], v173
	ds_read_b128 v[142:145], v173 offset:1024
	ds_read_b128 v[174:177], v173 offset:2048
	ds_read_b128 v[178:181], v173 offset:3072
	s_add_u32 s26, s24, 0xfff80080
	s_addc_u32 s27, s25, -1
	s_cmp_eq_u32 s56, 28
	s_cselect_b32 s29, s17, s27
	s_cselect_b32 s28, s52, s26
	s_cselect_b32 s27, s15, s55
	s_cselect_b32 s26, s53, s54
	v_lshl_add_u64 v[200:201], s[24:25], 0, v[134:135]
	s_add_i32 m0, s35, 0xc000
	ds_read_b128 v[182:185], v172
	ds_read_b128 v[196:199], v172 offset:1024
	ds_read_b128 v[208:211], v172 offset:2048
	ds_read_b128 v[212:215], v172 offset:3072
	ds_read_b128 v[216:219], v172 offset:4096
	ds_read_b128 v[220:223], v172 offset:5120
	ds_read_b128 v[224:227], v172 offset:6144
	ds_read_b128 v[228:231], v172 offset:7168
	global_load_lds_dwordx4 v[200:201], off
	v_lshl_add_u64 v[200:201], s[24:25], 0, v[136:137]
	s_add_i32 m0, s35, 0xe000
	s_nop 0
	global_load_lds_dwordx4 v[200:201], off
	s_waitcnt lgkmcnt(8)
	s_barrier
	s_waitcnt lgkmcnt(0)
	s_setprio 1
	s_waitcnt lgkmcnt(0)
	v_mfma_f32_16x16x32_bf16 v[124:127], v[138:141], v[182:185], v[124:127]
	v_mfma_f32_16x16x32_bf16 v[120:123], v[174:177], v[182:185], v[120:123]
	v_mfma_f32_16x16x32_bf16 v[108:111], v[138:141], v[208:211], v[108:111]
	v_mfma_f32_16x16x32_bf16 v[104:107], v[174:177], v[208:211], v[104:107]
	v_mfma_f32_16x16x32_bf16 v[92:95], v[138:141], v[216:219], v[92:95]
	v_mfma_f32_16x16x32_bf16 v[88:91], v[174:177], v[216:219], v[88:91]
	v_mfma_f32_16x16x32_bf16 v[76:79], v[138:141], v[224:227], v[76:79]
	v_mfma_f32_16x16x32_bf16 v[72:75], v[174:177], v[224:227], v[72:75]
	v_mfma_f32_16x16x32_bf16 v[124:127], v[142:145], v[196:199], v[124:127]
	v_mfma_f32_16x16x32_bf16 v[120:123], v[178:181], v[196:199], v[120:123]
	v_mfma_f32_16x16x32_bf16 v[108:111], v[142:145], v[212:215], v[108:111]
	v_mfma_f32_16x16x32_bf16 v[104:107], v[178:181], v[212:215], v[104:107]
	v_mfma_f32_16x16x32_bf16 v[92:95], v[142:145], v[220:223], v[92:95]
	v_mfma_f32_16x16x32_bf16 v[88:91], v[178:181], v[220:223], v[88:91]
	v_mfma_f32_16x16x32_bf16 v[76:79], v[142:145], v[228:231], v[76:79]
	v_mfma_f32_16x16x32_bf16 v[72:75], v[178:181], v[228:231], v[72:75]
	s_setprio 0
	s_barrier
	s_mov_b32 m0, s31
	v_add_u32_e32 v173, s37, v170
	v_lshl_add_u64 v[200:201], s[26:27], 0, v[160:161]
	ds_read_b128 v[232:235], v173
	ds_read_b128 v[236:239], v173 offset:1024
	ds_read_b128 v[240:243], v173 offset:2048
	ds_read_b128 v[244:247], v173 offset:3072
	global_load_lds_dwordx4 v[200:201], off
	v_lshl_add_u64 v[248:249], s[26:27], 0, v[132:133]
	s_mov_b32 m0, s34
	s_nop 0
	global_load_lds_dwordx4 v[248:249], off
	s_barrier
	s_waitcnt lgkmcnt(0)
	s_setprio 1
	s_waitcnt lgkmcnt(0)
	v_mfma_f32_16x16x32_bf16 v[116:119], v[232:235], v[182:185], v[116:119]
	v_mfma_f32_16x16x32_bf16 v[112:115], v[240:243], v[182:185], v[112:115]
	v_mfma_f32_16x16x32_bf16 v[100:103], v[232:235], v[208:211], v[100:103]
	v_mfma_f32_16x16x32_bf16 v[96:99], v[240:243], v[208:211], v[96:99]
	v_mfma_f32_16x16x32_bf16 v[84:87], v[232:235], v[216:219], v[84:87]
	v_mfma_f32_16x16x32_bf16 v[80:83], v[240:243], v[216:219], v[80:83]
	v_mfma_f32_16x16x32_bf16 v[68:71], v[232:235], v[224:227], v[68:71]
	v_mfma_f32_16x16x32_bf16 v[64:67], v[240:243], v[224:227], v[64:67]
	v_mfma_f32_16x16x32_bf16 v[116:119], v[236:239], v[196:199], v[116:119]
	v_mfma_f32_16x16x32_bf16 v[112:115], v[244:247], v[196:199], v[112:115]
	v_mfma_f32_16x16x32_bf16 v[100:103], v[236:239], v[212:215], v[100:103]
	v_mfma_f32_16x16x32_bf16 v[96:99], v[244:247], v[212:215], v[96:99]
	v_mfma_f32_16x16x32_bf16 v[84:87], v[236:239], v[220:223], v[84:87]
	v_mfma_f32_16x16x32_bf16 v[80:83], v[244:247], v[220:223], v[80:83]
	v_mfma_f32_16x16x32_bf16 v[68:71], v[236:239], v[228:231], v[68:71]
	v_mfma_f32_16x16x32_bf16 v[64:67], v[244:247], v[228:231], v[64:67]
	s_setprio 0
	s_mov_b32 m0, s35
	v_lshl_add_u64 v[250:251], s[28:29], 0, v[128:129]
	s_barrier
	ds_read_b128 v[182:185], v172 offset:16384
	ds_read_b128 v[196:199], v172 offset:17408
	ds_read_b128 v[208:211], v172 offset:18432
	ds_read_b128 v[212:215], v172 offset:19456
	ds_read_b128 v[216:219], v172 offset:20480
	ds_read_b128 v[220:223], v172 offset:21504
	ds_read_b128 v[224:227], v172 offset:22528
	ds_read_b128 v[228:231], v172 offset:23552
	global_load_lds_dwordx4 v[250:251], off
	v_lshl_add_u64 v[252:253], s[28:29], 0, v[130:131]
	s_mov_b32 m0, s36
	s_nop 0
	global_load_lds_dwordx4 v[252:253], off
	s_barrier
	s_waitcnt lgkmcnt(0)
	s_setprio 1
	s_waitcnt lgkmcnt(0)
	v_mfma_f32_16x16x32_bf16 v[60:63], v[138:141], v[182:185], v[60:63]
	v_mfma_f32_16x16x32_bf16 v[56:59], v[174:177], v[182:185], v[56:59]
	v_mfma_f32_16x16x32_bf16 v[44:47], v[138:141], v[208:211], v[44:47]
	v_mfma_f32_16x16x32_bf16 v[40:43], v[174:177], v[208:211], v[40:43]
	v_mfma_f32_16x16x32_bf16 v[28:31], v[138:141], v[216:219], v[28:31]
	v_mfma_f32_16x16x32_bf16 v[24:27], v[174:177], v[216:219], v[24:27]
	v_mfma_f32_16x16x32_bf16 v[12:15], v[138:141], v[224:227], v[12:15]
	v_mfma_f32_16x16x32_bf16 v[8:11], v[174:177], v[224:227], v[8:11]
	v_mfma_f32_16x16x32_bf16 v[60:63], v[142:145], v[196:199], v[60:63]
	v_mfma_f32_16x16x32_bf16 v[56:59], v[178:181], v[196:199], v[56:59]
	v_mfma_f32_16x16x32_bf16 v[44:47], v[142:145], v[212:215], v[44:47]
	v_mfma_f32_16x16x32_bf16 v[40:43], v[178:181], v[212:215], v[40:43]
	v_mfma_f32_16x16x32_bf16 v[28:31], v[142:145], v[220:223], v[28:31]
	v_mfma_f32_16x16x32_bf16 v[24:27], v[178:181], v[220:223], v[24:27]
	v_mfma_f32_16x16x32_bf16 v[12:15], v[142:145], v[228:231], v[12:15]
	v_mfma_f32_16x16x32_bf16 v[8:11], v[178:181], v[228:231], v[8:11]
	s_setprio 0
	s_barrier
; #define PG8_STAGE(bufoff, gbase, voff) do { _Pragma("unroll") for (int _i = 0; _i < 2; ++_i) \
;         __builtin_amdgcn_global_load_lds((const unsigned*)((const char*)(gbase) + (voff)[_i]), (LAS unsigned*)(lds + (bufoff) + ldsw + _i * 8192), 16, 0, 0); } while (0)
; #define PG8_LDA(dst, b, h) do { _Pragma("unroll") for (int m = 0; m < 4; ++m) _Pragma("unroll") for (int k = 0; k < 2; ++k) dst[m][k] = *(const LAS bf16x8*)(lds + PG8_SA(b, h) + aoff + m * 2048 + k * 1024); } while (0)
; #define PG8_LDB(dst, b, h) do { _Pragma("unroll") for (int n = 0; n < 2; ++n) _Pragma("unroll") for (int k = 0; k < 2; ++k) dst[n][k] = *(const LAS bf16x8*)(lds + PG8_SB(b, h) + boff + n * 2048 + k * 1024); } while (0)
; #define PG8_MMA(ai, bj, At, Bt) do { __builtin_amdgcn_s_setprio(1); _Pragma("unroll") for (int m = 0; m < 4; ++m) _Pragma("unroll") for (int n = 0; n < 2; ++n) _Pragma("unroll") for (int k = 0; k < 2; ++k) \
;         acc[ai][bj][m][n] = __builtin_amdgcn_mfma_f32_16x16x32_bf16(Bt[n][k], At[m][k], acc[ai][bj][m][n], 0, 0, 0); __builtin_amdgcn_s_setprio(0); } while (0)
; #define PG8_WAIT_V(n) asm volatile("s_waitcnt vmcnt(" #n ")" ::: "memory")
; #define PG8_WAIT_L(n) asm volatile("s_waitcnt lgkmcnt(" #n ")" ::: "memory")
; #define PG8_BAR __builtin_amdgcn_s_barrier()
; #define PG8_SCHED __builtin_amdgcn_sched_barrier(0)
; template <class Epi>
; __device__ __forceinline__ void gemm_phase(const int TID, const int BID, LAS unsigned char* lds, const Gemm g, const StaticOrder& S, const Epi& E) {
;     ...
;             PG8_STAGE(PG8_SB(0, 1), b2 + hstepB, voffB);
;             PG8_WAIT_V(6); PG8_BAR; PG8_MMA(1, 1, At, B1); PG8_BAR;
;             PG8_LDB(B0, 1, 0); PG8_SCHED; PG8_LDA(At, 1, 0); PG8_STAGE(PG8_SA(0, 1), a2 + hstepA, voffA);
;             PG8_WAIT_L(8); PG8_BAR; PG8_WAIT_L(0); PG8_MMA(0, 0, At, B0); PG8_BAR; PG8_SCHED;
;             PG8_LDB(B1, 1, 1); PG8_STAGE(PG8_SB(1, 0), b3, voffB);
;             PG8_BAR; PG8_WAIT_L(0); PG8_MMA(0, 1, At, B1); PG8_BAR;
;             PG8_LDA(At, 1, 1); PG8_STAGE(PG8_SA(1, 0), a3, voffA);
	s_add_u32 s58, s26, 0x80000
	s_addc_u32 s59, s27, 0
	s_mov_b32 m0, s38
	v_lshl_add_u64 v[138:139], s[58:59], 0, v[160:161]
	global_load_lds_dwordx4 v[138:139], off
	v_lshl_add_u64 v[138:139], s[58:59], 0, v[132:133]
	s_mov_b32 m0, s39
	s_nop 0
	global_load_lds_dwordx4 v[138:139], off
	s_waitcnt vmcnt(6)
	s_barrier
	s_setprio 1
	v_mfma_f32_16x16x32_bf16 v[52:55], v[232:235], v[182:185], v[52:55]
	v_mfma_f32_16x16x32_bf16 v[48:51], v[240:243], v[182:185], v[48:51]
	v_mfma_f32_16x16x32_bf16 v[36:39], v[232:235], v[208:211], v[36:39]
	v_mfma_f32_16x16x32_bf16 v[32:35], v[240:243], v[208:211], v[32:35]
	v_mfma_f32_16x16x32_bf16 v[20:23], v[232:235], v[216:219], v[20:23]
	v_mfma_f32_16x16x32_bf16 v[16:19], v[240:243], v[216:219], v[16:19]
	v_mfma_f32_16x16x32_bf16 v[4:7], v[232:235], v[224:227], v[4:7]
	v_mfma_f32_16x16x32_bf16 v[0:3], v[240:243], v[224:227], v[0:3]
	v_mfma_f32_16x16x32_bf16 v[52:55], v[236:239], v[196:199], v[52:55]
	v_mfma_f32_16x16x32_bf16 v[48:51], v[244:247], v[196:199], v[48:51]
	v_mfma_f32_16x16x32_bf16 v[36:39], v[236:239], v[212:215], v[36:39]
	v_mfma_f32_16x16x32_bf16 v[32:35], v[244:247], v[212:215], v[32:35]
	v_mfma_f32_16x16x32_bf16 v[20:23], v[236:239], v[220:223], v[20:23]
	v_mfma_f32_16x16x32_bf16 v[16:19], v[244:247], v[220:223], v[16:19]
	v_mfma_f32_16x16x32_bf16 v[4:7], v[236:239], v[228:231], v[4:7]
	v_mfma_f32_16x16x32_bf16 v[0:3], v[244:247], v[228:231], v[0:3]
	s_setprio 0
	v_add_u32_e32 v173, s42, v170
	s_barrier
	ds_read_b128 v[138:141], v173
	ds_read_b128 v[142:145], v173 offset:1024
	ds_read_b128 v[174:177], v173 offset:2048
	ds_read_b128 v[178:181], v173 offset:3072
	s_add_u32 s28, s28, 0x80000
	s_addc_u32 s29, s29, 0
	s_mov_b32 m0, s40
	v_lshl_add_u64 v[232:233], s[28:29], 0, v[128:129]
	ds_read_b128 v[182:185], v172 offset:32768
	ds_read_b128 v[196:199], v172 offset:33792
	ds_read_b128 v[208:211], v172 offset:34816
	ds_read_b128 v[212:215], v172 offset:35840
	ds_read_b128 v[216:219], v172 offset:36864
	ds_read_b128 v[220:223], v172 offset:37888
	ds_read_b128 v[224:227], v172 offset:38912
	ds_read_b128 v[228:231], v172 offset:39936
	global_load_lds_dwordx4 v[232:233], off
	v_lshl_add_u64 v[232:233], s[28:29], 0, v[130:131]
	s_mov_b32 m0, s41
	s_nop 0
	global_load_lds_dwordx4 v[232:233], off
	s_waitcnt lgkmcnt(8)
	s_barrier
	s_waitcnt lgkmcnt(0)
	s_setprio 1
	s_waitcnt lgkmcnt(0)
	v_mfma_f32_16x16x32_bf16 v[124:127], v[138:141], v[182:185], v[124:127]
	v_mfma_f32_16x16x32_bf16 v[120:123], v[174:177], v[182:185], v[120:123]
	v_mfma_f32_16x16x32_bf16 v[108:111], v[138:141], v[208:211], v[108:111]
	v_mfma_f32_16x16x32_bf16 v[104:107], v[174:177], v[208:211], v[104:107]
	v_mfma_f32_16x16x32_bf16 v[92:95], v[138:141], v[216:219], v[92:95]
	v_mfma_f32_16x16x32_bf16 v[88:91], v[174:177], v[216:219], v[88:91]
	v_mfma_f32_16x16x32_bf16 v[76:79], v[138:141], v[224:227], v[76:79]
	v_mfma_f32_16x16x32_bf16 v[72:75], v[174:177], v[224:227], v[72:75]
	v_mfma_f32_16x16x32_bf16 v[124:127], v[142:145], v[196:199], v[124:127]
	v_mfma_f32_16x16x32_bf16 v[120:123], v[178:181], v[196:199], v[120:123]
	v_mfma_f32_16x16x32_bf16 v[108:111], v[142:145], v[212:215], v[108:111]
	v_mfma_f32_16x16x32_bf16 v[104:107], v[178:181], v[212:215], v[104:107]
	v_mfma_f32_16x16x32_bf16 v[92:95], v[142:145], v[220:223], v[92:95]
	v_mfma_f32_16x16x32_bf16 v[88:91], v[178:181], v[220:223], v[88:91]
	v_mfma_f32_16x16x32_bf16 v[76:79], v[142:145], v[228:231], v[76:79]
	v_mfma_f32_16x16x32_bf16 v[72:75], v[178:181], v[228:231], v[72:75]
	s_setprio 0
	s_barrier
	s_mov_b32 m0, s43
	v_add_u32_e32 v173, s47, v170
	v_lshl_add_u64 v[200:201], v[200:201], 0, s[90:91]
	ds_read_b128 v[232:235], v173
	ds_read_b128 v[236:239], v173 offset:1024
	ds_read_b128 v[240:243], v173 offset:2048
	ds_read_b128 v[244:247], v173 offset:3072
	global_load_lds_dwordx4 v[200:201], off
	v_lshl_add_u64 v[200:201], v[248:249], 0, s[90:91]
	s_mov_b32 m0, s44
	s_nop 0
	global_load_lds_dwordx4 v[200:201], off
	s_barrier
	s_waitcnt lgkmcnt(0)
	s_setprio 1
	s_waitcnt lgkmcnt(0)
	v_mfma_f32_16x16x32_bf16 v[116:119], v[232:235], v[182:185], v[116:119]
	v_mfma_f32_16x16x32_bf16 v[112:115], v[240:243], v[182:185], v[112:115]
	v_mfma_f32_16x16x32_bf16 v[100:103], v[232:235], v[208:211], v[100:103]
	v_mfma_f32_16x16x32_bf16 v[96:99], v[240:243], v[208:211], v[96:99]
	v_mfma_f32_16x16x32_bf16 v[84:87], v[232:235], v[216:219], v[84:87]
	v_mfma_f32_16x16x32_bf16 v[80:83], v[240:243], v[216:219], v[80:83]
	v_mfma_f32_16x16x32_bf16 v[68:71], v[232:235], v[224:227], v[68:71]
	v_mfma_f32_16x16x32_bf16 v[64:67], v[240:243], v[224:227], v[64:67]
	v_mfma_f32_16x16x32_bf16 v[116:119], v[236:239], v[196:199], v[116:119]
	v_mfma_f32_16x16x32_bf16 v[112:115], v[244:247], v[196:199], v[112:115]
	v_mfma_f32_16x16x32_bf16 v[100:103], v[236:239], v[212:215], v[100:103]
	v_mfma_f32_16x16x32_bf16 v[96:99], v[244:247], v[212:215], v[96:99]
	v_mfma_f32_16x16x32_bf16 v[84:87], v[236:239], v[220:223], v[84:87]
	v_mfma_f32_16x16x32_bf16 v[80:83], v[244:247], v[220:223], v[80:83]
	v_mfma_f32_16x16x32_bf16 v[68:71], v[236:239], v[228:231], v[68:71]
	v_mfma_f32_16x16x32_bf16 v[64:67], v[244:247], v[228:231], v[64:67]
	s_setprio 0
	s_mov_b32 m0, s45
	v_lshl_add_u64 v[200:201], v[250:251], 0, s[90:91]
	s_barrier
	ds_read_b128 v[182:185], v172 offset:49152
	ds_read_b128 v[196:199], v172 offset:50176
	ds_read_b128 v[208:211], v172 offset:51200
	ds_read_b128 v[212:215], v172 offset:52224
	ds_read_b128 v[216:219], v172 offset:53248
	ds_read_b128 v[220:223], v172 offset:54272
	ds_read_b128 v[224:227], v172 offset:55296
	ds_read_b128 v[228:231], v172 offset:56320
	global_load_lds_dwordx4 v[200:201], off
	v_lshl_add_u64 v[200:201], v[252:253], 0, s[90:91]
	s_mov_b32 m0, s46
	s_nop 0
	global_load_lds_dwordx4 v[200:201], off
	s_barrier
; __device__ __forceinline__ unsigned cvt_pk_bf16(float lo, float hi) { unsigned r; asm volatile("v_cvt_pk_bf16_f32 %0, %1, %2" : "=v"(r) : "v"(lo), "v"(hi)); return r; }
; __device__ __forceinline__ float rinv_st(stat_t s, float invn) { return rsqrtf((float)((double)s * (1.0 / 4294967296.0)) * invn + 1e-6f); }
; #define PG8_STAGE(bufoff, gbase, voff) do { _Pragma("unroll") for (int _i = 0; _i < 2; ++_i) \
;         __builtin_amdgcn_global_load_lds((const unsigned*)((const char*)(gbase) + (voff)[_i]), (LAS unsigned*)(lds + (bufoff) + ldsw + _i * 8192), 16, 0, 0); } while (0)
; #define PG8_MMA(ai, bj, At, Bt) do { __builtin_amdgcn_s_setprio(1); _Pragma("unroll") for (int m = 0; m < 4; ++m) _Pragma("unroll") for (int n = 0; n < 2; ++n) _Pragma("unroll") for (int k = 0; k < 2; ++k) \
;         acc[ai][bj][m][n] = __builtin_amdgcn_mfma_f32_16x16x32_bf16(Bt[n][k], At[m][k], acc[ai][bj][m][n], 0, 0, 0); __builtin_amdgcn_s_setprio(0); } while (0)
; #define PG8_WAIT_V(n) asm volatile("s_waitcnt vmcnt(" #n ")" ::: "memory")
; #define PG8_WAIT_L(n) asm volatile("s_waitcnt lgkmcnt(" #n ")" ::: "memory")
; #define PG8_BAR __builtin_amdgcn_s_barrier()
; #define PG8_SCHED __builtin_amdgcn_sched_barrier(0)
; template <class Epi>
; __device__ __forceinline__ void gemm_phase(const int TID, const int BID, LAS unsigned char* lds, const Gemm g, const StaticOrder& S, const Epi& E) {
;     ...
;             PG8_BAR; PG8_WAIT_L(0); PG8_MMA(1, 0, At, B0); PG8_BAR; PG8_SCHED;
;             PG8_STAGE(PG8_SB(1, 1), b3 + hstepB, voffB);
;             PG8_WAIT_V(6); PG8_BAR; PG8_MMA(1, 1, At, B1); PG8_BAR;
;         }
;     __device__ __forceinline__ void operator()(const f32x4 (&acc)[2][2][4][2], const Unit& u, int wr, int wc, int fr, int fq) const {
;     ...
;             for (int m = 0; m < 4; ++m) {
;                 const int row = row0 + ai * HALF + m * 16; const float r = rinv_st(stats[row], 1.0f / 2048.0f);
;                 bf16_t* rowp = raw + (size_t)row * NINP + col0;
; #pragma unroll
;                 for (int bj = 0; bj < 2; ++bj) {
;                     const f32x4 v0 = acc[ai][bj][m][0] * r, v1 = acc[ai][bj][m][1] * r;
;                     u32x4 w; w.x = cvt_pk_bf16(v0[0], v0[1]); w.y = cvt_pk_bf16(v0[2], v0[3]); w.z = cvt_pk_bf16(v1[0], v1[1]); w.w = cvt_pk_bf16(v1[2], v1[3]);
;                     *(u32x4*)(rowp + bj * HALF) = w;
	s_waitcnt lgkmcnt(0)
	s_setprio 1
	s_waitcnt lgkmcnt(0)
	v_mfma_f32_16x16x32_bf16 v[60:63], v[138:141], v[182:185], v[60:63]
	v_mfma_f32_16x16x32_bf16 v[56:59], v[174:177], v[182:185], v[56:59]
	v_mfma_f32_16x16x32_bf16 v[44:47], v[138:141], v[208:211], v[44:47]
	v_mfma_f32_16x16x32_bf16 v[40:43], v[174:177], v[208:211], v[40:43]
	v_mfma_f32_16x16x32_bf16 v[28:31], v[138:141], v[216:219], v[28:31]
	v_mfma_f32_16x16x32_bf16 v[24:27], v[174:177], v[216:219], v[24:27]
	v_mfma_f32_16x16x32_bf16 v[12:15], v[138:141], v[224:227], v[12:15]
	v_mfma_f32_16x16x32_bf16 v[8:11], v[174:177], v[224:227], v[8:11]
	v_mfma_f32_16x16x32_bf16 v[60:63], v[142:145], v[196:199], v[60:63]
	v_mfma_f32_16x16x32_bf16 v[56:59], v[178:181], v[196:199], v[56:59]
	v_mfma_f32_16x16x32_bf16 v[44:47], v[142:145], v[212:215], v[44:47]
	v_mfma_f32_16x16x32_bf16 v[40:43], v[178:181], v[212:215], v[40:43]
	v_mfma_f32_16x16x32_bf16 v[28:31], v[142:145], v[220:223], v[28:31]
	v_mfma_f32_16x16x32_bf16 v[24:27], v[178:181], v[220:223], v[24:27]
	v_mfma_f32_16x16x32_bf16 v[12:15], v[142:145], v[228:231], v[12:15]
	v_mfma_f32_16x16x32_bf16 v[8:11], v[178:181], v[228:231], v[8:11]
	s_setprio 0
	s_barrier
	s_add_u32 s26, s26, 0x80080
	s_addc_u32 s27, s27, 0
	s_mov_b32 m0, s48
	v_lshl_add_u64 v[138:139], s[26:27], 0, v[160:161]
	global_load_lds_dwordx4 v[138:139], off
	v_lshl_add_u64 v[138:139], s[26:27], 0, v[132:133]
	s_mov_b32 m0, s49
	s_nop 0
	global_load_lds_dwordx4 v[138:139], off
	s_waitcnt vmcnt(6)
	s_barrier
	s_setprio 1
	v_mfma_f32_16x16x32_bf16 v[52:55], v[232:235], v[182:185], v[52:55]
	v_mfma_f32_16x16x32_bf16 v[48:51], v[240:243], v[182:185], v[48:51]
	v_mfma_f32_16x16x32_bf16 v[36:39], v[232:235], v[208:211], v[36:39]
	v_mfma_f32_16x16x32_bf16 v[32:35], v[240:243], v[208:211], v[32:35]
	v_mfma_f32_16x16x32_bf16 v[20:23], v[232:235], v[216:219], v[20:23]
	v_mfma_f32_16x16x32_bf16 v[16:19], v[240:243], v[216:219], v[16:19]
	v_mfma_f32_16x16x32_bf16 v[4:7], v[232:235], v[224:227], v[4:7]
	v_mfma_f32_16x16x32_bf16 v[0:3], v[240:243], v[224:227], v[0:3]
	v_mfma_f32_16x16x32_bf16 v[52:55], v[236:239], v[196:199], v[52:55]
	v_mfma_f32_16x16x32_bf16 v[48:51], v[244:247], v[196:199], v[48:51]
	v_mfma_f32_16x16x32_bf16 v[36:39], v[236:239], v[212:215], v[36:39]
	v_mfma_f32_16x16x32_bf16 v[32:35], v[244:247], v[212:215], v[32:35]
	v_mfma_f32_16x16x32_bf16 v[20:23], v[236:239], v[220:223], v[20:23]
	v_mfma_f32_16x16x32_bf16 v[16:19], v[244:247], v[220:223], v[16:19]
	v_mfma_f32_16x16x32_bf16 v[4:7], v[236:239], v[228:231], v[4:7]
	v_mfma_f32_16x16x32_bf16 v[0:3], v[244:247], v[228:231], v[0:3]
	s_setprio 0
	s_add_i32 s56, s56, 2
	s_add_u32 s24, s24, 0x100
	s_addc_u32 s25, s25, 0
	s_add_u32 s54, s54, 0x100
	s_addc_u32 s55, s55, 0
	s_cmp_gt_u32 s56, 29
	s_barrier
	s_cbranch_scc0 .LBB0_799
	v_lshl_add_u32 v138, s22, 8, v169
	v_ashrrev_i32_e32 v139, 31, v138
	v_lshl_add_u64 v[140:141], v[138:139], 3, s[10:11]
	global_load_dwordx2 v[142:143], v[140:141], off
	global_load_dwordx2 v[208:209], v[140:141], off offset:128
	global_load_dwordx2 v[210:211], v[140:141], off offset:256
	global_load_dwordx2 v[212:213], v[140:141], off offset:384
	global_load_dwordx2 v[214:215], v[140:141], off offset:1024
	global_load_dwordx2 v[216:217], v[140:141], off offset:1152
	global_load_dwordx2 v[218:219], v[140:141], off offset:1280
	global_load_dwordx2 v[220:221], v[140:141], off offset:1408
	v_lshl_or_b32 v144, s51, 8, v171
	v_ashrrev_i32_e32 v145, 31, v144
	s_movk_i32 s15, 0x2200
	v_lshlrev_b64 v[144:145], 1, v[144:145]
	s_mov_b32 s51, s14
	s_mov_b32 s22, s16
	s_mov_b64 s[26:27], s[20:21]
	s_waitcnt vmcnt(0)
	v_cvt_f64_u32_e32 v[174:175], v143
	v_ldexp_f64 v[174:175], v[174:175], 32
	v_cvt_f64_u32_e32 v[142:143], v142
	v_add_f64 v[142:143], v[174:175], v[142:143]
	v_ldexp_f64 v[142:143], v[142:143], s93
	v_cvt_f32_f64_e32 v139, v[142:143]
	v_fmamk_f32 v139, v139, 0x3a000000, v189
	v_cmp_gt_f32_e32 vcc, s78, v139
	v_mul_f32_e32 v142, 0x4b800000, v139
	s_nop 0
	v_cndmask_b32_e32 v139, v139, v142, vcc
	v_rsq_f32_e32 v139, v139
	s_nop 0
	v_mul_f32_e32 v142, 0x45800000, v139
	v_cndmask_b32_e32 v174, v139, v142, vcc
	v_mov_b64_e32 v[142:143], s[12:13]
	v_mad_i64_i32 v[176:177], s[24:25], v138, s15, v[142:143]
	v_lshl_add_u64 v[176:177], v[176:177], 0, v[144:145]
	v_pk_mul_f32 v[126:127], v[126:127], v[174:175] op_sel_hi:[1,0]
	v_pk_mul_f32 v[124:125], v[124:125], v[174:175] op_sel_hi:[1,0]
	v_pk_mul_f32 v[178:179], v[122:123], v[174:175] op_sel_hi:[1,0]
	v_pk_mul_f32 v[122:123], v[120:121], v[174:175] op_sel_hi:[1,0]
	v_cvt_pk_bf16_f32 v120, v124, v125
	v_cvt_pk_bf16_f32 v121, v126, v127
	v_pk_mul_f32 v[116:117], v[116:117], v[174:175] op_sel_hi:[1,0]
	v_cvt_pk_bf16_f32 v122, v122, v123
	v_cvt_pk_bf16_f32 v123, v178, v179
	global_store_dwordx4 v[176:177], v[120:123], off
	v_pk_mul_f32 v[118:119], v[118:119], v[174:175] op_sel_hi:[1,0]
	s_nop 0
	v_pk_mul_f32 v[120:121], v[114:115], v[174:175] op_sel_hi:[1,0]
	v_pk_mul_f32 v[114:115], v[112:113], v[174:175] op_sel_hi:[1,0]
	v_cvt_pk_bf16_f32 v112, v116, v117
	v_cvt_pk_bf16_f32 v113, v118, v119
	s_nop 0
	v_cvt_pk_bf16_f32 v114, v114, v115
	v_cvt_pk_bf16_f32 v115, v120, v121
	global_store_dwordx4 v[176:177], v[112:115], off offset:256
	s_nop 1
	v_or_b32_e32 v112, 16, v138
	v_ashrrev_i32_e32 v113, 31, v112
	v_lshl_add_u64 v[114:115], v[112:113], 3, s[10:11]
	s_nop 1
	v_mov_b64_e32 v[114:115], v[208:209]
	v_cvt_f64_u32_e32 v[116:117], v115
	v_ldexp_f64 v[116:117], v[116:117], 32
	v_cvt_f64_u32_e32 v[114:115], v114
	v_add_f64 v[114:115], v[116:117], v[114:115]
	v_ldexp_f64 v[114:115], v[114:115], s93
	v_cvt_f32_f64_e32 v113, v[114:115]
	v_fmamk_f32 v113, v113, 0x3a000000, v189
; __device__ __forceinline__ unsigned cvt_pk_bf16(float lo, float hi) { unsigned r; asm volatile("v_cvt_pk_bf16_f32 %0, %1, %2" : "=v"(r) : "v"(lo), "v"(hi)); return r; }
; __device__ __forceinline__ float rinv_st(stat_t s, float invn) { return rsqrtf((float)((double)s * (1.0 / 4294967296.0)) * invn + 1e-6f); }
;     __device__ __forceinline__ void operator()(const f32x4 (&acc)[2][2][4][2], const Unit& u, int wr, int wc, int fr, int fq) const {
;     ...
;             for (int m = 0; m < 4; ++m) {
;                 const int row = row0 + ai * HALF + m * 16; const float r = rinv_st(stats[row], 1.0f / 2048.0f);
;                 bf16_t* rowp = raw + (size_t)row * NINP + col0;
; #pragma unroll
;                 for (int bj = 0; bj < 2; ++bj) {
;                     const f32x4 v0 = acc[ai][bj][m][0] * r, v1 = acc[ai][bj][m][1] * r;
;                     u32x4 w; w.x = cvt_pk_bf16(v0[0], v0[1]); w.y = cvt_pk_bf16(v0[2], v0[3]); w.z = cvt_pk_bf16(v1[0], v1[1]); w.w = cvt_pk_bf16(v1[2], v1[3]);
;                     *(u32x4*)(rowp + bj * HALF) = w;
;                 }
	v_cmp_gt_f32_e32 vcc, s78, v113
	v_mul_f32_e32 v114, 0x4b800000, v113
	s_nop 0
	v_cndmask_b32_e32 v113, v113, v114, vcc
	v_rsq_f32_e32 v113, v113
	s_nop 0
	v_mul_f32_e32 v114, 0x45800000, v113
	v_cndmask_b32_e32 v114, v113, v114, vcc
	v_mad_i64_i32 v[112:113], s[24:25], v112, s15, v[142:143]
	v_lshl_add_u64 v[112:113], v[112:113], 0, v[144:145]
	v_pk_mul_f32 v[110:111], v[110:111], v[114:115] op_sel_hi:[1,0]
	v_pk_mul_f32 v[108:109], v[108:109], v[114:115] op_sel_hi:[1,0]
	v_pk_mul_f32 v[116:117], v[106:107], v[114:115] op_sel_hi:[1,0]
	v_pk_mul_f32 v[106:107], v[104:105], v[114:115] op_sel_hi:[1,0]
	v_cvt_pk_bf16_f32 v104, v108, v109
	v_cvt_pk_bf16_f32 v105, v110, v111
	v_pk_mul_f32 v[100:101], v[100:101], v[114:115] op_sel_hi:[1,0]
	v_cvt_pk_bf16_f32 v106, v106, v107
	v_cvt_pk_bf16_f32 v107, v116, v117
	global_store_dwordx4 v[112:113], v[104:107], off
	v_pk_mul_f32 v[102:103], v[102:103], v[114:115] op_sel_hi:[1,0]
	s_nop 0
	v_pk_mul_f32 v[104:105], v[98:99], v[114:115] op_sel_hi:[1,0]
	v_pk_mul_f32 v[98:99], v[96:97], v[114:115] op_sel_hi:[1,0]
	v_cvt_pk_bf16_f32 v96, v100, v101
	v_cvt_pk_bf16_f32 v97, v102, v103
	s_nop 0
	v_cvt_pk_bf16_f32 v98, v98, v99
	v_cvt_pk_bf16_f32 v99, v104, v105
	global_store_dwordx4 v[112:113], v[96:99], off offset:256
	s_nop 1
	v_or_b32_e32 v96, 32, v138
	v_ashrrev_i32_e32 v97, 31, v96
	v_lshl_add_u64 v[98:99], v[96:97], 3, s[10:11]
	s_nop 1
	v_mov_b64_e32 v[98:99], v[210:211]
	v_cvt_f64_u32_e32 v[100:101], v99
	v_ldexp_f64 v[100:101], v[100:101], 32
	v_cvt_f64_u32_e32 v[98:99], v98
	v_add_f64 v[98:99], v[100:101], v[98:99]
	v_ldexp_f64 v[98:99], v[98:99], s93
	v_cvt_f32_f64_e32 v97, v[98:99]
	v_fmamk_f32 v97, v97, 0x3a000000, v189
	v_cmp_gt_f32_e32 vcc, s78, v97
	v_mul_f32_e32 v98, 0x4b800000, v97
	s_nop 0
	v_cndmask_b32_e32 v97, v97, v98, vcc
	v_rsq_f32_e32 v97, v97
	s_nop 0
	v_mul_f32_e32 v98, 0x45800000, v97
	v_cndmask_b32_e32 v98, v97, v98, vcc
	v_mad_i64_i32 v[96:97], s[24:25], v96, s15, v[142:143]
	v_lshl_add_u64 v[96:97], v[96:97], 0, v[144:145]
	v_pk_mul_f32 v[94:95], v[94:95], v[98:99] op_sel_hi:[1,0]
	v_pk_mul_f32 v[92:93], v[92:93], v[98:99] op_sel_hi:[1,0]
	v_pk_mul_f32 v[100:101], v[90:91], v[98:99] op_sel_hi:[1,0]
	v_pk_mul_f32 v[90:91], v[88:89], v[98:99] op_sel_hi:[1,0]
	v_cvt_pk_bf16_f32 v88, v92, v93
	v_cvt_pk_bf16_f32 v89, v94, v95
	v_pk_mul_f32 v[84:85], v[84:85], v[98:99] op_sel_hi:[1,0]
	v_cvt_pk_bf16_f32 v90, v90, v91
	v_cvt_pk_bf16_f32 v91, v100, v101
	global_store_dwordx4 v[96:97], v[88:91], off
	v_pk_mul_f32 v[86:87], v[86:87], v[98:99] op_sel_hi:[1,0]
	s_nop 0
	v_pk_mul_f32 v[88:89], v[82:83], v[98:99] op_sel_hi:[1,0]
	v_pk_mul_f32 v[82:83], v[80:81], v[98:99] op_sel_hi:[1,0]
	v_cvt_pk_bf16_f32 v80, v84, v85
	v_cvt_pk_bf16_f32 v81, v86, v87
	s_nop 0
	v_cvt_pk_bf16_f32 v82, v82, v83
	v_cvt_pk_bf16_f32 v83, v88, v89
	global_store_dwordx4 v[96:97], v[80:83], off offset:256
	s_nop 1
	v_or_b32_e32 v80, 48, v138
	v_ashrrev_i32_e32 v81, 31, v80
	v_lshl_add_u64 v[82:83], v[80:81], 3, s[10:11]
	s_nop 1
	v_mov_b64_e32 v[82:83], v[212:213]
	v_cvt_f64_u32_e32 v[84:85], v83
	v_ldexp_f64 v[84:85], v[84:85], 32
	v_cvt_f64_u32_e32 v[82:83], v82
	v_add_f64 v[82:83], v[84:85], v[82:83]
	v_ldexp_f64 v[82:83], v[82:83], s93
	v_cvt_f32_f64_e32 v81, v[82:83]
	v_fmamk_f32 v81, v81, 0x3a000000, v189
	v_cmp_gt_f32_e32 vcc, s78, v81
	v_mul_f32_e32 v82, 0x4b800000, v81
	s_nop 0
	v_cndmask_b32_e32 v81, v81, v82, vcc
	v_rsq_f32_e32 v81, v81
	s_nop 0
	v_mul_f32_e32 v82, 0x45800000, v81
	v_cndmask_b32_e32 v82, v81, v82, vcc
	v_mad_i64_i32 v[80:81], s[24:25], v80, s15, v[142:143]
	v_lshl_add_u64 v[80:81], v[80:81], 0, v[144:145]
	v_pk_mul_f32 v[78:79], v[78:79], v[82:83] op_sel_hi:[1,0]
	v_pk_mul_f32 v[76:77], v[76:77], v[82:83] op_sel_hi:[1,0]
	v_pk_mul_f32 v[84:85], v[74:75], v[82:83] op_sel_hi:[1,0]
	v_pk_mul_f32 v[74:75], v[72:73], v[82:83] op_sel_hi:[1,0]
	v_cvt_pk_bf16_f32 v72, v76, v77
	v_cvt_pk_bf16_f32 v73, v78, v79
	v_pk_mul_f32 v[70:71], v[70:71], v[82:83] op_sel_hi:[1,0]
	v_cvt_pk_bf16_f32 v74, v74, v75
	v_cvt_pk_bf16_f32 v75, v84, v85
	global_store_dwordx4 v[80:81], v[72:75], off
	v_pk_mul_f32 v[68:69], v[68:69], v[82:83] op_sel_hi:[1,0]
	s_nop 0
	v_pk_mul_f32 v[72:73], v[66:67], v[82:83] op_sel_hi:[1,0]
	v_pk_mul_f32 v[66:67], v[64:65], v[82:83] op_sel_hi:[1,0]
	v_cvt_pk_bf16_f32 v64, v68, v69
	v_cvt_pk_bf16_f32 v65, v70, v71
	v_add_u32_e32 v68, 0x80, v138
	v_cvt_pk_bf16_f32 v66, v66, v67
	v_cvt_pk_bf16_f32 v67, v72, v73
	global_store_dwordx4 v[80:81], v[64:67], off offset:256
	s_nop 1
	v_mov_b64_e32 v[64:65], v[214:215]
	v_cvt_f64_u32_e32 v[66:67], v65
	v_ldexp_f64 v[66:67], v[66:67], 32
	v_cvt_f64_u32_e32 v[64:65], v64
	v_add_f64 v[64:65], v[66:67], v[64:65]
	v_ldexp_f64 v[64:65], v[64:65], s93
	v_cvt_f32_f64_e32 v64, v[64:65]
	v_fmamk_f32 v64, v64, 0x3a000000, v189
	v_cmp_gt_f32_e32 vcc, s78, v64
	v_mul_f32_e32 v65, 0x4b800000, v64
	v_mad_i64_i32 v[66:67], s[24:25], v68, s15, v[142:143]
	v_cndmask_b32_e32 v64, v64, v65, vcc
	v_rsq_f32_e32 v64, v64
	v_lshl_add_u64 v[66:67], v[66:67], 0, v[144:145]
	v_mul_f32_e32 v65, 0x45800000, v64
	v_cndmask_b32_e32 v64, v64, v65, vcc
	v_pk_mul_f32 v[62:63], v[62:63], v[64:65] op_sel_hi:[1,0]
	v_pk_mul_f32 v[60:61], v[60:61], v[64:65] op_sel_hi:[1,0]
	v_pk_mul_f32 v[68:69], v[58:59], v[64:65] op_sel_hi:[1,0]
; __device__ __forceinline__ unsigned cvt_pk_bf16(float lo, float hi) { unsigned r; asm volatile("v_cvt_pk_bf16_f32 %0, %1, %2" : "=v"(r) : "v"(lo), "v"(hi)); return r; }
; __device__ __forceinline__ float rinv_st(stat_t s, float invn) { return rsqrtf((float)((double)s * (1.0 / 4294967296.0)) * invn + 1e-6f); }
;     __device__ __forceinline__ void operator()(const f32x4 (&acc)[2][2][4][2], const Unit& u, int wr, int wc, int fr, int fq) const {
;     ...
;             for (int m = 0; m < 4; ++m) {
;                 const int row = row0 + ai * HALF + m * 16; const float r = rinv_st(stats[row], 1.0f / 2048.0f);
;                 bf16_t* rowp = raw + (size_t)row * NINP + col0;
; #pragma unroll
;                 for (int bj = 0; bj < 2; ++bj) {
;                     const f32x4 v0 = acc[ai][bj][m][0] * r, v1 = acc[ai][bj][m][1] * r;
;                     u32x4 w; w.x = cvt_pk_bf16(v0[0], v0[1]); w.y = cvt_pk_bf16(v0[2], v0[3]); w.z = cvt_pk_bf16(v1[0], v1[1]); w.w = cvt_pk_bf16(v1[2], v1[3]);
;                     *(u32x4*)(rowp + bj * HALF) = w;
;                 }
	v_pk_mul_f32 v[58:59], v[56:57], v[64:65] op_sel_hi:[1,0]
	v_cvt_pk_bf16_f32 v56, v60, v61
	v_cvt_pk_bf16_f32 v57, v62, v63
	v_pk_mul_f32 v[54:55], v[54:55], v[64:65] op_sel_hi:[1,0]
	v_cvt_pk_bf16_f32 v58, v58, v59
	v_cvt_pk_bf16_f32 v59, v68, v69
	global_store_dwordx4 v[66:67], v[56:59], off
	v_pk_mul_f32 v[52:53], v[52:53], v[64:65] op_sel_hi:[1,0]
	s_nop 0
	v_pk_mul_f32 v[56:57], v[50:51], v[64:65] op_sel_hi:[1,0]
	v_pk_mul_f32 v[50:51], v[48:49], v[64:65] op_sel_hi:[1,0]
	v_cvt_pk_bf16_f32 v48, v52, v53
	v_cvt_pk_bf16_f32 v49, v54, v55
	v_add_u32_e32 v52, 0x90, v138
	v_cvt_pk_bf16_f32 v50, v50, v51
	v_cvt_pk_bf16_f32 v51, v56, v57
	global_store_dwordx4 v[66:67], v[48:51], off offset:256
	s_nop 1
	v_mov_b64_e32 v[48:49], v[216:217]
	v_cvt_f64_u32_e32 v[50:51], v49
	v_ldexp_f64 v[50:51], v[50:51], 32
	v_cvt_f64_u32_e32 v[48:49], v48
	v_add_f64 v[48:49], v[50:51], v[48:49]
	v_ldexp_f64 v[48:49], v[48:49], s93
	v_cvt_f32_f64_e32 v48, v[48:49]
	v_fmamk_f32 v48, v48, 0x3a000000, v189
	v_cmp_gt_f32_e32 vcc, s78, v48
	v_mul_f32_e32 v49, 0x4b800000, v48
	v_mad_i64_i32 v[50:51], s[24:25], v52, s15, v[142:143]
	v_cndmask_b32_e32 v48, v48, v49, vcc
	v_rsq_f32_e32 v48, v48
	v_lshl_add_u64 v[50:51], v[50:51], 0, v[144:145]
	v_mul_f32_e32 v49, 0x45800000, v48
	v_cndmask_b32_e32 v48, v48, v49, vcc
	v_pk_mul_f32 v[46:47], v[46:47], v[48:49] op_sel_hi:[1,0]
	v_pk_mul_f32 v[44:45], v[44:45], v[48:49] op_sel_hi:[1,0]
	v_pk_mul_f32 v[52:53], v[42:43], v[48:49] op_sel_hi:[1,0]
	v_pk_mul_f32 v[42:43], v[40:41], v[48:49] op_sel_hi:[1,0]
	v_cvt_pk_bf16_f32 v40, v44, v45
	v_cvt_pk_bf16_f32 v41, v46, v47
	v_pk_mul_f32 v[38:39], v[38:39], v[48:49] op_sel_hi:[1,0]
	v_cvt_pk_bf16_f32 v42, v42, v43
	v_cvt_pk_bf16_f32 v43, v52, v53
	global_store_dwordx4 v[50:51], v[40:43], off
	v_pk_mul_f32 v[36:37], v[36:37], v[48:49] op_sel_hi:[1,0]
	s_nop 0
	v_pk_mul_f32 v[40:41], v[34:35], v[48:49] op_sel_hi:[1,0]
	v_pk_mul_f32 v[34:35], v[32:33], v[48:49] op_sel_hi:[1,0]
	v_cvt_pk_bf16_f32 v32, v36, v37
	v_cvt_pk_bf16_f32 v33, v38, v39
	v_add_u32_e32 v36, 0xa0, v138
	v_cvt_pk_bf16_f32 v34, v34, v35
	v_cvt_pk_bf16_f32 v35, v40, v41
	global_store_dwordx4 v[50:51], v[32:35], off offset:256
	s_nop 1
	v_mov_b64_e32 v[32:33], v[218:219]
	v_cvt_f64_u32_e32 v[34:35], v33
	v_ldexp_f64 v[34:35], v[34:35], 32
	v_cvt_f64_u32_e32 v[32:33], v32
	v_add_f64 v[32:33], v[34:35], v[32:33]
	v_ldexp_f64 v[32:33], v[32:33], s93
	v_cvt_f32_f64_e32 v32, v[32:33]
	v_fmamk_f32 v32, v32, 0x3a000000, v189
	v_cmp_gt_f32_e32 vcc, s78, v32
	v_mul_f32_e32 v33, 0x4b800000, v32
	v_mad_i64_i32 v[34:35], s[24:25], v36, s15, v[142:143]
	v_cndmask_b32_e32 v32, v32, v33, vcc
	v_rsq_f32_e32 v32, v32
	v_lshl_add_u64 v[34:35], v[34:35], 0, v[144:145]
	v_mul_f32_e32 v33, 0x45800000, v32
	v_cndmask_b32_e32 v32, v32, v33, vcc
	v_pk_mul_f32 v[30:31], v[30:31], v[32:33] op_sel_hi:[1,0]
	v_pk_mul_f32 v[28:29], v[28:29], v[32:33] op_sel_hi:[1,0]
	v_pk_mul_f32 v[36:37], v[26:27], v[32:33] op_sel_hi:[1,0]
	v_pk_mul_f32 v[26:27], v[24:25], v[32:33] op_sel_hi:[1,0]
	v_cvt_pk_bf16_f32 v24, v28, v29
	v_cvt_pk_bf16_f32 v25, v30, v31
	v_pk_mul_f32 v[22:23], v[22:23], v[32:33] op_sel_hi:[1,0]
	v_cvt_pk_bf16_f32 v26, v26, v27
	v_cvt_pk_bf16_f32 v27, v36, v37
	global_store_dwordx4 v[34:35], v[24:27], off
	v_pk_mul_f32 v[20:21], v[20:21], v[32:33] op_sel_hi:[1,0]
	s_nop 0
	v_pk_mul_f32 v[24:25], v[18:19], v[32:33] op_sel_hi:[1,0]
	v_pk_mul_f32 v[18:19], v[16:17], v[32:33] op_sel_hi:[1,0]
	v_cvt_pk_bf16_f32 v16, v20, v21
	v_cvt_pk_bf16_f32 v17, v22, v23
	v_add_u32_e32 v20, 0xb0, v138
	v_cvt_pk_bf16_f32 v18, v18, v19
	v_cvt_pk_bf16_f32 v19, v24, v25
	global_store_dwordx4 v[34:35], v[16:19], off offset:256
	s_nop 1
	v_mov_b64_e32 v[16:17], v[220:221]
	v_cvt_f64_u32_e32 v[18:19], v17
	v_ldexp_f64 v[18:19], v[18:19], 32
	v_cvt_f64_u32_e32 v[16:17], v16
	v_add_f64 v[16:17], v[18:19], v[16:17]
	v_ldexp_f64 v[16:17], v[16:17], s93
	v_cvt_f32_f64_e32 v16, v[16:17]
	v_fmamk_f32 v16, v16, 0x3a000000, v189
	v_cmp_gt_f32_e32 vcc, s78, v16
	v_mul_f32_e32 v17, 0x4b800000, v16
	v_mad_i64_i32 v[18:19], s[24:25], v20, s15, v[142:143]
	v_cndmask_b32_e32 v16, v16, v17, vcc
	v_rsq_f32_e32 v16, v16
	v_lshl_add_u64 v[18:19], v[18:19], 0, v[144:145]
	s_mov_b64 s[24:25], s[18:19]
	v_mul_f32_e32 v17, 0x45800000, v16
	v_cndmask_b32_e32 v16, v16, v17, vcc
	v_pk_mul_f32 v[14:15], v[14:15], v[16:17] op_sel_hi:[1,0]
	v_pk_mul_f32 v[12:13], v[12:13], v[16:17] op_sel_hi:[1,0]
	v_pk_mul_f32 v[20:21], v[10:11], v[16:17] op_sel_hi:[1,0]
	v_pk_mul_f32 v[10:11], v[8:9], v[16:17] op_sel_hi:[1,0]
	v_cvt_pk_bf16_f32 v8, v12, v13
	v_cvt_pk_bf16_f32 v9, v14, v15
	s_and_b64 vcc, exec, s[8:9]
	v_cvt_pk_bf16_f32 v10, v10, v11
	v_cvt_pk_bf16_f32 v11, v20, v21
	global_store_dwordx4 v[18:19], v[8:11], off
	v_pk_mul_f32 v[6:7], v[6:7], v[16:17] op_sel_hi:[1,0]
	v_pk_mul_f32 v[4:5], v[4:5], v[16:17] op_sel_hi:[1,0]
	v_pk_mul_f32 v[8:9], v[2:3], v[16:17] op_sel_hi:[1,0]
	v_pk_mul_f32 v[2:3], v[0:1], v[16:17] op_sel_hi:[1,0]
	v_cvt_pk_bf16_f32 v0, v4, v5
	v_cvt_pk_bf16_f32 v1, v6, v7
	s_nop 0
	v_cvt_pk_bf16_f32 v2, v2, v3
	v_cvt_pk_bf16_f32 v3, v8, v9
	global_store_dwordx4 v[18:19], v[0:3], off offset:256
	s_cbranch_vccz .LBB0_792
	s_waitcnt vmcnt(0)
	s_cmpk_gt_u32 s0, 0xff
	s_cbranch_scc1 .LBB0_803
	s_barrier

; #define PG8_STAGE(bufoff, gbase, voff) do { _Pragma("unroll") for (int _i = 0; _i < 2; ++_i) \
;         __builtin_amdgcn_global_load_lds((const unsigned*)((const char*)(gbase) + (voff)[_i]), (LAS unsigned*)(lds + (bufoff) + ldsw + _i * 8192), 16, 0, 0); } while (0)
; #define PG8_LDA(dst, b, h) do { _Pragma("unroll") for (int m = 0; m < 4; ++m) _Pragma("unroll") for (int k = 0; k < 2; ++k) dst[m][k] = *(const LAS bf16x8*)(lds + PG8_SA(b, h) + aoff + m * 2048 + k * 1024); } while (0)
; #define PG8_LDB(dst, b, h) do { _Pragma("unroll") for (int n = 0; n < 2; ++n) _Pragma("unroll") for (int k = 0; k < 2; ++k) dst[n][k] = *(const LAS bf16x8*)(lds + PG8_SB(b, h) + boff + n * 2048 + k * 1024); } while (0)
; #define PG8_MMA(ai, bj, At, Bt) do { __builtin_amdgcn_s_setprio(1); _Pragma("unroll") for (int m = 0; m < 4; ++m) _Pragma("unroll") for (int n = 0; n < 2; ++n) _Pragma("unroll") for (int k = 0; k < 2; ++k) \
;         acc[ai][bj][m][n] = __builtin_amdgcn_mfma_f32_16x16x32_bf16(Bt[n][k], At[m][k], acc[ai][bj][m][n], 0, 0, 0); __builtin_amdgcn_s_setprio(0); } while (0)
; #define PG8_WAIT_L(n) asm volatile("s_waitcnt lgkmcnt(" #n ")" ::: "memory")
; #define PG8_BAR __builtin_amdgcn_s_barrier()
; #define PG8_SCHED __builtin_amdgcn_sched_barrier(0)
; template <class Epi>
; __device__ __forceinline__ void gemm_phase(const int TID, const int BID, LAS unsigned char* lds, const Gemm g, const StaticOrder& S, const Epi& E) {
;     ...
;             PG8_LDB(B0, 0, 0); PG8_SCHED; PG8_LDA(At, 0, 0); PG8_STAGE(PG8_SA(1, 1), a1 + hstepA, voffA);
;             PG8_WAIT_L(8); PG8_BAR; PG8_WAIT_L(0); PG8_MMA(0, 0, At, B0); PG8_BAR; PG8_SCHED;
;             PG8_LDB(B1, 0, 1); PG8_STAGE(PG8_SB(0, 0), b2, voffB);
;             PG8_BAR; PG8_WAIT_L(0); PG8_MMA(0, 1, At, B1); PG8_BAR;
;             PG8_LDA(At, 0, 1); PG8_STAGE(PG8_SA(0, 0), a2, voffA);
;             PG8_BAR; PG8_WAIT_L(0); PG8_MMA(1, 0, At, B0); PG8_BAR; PG8_SCHED;
.LBB0_822:
	v_add_u32_e32 v154, s36, v147
	ds_read_b128 v[134:137], v154
	ds_read_b128 v[138:141], v154 offset:1024
	ds_read_b128 v[150:153], v154 offset:2048
	ds_read_b128 v[154:157], v154 offset:3072
	s_add_u32 s28, s26, 0xfff80080
	s_addc_u32 s29, s27, -1
	s_cmp_eq_u32 s66, 4
	s_cselect_b32 s31, s17, s29
	s_cselect_b32 s30, s61, s28
	s_cselect_b32 s29, s15, s64
	s_cselect_b32 s28, s62, s63
	v_lshl_add_u64 v[158:159], s[26:27], 0, v[130:131]
	s_add_i32 m0, s47, 0xc000
	ds_read_b128 v[166:169], v149
	ds_read_b128 v[170:173], v149 offset:1024
	ds_read_b128 v[174:177], v149 offset:2048
	ds_read_b128 v[178:181], v149 offset:3072
	ds_read_b128 v[182:185], v149 offset:4096
	ds_read_b128 v[196:199], v149 offset:5120
	ds_read_b128 v[208:211], v149 offset:6144
	ds_read_b128 v[212:215], v149 offset:7168
	global_load_lds_dwordx4 v[158:159], off
	v_lshl_add_u64 v[158:159], s[26:27], 0, v[132:133]
	s_add_i32 m0, s47, 0xe000
	s_nop 0
	global_load_lds_dwordx4 v[158:159], off
	s_waitcnt lgkmcnt(8)
	s_barrier
	s_waitcnt lgkmcnt(0)
	s_setprio 1
	s_waitcnt lgkmcnt(0)
	v_mfma_f32_16x16x32_bf16 v[124:127], v[134:137], v[166:169], v[124:127]
	v_mfma_f32_16x16x32_bf16 v[120:123], v[150:153], v[166:169], v[120:123]
	v_mfma_f32_16x16x32_bf16 v[108:111], v[134:137], v[174:177], v[108:111]
	v_mfma_f32_16x16x32_bf16 v[104:107], v[150:153], v[174:177], v[104:107]
	v_mfma_f32_16x16x32_bf16 v[92:95], v[134:137], v[182:185], v[92:95]
	v_mfma_f32_16x16x32_bf16 v[88:91], v[150:153], v[182:185], v[88:91]
	v_mfma_f32_16x16x32_bf16 v[76:79], v[134:137], v[208:211], v[76:79]
	v_mfma_f32_16x16x32_bf16 v[72:75], v[150:153], v[208:211], v[72:75]
	v_mfma_f32_16x16x32_bf16 v[124:127], v[138:141], v[170:173], v[124:127]
	v_mfma_f32_16x16x32_bf16 v[120:123], v[154:157], v[170:173], v[120:123]
	v_mfma_f32_16x16x32_bf16 v[108:111], v[138:141], v[178:181], v[108:111]
	v_mfma_f32_16x16x32_bf16 v[104:107], v[154:157], v[178:181], v[104:107]
	v_mfma_f32_16x16x32_bf16 v[92:95], v[138:141], v[196:199], v[92:95]
	v_mfma_f32_16x16x32_bf16 v[88:91], v[154:157], v[196:199], v[88:91]
	v_mfma_f32_16x16x32_bf16 v[76:79], v[138:141], v[212:215], v[76:79]
	v_mfma_f32_16x16x32_bf16 v[72:75], v[154:157], v[212:215], v[72:75]
	s_setprio 0
	s_barrier
	v_add_u32_e32 v158, s37, v147
	s_mov_b32 m0, s25
	ds_read_b128 v[216:219], v158
	ds_read_b128 v[220:223], v158 offset:1024
	ds_read_b128 v[224:227], v158 offset:2048
	ds_read_b128 v[228:231], v158 offset:3072
	v_lshl_add_u64 v[158:159], s[28:29], 0, v[160:161]
	global_load_lds_dwordx4 v[158:159], off
	v_lshl_add_u64 v[200:201], s[28:29], 0, v[128:129]
	s_mov_b32 m0, s46
	s_nop 0
	global_load_lds_dwordx4 v[200:201], off
	s_barrier
	s_waitcnt lgkmcnt(0)
	s_setprio 1
	s_waitcnt lgkmcnt(0)
	v_mfma_f32_16x16x32_bf16 v[116:119], v[216:219], v[166:169], v[116:119]
	v_mfma_f32_16x16x32_bf16 v[112:115], v[224:227], v[166:169], v[112:115]
	v_mfma_f32_16x16x32_bf16 v[100:103], v[216:219], v[174:177], v[100:103]
	v_mfma_f32_16x16x32_bf16 v[96:99], v[224:227], v[174:177], v[96:99]
	v_mfma_f32_16x16x32_bf16 v[84:87], v[216:219], v[182:185], v[84:87]
	v_mfma_f32_16x16x32_bf16 v[80:83], v[224:227], v[182:185], v[80:83]
	v_mfma_f32_16x16x32_bf16 v[68:71], v[216:219], v[208:211], v[68:71]
	v_mfma_f32_16x16x32_bf16 v[64:67], v[224:227], v[208:211], v[64:67]
	v_mfma_f32_16x16x32_bf16 v[116:119], v[220:223], v[170:173], v[116:119]
	v_mfma_f32_16x16x32_bf16 v[112:115], v[228:231], v[170:173], v[112:115]
	v_mfma_f32_16x16x32_bf16 v[100:103], v[220:223], v[178:181], v[100:103]
	v_mfma_f32_16x16x32_bf16 v[96:99], v[228:231], v[178:181], v[96:99]
	v_mfma_f32_16x16x32_bf16 v[84:87], v[220:223], v[196:199], v[84:87]
	v_mfma_f32_16x16x32_bf16 v[80:83], v[228:231], v[196:199], v[80:83]
	v_mfma_f32_16x16x32_bf16 v[68:71], v[220:223], v[212:215], v[68:71]
	v_mfma_f32_16x16x32_bf16 v[64:67], v[228:231], v[212:215], v[64:67]
	s_setprio 0
	s_mov_b32 m0, s47
	v_lshl_add_u64 v[232:233], s[30:31], 0, v[160:161]
	s_barrier
	ds_read_b128 v[166:169], v149 offset:16384
	ds_read_b128 v[170:173], v149 offset:17408
	ds_read_b128 v[174:177], v149 offset:18432
	ds_read_b128 v[178:181], v149 offset:19456
	ds_read_b128 v[182:185], v149 offset:20480
	ds_read_b128 v[196:199], v149 offset:21504
	ds_read_b128 v[208:211], v149 offset:22528
	ds_read_b128 v[212:215], v149 offset:23552
	global_load_lds_dwordx4 v[232:233], off
	v_lshl_add_u64 v[234:235], s[30:31], 0, v[128:129]
	s_mov_b32 m0, s48
	s_nop 0
	global_load_lds_dwordx4 v[234:235], off
	s_barrier
	s_waitcnt lgkmcnt(0)
	s_setprio 1
	s_waitcnt lgkmcnt(0)
	v_mfma_f32_16x16x32_bf16 v[60:63], v[134:137], v[166:169], v[60:63]
	v_mfma_f32_16x16x32_bf16 v[56:59], v[150:153], v[166:169], v[56:59]
	v_mfma_f32_16x16x32_bf16 v[44:47], v[134:137], v[174:177], v[44:47]
	v_mfma_f32_16x16x32_bf16 v[40:43], v[150:153], v[174:177], v[40:43]
	v_mfma_f32_16x16x32_bf16 v[28:31], v[134:137], v[182:185], v[28:31]
	v_mfma_f32_16x16x32_bf16 v[24:27], v[150:153], v[182:185], v[24:27]
	v_mfma_f32_16x16x32_bf16 v[12:15], v[134:137], v[208:211], v[12:15]
	v_mfma_f32_16x16x32_bf16 v[8:11], v[150:153], v[208:211], v[8:11]
	v_mfma_f32_16x16x32_bf16 v[60:63], v[138:141], v[170:173], v[60:63]
	v_mfma_f32_16x16x32_bf16 v[56:59], v[154:157], v[170:173], v[56:59]
	v_mfma_f32_16x16x32_bf16 v[44:47], v[138:141], v[178:181], v[44:47]
	v_mfma_f32_16x16x32_bf16 v[40:43], v[154:157], v[178:181], v[40:43]
	v_mfma_f32_16x16x32_bf16 v[28:31], v[138:141], v[196:199], v[28:31]
	v_mfma_f32_16x16x32_bf16 v[24:27], v[154:157], v[196:199], v[24:27]
	v_mfma_f32_16x16x32_bf16 v[12:15], v[138:141], v[212:215], v[12:15]
	v_mfma_f32_16x16x32_bf16 v[8:11], v[154:157], v[212:215], v[8:11]
	s_setprio 0
	s_barrier
; #define PG8_STAGE(bufoff, gbase, voff) do { _Pragma("unroll") for (int _i = 0; _i < 2; ++_i) \
;         __builtin_amdgcn_global_load_lds((const unsigned*)((const char*)(gbase) + (voff)[_i]), (LAS unsigned*)(lds + (bufoff) + ldsw + _i * 8192), 16, 0, 0); } while (0)
; #define PG8_LDA(dst, b, h) do { _Pragma("unroll") for (int m = 0; m < 4; ++m) _Pragma("unroll") for (int k = 0; k < 2; ++k) dst[m][k] = *(const LAS bf16x8*)(lds + PG8_SA(b, h) + aoff + m * 2048 + k * 1024); } while (0)
; #define PG8_LDB(dst, b, h) do { _Pragma("unroll") for (int n = 0; n < 2; ++n) _Pragma("unroll") for (int k = 0; k < 2; ++k) dst[n][k] = *(const LAS bf16x8*)(lds + PG8_SB(b, h) + boff + n * 2048 + k * 1024); } while (0)
; #define PG8_MMA(ai, bj, At, Bt) do { __builtin_amdgcn_s_setprio(1); _Pragma("unroll") for (int m = 0; m < 4; ++m) _Pragma("unroll") for (int n = 0; n < 2; ++n) _Pragma("unroll") for (int k = 0; k < 2; ++k) \
;         acc[ai][bj][m][n] = __builtin_amdgcn_mfma_f32_16x16x32_bf16(Bt[n][k], At[m][k], acc[ai][bj][m][n], 0, 0, 0); __builtin_amdgcn_s_setprio(0); } while (0)
; #define PG8_WAIT_V(n) asm volatile("s_waitcnt vmcnt(" #n ")" ::: "memory")
; #define PG8_WAIT_L(n) asm volatile("s_waitcnt lgkmcnt(" #n ")" ::: "memory")
; #define PG8_BAR __builtin_amdgcn_s_barrier()
; #define PG8_SCHED __builtin_amdgcn_sched_barrier(0)
; template <class Epi>
; __device__ __forceinline__ void gemm_phase(const int TID, const int BID, LAS unsigned char* lds, const Gemm g, const StaticOrder& S, const Epi& E) {
;     ...
;             PG8_WAIT_V(6); PG8_BAR; PG8_MMA(1, 1, At, B1); PG8_BAR;
;             PG8_LDB(B0, 1, 0); PG8_SCHED; PG8_LDA(At, 1, 0); PG8_STAGE(PG8_SA(0, 1), a2 + hstepA, voffA);
;             PG8_WAIT_L(8); PG8_BAR; PG8_WAIT_L(0); PG8_MMA(0, 0, At, B0); PG8_BAR; PG8_SCHED;
;             PG8_LDB(B1, 1, 1); PG8_STAGE(PG8_SB(1, 0), b3, voffB);
;             PG8_BAR; PG8_WAIT_L(0); PG8_MMA(0, 1, At, B1); PG8_BAR;
;             PG8_LDA(At, 1, 1); PG8_STAGE(PG8_SA(1, 0), a3, voffA);
	s_add_u32 s74, s28, 0x80000
	s_addc_u32 s75, s29, 0
	s_mov_b32 m0, s49
	v_lshl_add_u64 v[134:135], s[74:75], 0, v[160:161]
	global_load_lds_dwordx4 v[134:135], off
	v_lshl_add_u64 v[134:135], s[74:75], 0, v[128:129]
	s_mov_b32 m0, s50
	s_nop 0
	global_load_lds_dwordx4 v[134:135], off
	s_waitcnt vmcnt(6)
	s_barrier
	s_setprio 1
	v_mfma_f32_16x16x32_bf16 v[52:55], v[216:219], v[166:169], v[52:55]
	v_mfma_f32_16x16x32_bf16 v[48:51], v[224:227], v[166:169], v[48:51]
	v_mfma_f32_16x16x32_bf16 v[36:39], v[216:219], v[174:177], v[36:39]
	v_mfma_f32_16x16x32_bf16 v[32:35], v[224:227], v[174:177], v[32:35]
	v_mfma_f32_16x16x32_bf16 v[20:23], v[216:219], v[182:185], v[20:23]
	v_mfma_f32_16x16x32_bf16 v[16:19], v[224:227], v[182:185], v[16:19]
	v_mfma_f32_16x16x32_bf16 v[4:7], v[216:219], v[208:211], v[4:7]
	v_mfma_f32_16x16x32_bf16 v[0:3], v[224:227], v[208:211], v[0:3]
	v_mfma_f32_16x16x32_bf16 v[52:55], v[220:223], v[170:173], v[52:55]
	v_mfma_f32_16x16x32_bf16 v[48:51], v[228:231], v[170:173], v[48:51]
	v_mfma_f32_16x16x32_bf16 v[36:39], v[220:223], v[178:181], v[36:39]
	v_mfma_f32_16x16x32_bf16 v[32:35], v[228:231], v[178:181], v[32:35]
	v_mfma_f32_16x16x32_bf16 v[20:23], v[220:223], v[196:199], v[20:23]
	v_mfma_f32_16x16x32_bf16 v[16:19], v[228:231], v[196:199], v[16:19]
	v_mfma_f32_16x16x32_bf16 v[4:7], v[220:223], v[212:215], v[4:7]
	v_mfma_f32_16x16x32_bf16 v[0:3], v[228:231], v[212:215], v[0:3]
	s_setprio 0
	v_add_u32_e32 v154, s38, v147
	s_barrier
	ds_read_b128 v[134:137], v154
	ds_read_b128 v[138:141], v154 offset:1024
	ds_read_b128 v[150:153], v154 offset:2048
	ds_read_b128 v[154:157], v154 offset:3072
	s_add_u32 s30, s30, 0x80000
	s_addc_u32 s31, s31, 0
	s_mov_b32 m0, s51
	v_lshl_add_u64 v[216:217], s[30:31], 0, v[160:161]
	ds_read_b128 v[166:169], v149 offset:32768
	ds_read_b128 v[170:173], v149 offset:33792
	ds_read_b128 v[174:177], v149 offset:34816
	ds_read_b128 v[178:181], v149 offset:35840
	ds_read_b128 v[182:185], v149 offset:36864
	ds_read_b128 v[196:199], v149 offset:37888
	ds_read_b128 v[208:211], v149 offset:38912
	ds_read_b128 v[212:215], v149 offset:39936
	global_load_lds_dwordx4 v[216:217], off
	v_lshl_add_u64 v[216:217], s[30:31], 0, v[128:129]
	s_mov_b32 m0, s52
	s_nop 0
	global_load_lds_dwordx4 v[216:217], off
	s_waitcnt lgkmcnt(8)
	s_barrier
	s_waitcnt lgkmcnt(0)
	s_setprio 1
	s_waitcnt lgkmcnt(0)
	v_mfma_f32_16x16x32_bf16 v[124:127], v[134:137], v[166:169], v[124:127]
	v_mfma_f32_16x16x32_bf16 v[120:123], v[150:153], v[166:169], v[120:123]
	v_mfma_f32_16x16x32_bf16 v[108:111], v[134:137], v[174:177], v[108:111]
	v_mfma_f32_16x16x32_bf16 v[104:107], v[150:153], v[174:177], v[104:107]
	v_mfma_f32_16x16x32_bf16 v[92:95], v[134:137], v[182:185], v[92:95]
	v_mfma_f32_16x16x32_bf16 v[88:91], v[150:153], v[182:185], v[88:91]
	v_mfma_f32_16x16x32_bf16 v[76:79], v[134:137], v[208:211], v[76:79]
	v_mfma_f32_16x16x32_bf16 v[72:75], v[150:153], v[208:211], v[72:75]
	v_mfma_f32_16x16x32_bf16 v[124:127], v[138:141], v[170:173], v[124:127]
	v_mfma_f32_16x16x32_bf16 v[120:123], v[154:157], v[170:173], v[120:123]
	v_mfma_f32_16x16x32_bf16 v[108:111], v[138:141], v[178:181], v[108:111]
	v_mfma_f32_16x16x32_bf16 v[104:107], v[154:157], v[178:181], v[104:107]
	v_mfma_f32_16x16x32_bf16 v[92:95], v[138:141], v[196:199], v[92:95]
	v_mfma_f32_16x16x32_bf16 v[88:91], v[154:157], v[196:199], v[88:91]
	v_mfma_f32_16x16x32_bf16 v[76:79], v[138:141], v[212:215], v[76:79]
	v_mfma_f32_16x16x32_bf16 v[72:75], v[154:157], v[212:215], v[72:75]
	s_setprio 0
	s_barrier
	s_mov_b32 m0, s53
	v_add_u32_e32 v228, s39, v147
	v_lshl_add_u64 v[158:159], v[158:159], 0, s[90:91]
	ds_read_b128 v[216:219], v228
	ds_read_b128 v[220:223], v228 offset:1024
	ds_read_b128 v[224:227], v228 offset:2048
	ds_read_b128 v[228:231], v228 offset:3072
	global_load_lds_dwordx4 v[158:159], off
	v_lshl_add_u64 v[158:159], v[200:201], 0, s[90:91]
	s_mov_b32 m0, s54
	s_nop 0
	global_load_lds_dwordx4 v[158:159], off
	s_barrier
	s_waitcnt lgkmcnt(0)
	s_setprio 1
	s_waitcnt lgkmcnt(0)
	v_mfma_f32_16x16x32_bf16 v[116:119], v[216:219], v[166:169], v[116:119]
	v_mfma_f32_16x16x32_bf16 v[112:115], v[224:227], v[166:169], v[112:115]
	v_mfma_f32_16x16x32_bf16 v[100:103], v[216:219], v[174:177], v[100:103]
	v_mfma_f32_16x16x32_bf16 v[96:99], v[224:227], v[174:177], v[96:99]
	v_mfma_f32_16x16x32_bf16 v[84:87], v[216:219], v[182:185], v[84:87]
	v_mfma_f32_16x16x32_bf16 v[80:83], v[224:227], v[182:185], v[80:83]
	v_mfma_f32_16x16x32_bf16 v[68:71], v[216:219], v[208:211], v[68:71]
	v_mfma_f32_16x16x32_bf16 v[64:67], v[224:227], v[208:211], v[64:67]
	v_mfma_f32_16x16x32_bf16 v[116:119], v[220:223], v[170:173], v[116:119]
	v_mfma_f32_16x16x32_bf16 v[112:115], v[228:231], v[170:173], v[112:115]
	v_mfma_f32_16x16x32_bf16 v[100:103], v[220:223], v[178:181], v[100:103]
	v_mfma_f32_16x16x32_bf16 v[96:99], v[228:231], v[178:181], v[96:99]
	v_mfma_f32_16x16x32_bf16 v[84:87], v[220:223], v[196:199], v[84:87]
	v_mfma_f32_16x16x32_bf16 v[80:83], v[228:231], v[196:199], v[80:83]
	v_mfma_f32_16x16x32_bf16 v[68:71], v[220:223], v[212:215], v[68:71]
	v_mfma_f32_16x16x32_bf16 v[64:67], v[228:231], v[212:215], v[64:67]
	s_setprio 0
	s_mov_b32 m0, s55
	v_lshl_add_u64 v[158:159], v[232:233], 0, s[90:91]
	s_barrier
	ds_read_b128 v[166:169], v149 offset:49152
	ds_read_b128 v[170:173], v149 offset:50176
	ds_read_b128 v[174:177], v149 offset:51200
	ds_read_b128 v[178:181], v149 offset:52224
	ds_read_b128 v[182:185], v149 offset:53248
	ds_read_b128 v[196:199], v149 offset:54272
	ds_read_b128 v[208:211], v149 offset:55296
	ds_read_b128 v[212:215], v149 offset:56320
	global_load_lds_dwordx4 v[158:159], off
	v_lshl_add_u64 v[158:159], v[234:235], 0, s[90:91]
	s_mov_b32 m0, s56
	s_nop 0
	global_load_lds_dwordx4 v[158:159], off
	s_barrier
; __device__ __forceinline__ float rinv_st(stat_t s, float invn) { return rsqrtf((float)((double)s * (1.0 / 4294967296.0)) * invn + 1e-6f); }
; #define PG8_STAGE(bufoff, gbase, voff) do { _Pragma("unroll") for (int _i = 0; _i < 2; ++_i) \
;         __builtin_amdgcn_global_load_lds((const unsigned*)((const char*)(gbase) + (voff)[_i]), (LAS unsigned*)(lds + (bufoff) + ldsw + _i * 8192), 16, 0, 0); } while (0)
; #define PG8_MMA(ai, bj, At, Bt) do { __builtin_amdgcn_s_setprio(1); _Pragma("unroll") for (int m = 0; m < 4; ++m) _Pragma("unroll") for (int n = 0; n < 2; ++n) _Pragma("unroll") for (int k = 0; k < 2; ++k) \
;         acc[ai][bj][m][n] = __builtin_amdgcn_mfma_f32_16x16x32_bf16(Bt[n][k], At[m][k], acc[ai][bj][m][n], 0, 0, 0); __builtin_amdgcn_s_setprio(0); } while (0)
; #define PG8_WAIT_V(n) asm volatile("s_waitcnt vmcnt(" #n ")" ::: "memory")
; #define PG8_WAIT_L(n) asm volatile("s_waitcnt lgkmcnt(" #n ")" ::: "memory")
; #define PG8_BAR __builtin_amdgcn_s_barrier()
; #define PG8_SCHED __builtin_amdgcn_sched_barrier(0)
; template <class Epi>
; __device__ __forceinline__ void gemm_phase(const int TID, const int BID, LAS unsigned char* lds, const Gemm g, const StaticOrder& S, const Epi& E) {
;     ...
;             PG8_BAR; PG8_WAIT_L(0); PG8_MMA(1, 0, At, B0); PG8_BAR; PG8_SCHED;
;             PG8_STAGE(PG8_SB(1, 1), b3 + hstepB, voffB);
;             PG8_WAIT_V(6); PG8_BAR; PG8_MMA(1, 1, At, B1); PG8_BAR;
;     __device__ __forceinline__ void operator()(const f32x4 (&acc)[2][2][4][2], const Unit& u, int wr, int wc, int fr, int fq) const {
;         const int row0 = u.pm * BM + wr * 64 + fr, col0 = u.pn * BM + wc * 32 + 4 * fq;
; #pragma unroll
;         for (int ai = 0; ai < 2; ++ai)
; #pragma unroll
;             for (int m = 0; m < 4; ++m) {
;                 const int row = row0 + ai * HALF + m * 16; const float r = rinv_st(stats[row], 1.0f / 2048.0f);
;                 float* rowp = raw + (size_t)row * 256 + col0;
; #pragma unroll
;                 for (int bj = 0; bj < 2; ++bj)
; #pragma unroll
;                     for (int n = 0; n < 2; ++n) *(f32x4*)(rowp + bj * HALF + n * 16) = acc[ai][bj][m][n] * r;
	s_waitcnt lgkmcnt(0)
	s_setprio 1
	s_waitcnt lgkmcnt(0)
	v_mfma_f32_16x16x32_bf16 v[60:63], v[134:137], v[166:169], v[60:63]
	v_mfma_f32_16x16x32_bf16 v[56:59], v[150:153], v[166:169], v[56:59]
	v_mfma_f32_16x16x32_bf16 v[44:47], v[134:137], v[174:177], v[44:47]
	v_mfma_f32_16x16x32_bf16 v[40:43], v[150:153], v[174:177], v[40:43]
	v_mfma_f32_16x16x32_bf16 v[28:31], v[134:137], v[182:185], v[28:31]
	v_mfma_f32_16x16x32_bf16 v[24:27], v[150:153], v[182:185], v[24:27]
	v_mfma_f32_16x16x32_bf16 v[12:15], v[134:137], v[208:211], v[12:15]
	v_mfma_f32_16x16x32_bf16 v[8:11], v[150:153], v[208:211], v[8:11]
	v_mfma_f32_16x16x32_bf16 v[60:63], v[138:141], v[170:173], v[60:63]
	v_mfma_f32_16x16x32_bf16 v[56:59], v[154:157], v[170:173], v[56:59]
	v_mfma_f32_16x16x32_bf16 v[44:47], v[138:141], v[178:181], v[44:47]
	v_mfma_f32_16x16x32_bf16 v[40:43], v[154:157], v[178:181], v[40:43]
	v_mfma_f32_16x16x32_bf16 v[28:31], v[138:141], v[196:199], v[28:31]
	v_mfma_f32_16x16x32_bf16 v[24:27], v[154:157], v[196:199], v[24:27]
	v_mfma_f32_16x16x32_bf16 v[12:15], v[138:141], v[212:215], v[12:15]
	v_mfma_f32_16x16x32_bf16 v[8:11], v[154:157], v[212:215], v[8:11]
	s_setprio 0
	s_barrier
	s_add_u32 s28, s28, 0x80080
	s_addc_u32 s29, s29, 0
	s_mov_b32 m0, s57
	v_lshl_add_u64 v[134:135], s[28:29], 0, v[160:161]
	global_load_lds_dwordx4 v[134:135], off
	v_lshl_add_u64 v[134:135], s[28:29], 0, v[128:129]
	s_mov_b32 m0, s58
	s_nop 0
	global_load_lds_dwordx4 v[134:135], off
	s_waitcnt vmcnt(6)
	s_barrier
	s_setprio 1
	v_mfma_f32_16x16x32_bf16 v[52:55], v[216:219], v[166:169], v[52:55]
	v_mfma_f32_16x16x32_bf16 v[48:51], v[224:227], v[166:169], v[48:51]
	v_mfma_f32_16x16x32_bf16 v[36:39], v[216:219], v[174:177], v[36:39]
	v_mfma_f32_16x16x32_bf16 v[32:35], v[224:227], v[174:177], v[32:35]
	v_mfma_f32_16x16x32_bf16 v[20:23], v[216:219], v[182:185], v[20:23]
	v_mfma_f32_16x16x32_bf16 v[16:19], v[224:227], v[182:185], v[16:19]
	v_mfma_f32_16x16x32_bf16 v[4:7], v[216:219], v[208:211], v[4:7]
	v_mfma_f32_16x16x32_bf16 v[0:3], v[224:227], v[208:211], v[0:3]
	v_mfma_f32_16x16x32_bf16 v[52:55], v[220:223], v[170:173], v[52:55]
	v_mfma_f32_16x16x32_bf16 v[48:51], v[228:231], v[170:173], v[48:51]
	v_mfma_f32_16x16x32_bf16 v[36:39], v[220:223], v[178:181], v[36:39]
	v_mfma_f32_16x16x32_bf16 v[32:35], v[228:231], v[178:181], v[32:35]
	v_mfma_f32_16x16x32_bf16 v[20:23], v[220:223], v[196:199], v[20:23]
	v_mfma_f32_16x16x32_bf16 v[16:19], v[228:231], v[196:199], v[16:19]
	v_mfma_f32_16x16x32_bf16 v[4:7], v[220:223], v[212:215], v[4:7]
	v_mfma_f32_16x16x32_bf16 v[0:3], v[228:231], v[212:215], v[0:3]
	s_setprio 0
	s_add_i32 s66, s66, 2
	s_add_u32 s26, s26, 0x100
	s_addc_u32 s27, s27, 0
	s_add_u32 s63, s63, 0x100
	s_addc_u32 s64, s64, 0
	s_cmp_gt_u32 s66, 5
	s_barrier
	s_cbranch_scc0 .LBB0_822
	v_lshl_add_u32 v140, s24, 8, v145
	v_ashrrev_i32_e32 v141, 31, v140
	v_lshl_add_u64 v[136:137], v[140:141], 3, s[10:11]
	global_load_dwordx2 v[138:139], v[136:137], off
	global_load_dwordx2 v[208:209], v[136:137], off offset:128
	global_load_dwordx2 v[210:211], v[136:137], off offset:256
	global_load_dwordx2 v[212:213], v[136:137], off offset:384
	global_load_dwordx2 v[214:215], v[136:137], off offset:1024
	global_load_dwordx2 v[216:217], v[136:137], off offset:1152
	global_load_dwordx2 v[218:219], v[136:137], off offset:1280
	global_load_dwordx2 v[220:221], v[136:137], off offset:1408
	v_lshl_or_b32 v134, s60, 8, v148
	v_ashrrev_i32_e32 v135, 31, v134
	s_mov_b32 s15, 0x20000
	s_mov_b64 s[26:27], 0x20000
	s_mov_b32 s60, s14
	s_mov_b32 s24, s16
	s_mov_b64 s[28:29], s[22:23]
	s_waitcnt vmcnt(0)
	v_cvt_f64_u32_e32 v[150:151], v139
	v_ldexp_f64 v[150:151], v[150:151], 32
	v_cvt_f64_u32_e32 v[138:139], v138
	v_add_f64 v[138:139], v[150:151], v[138:139]
	v_ldexp_f64 v[138:139], v[138:139], s93
	v_cvt_f32_f64_e32 v138, v[138:139]
	v_fmamk_f32 v138, v138, 0x3a000000, v189
	v_cmp_gt_f32_e32 vcc, s78, v138
	v_mul_f32_e32 v139, 0x4b800000, v138
	s_nop 0
	v_cndmask_b32_e32 v138, v138, v139, vcc
	v_rsq_f32_e32 v138, v138
	s_nop 0
	v_mul_f32_e32 v139, 0x45800000, v138
	v_cndmask_b32_e32 v150, v138, v139, vcc
	v_lshlrev_b64 v[138:139], 10, v[140:141]
	v_lshl_add_u64 v[152:153], s[12:13], 0, v[138:139]
	v_lshlrev_b64 v[138:139], 2, v[134:135]
	v_lshl_add_u64 v[134:135], v[152:153], 0, v[138:139]
	v_pk_mul_f32 v[114:115], v[114:115], v[150:151] op_sel_hi:[1,0]
	v_pk_mul_f32 v[112:113], v[112:113], v[150:151] op_sel_hi:[1,0]
	global_store_dwordx4 v[134:135], v[112:115], off offset:576
	v_pk_mul_f32 v[126:127], v[126:127], v[150:151] op_sel_hi:[1,0]
	v_pk_mul_f32 v[124:125], v[124:125], v[150:151] op_sel_hi:[1,0]
	v_or_b32_e32 v112, 16, v140
	v_pk_mul_f32 v[122:123], v[122:123], v[150:151] op_sel_hi:[1,0]
	v_pk_mul_f32 v[120:121], v[120:121], v[150:151] op_sel_hi:[1,0]
	v_pk_mul_f32 v[118:119], v[118:119], v[150:151] op_sel_hi:[1,0]
	v_pk_mul_f32 v[116:117], v[116:117], v[150:151] op_sel_hi:[1,0]
	v_ashrrev_i32_e32 v113, 31, v112
	global_store_dwordx4 v[134:135], v[124:127], off
	global_store_dwordx4 v[134:135], v[120:123], off offset:64
	global_store_dwordx4 v[134:135], v[116:119], off offset:512
	v_lshl_add_u64 v[114:115], v[112:113], 3, s[10:11]
	s_nop 1
	v_mov_b64_e32 v[114:115], v[208:209]
	v_lshlrev_b64 v[112:113], 10, v[112:113]
	v_lshl_add_u64 v[112:113], s[12:13], 0, v[112:113]
	v_lshl_add_u64 v[112:113], v[112:113], 0, v[138:139]
	v_cvt_f64_u32_e32 v[116:117], v115
	v_ldexp_f64 v[116:117], v[116:117], 32
	v_cvt_f64_u32_e32 v[114:115], v114
	v_add_f64 v[114:115], v[116:117], v[114:115]
	v_ldexp_f64 v[114:115], v[114:115], s93
	v_cvt_f32_f64_e32 v114, v[114:115]
	v_fmamk_f32 v114, v114, 0x3a000000, v189
; __device__ __forceinline__ float rinv_st(stat_t s, float invn) { return rsqrtf((float)((double)s * (1.0 / 4294967296.0)) * invn + 1e-6f); }
;     __device__ __forceinline__ void operator()(const f32x4 (&acc)[2][2][4][2], const Unit& u, int wr, int wc, int fr, int fq) const {
;     ...
;         for (int ai = 0; ai < 2; ++ai)
; #pragma unroll
;             for (int m = 0; m < 4; ++m) {
;                 const int row = row0 + ai * HALF + m * 16; const float r = rinv_st(stats[row], 1.0f / 2048.0f);
;                 float* rowp = raw + (size_t)row * 256 + col0;
; #pragma unroll
;                 for (int bj = 0; bj < 2; ++bj)
; #pragma unroll
;                     for (int n = 0; n < 2; ++n) *(f32x4*)(rowp + bj * HALF + n * 16) = acc[ai][bj][m][n] * r;
	v_cmp_gt_f32_e32 vcc, s78, v114
	v_mul_f32_e32 v115, 0x4b800000, v114
	s_nop 0
	v_cndmask_b32_e32 v114, v114, v115, vcc
	v_rsq_f32_e32 v114, v114
	s_nop 0
	v_mul_f32_e32 v115, 0x45800000, v114
	v_cndmask_b32_e32 v114, v114, v115, vcc
	v_pk_mul_f32 v[98:99], v[98:99], v[114:115] op_sel_hi:[1,0]
	v_pk_mul_f32 v[96:97], v[96:97], v[114:115] op_sel_hi:[1,0]
	global_store_dwordx4 v[112:113], v[96:99], off offset:576
	v_pk_mul_f32 v[110:111], v[110:111], v[114:115] op_sel_hi:[1,0]
	v_pk_mul_f32 v[108:109], v[108:109], v[114:115] op_sel_hi:[1,0]
	v_or_b32_e32 v96, 32, v140
	v_pk_mul_f32 v[106:107], v[106:107], v[114:115] op_sel_hi:[1,0]
	v_pk_mul_f32 v[104:105], v[104:105], v[114:115] op_sel_hi:[1,0]
	v_pk_mul_f32 v[102:103], v[102:103], v[114:115] op_sel_hi:[1,0]
	v_pk_mul_f32 v[100:101], v[100:101], v[114:115] op_sel_hi:[1,0]
	v_ashrrev_i32_e32 v97, 31, v96
	global_store_dwordx4 v[112:113], v[108:111], off
	global_store_dwordx4 v[112:113], v[104:107], off offset:64
	global_store_dwordx4 v[112:113], v[100:103], off offset:512
	v_lshl_add_u64 v[98:99], v[96:97], 3, s[10:11]
	s_nop 1
	v_mov_b64_e32 v[98:99], v[210:211]
	v_lshlrev_b64 v[96:97], 10, v[96:97]
	v_lshl_add_u64 v[96:97], s[12:13], 0, v[96:97]
	v_lshl_add_u64 v[96:97], v[96:97], 0, v[138:139]
	v_cvt_f64_u32_e32 v[100:101], v99
	v_ldexp_f64 v[100:101], v[100:101], 32
	v_cvt_f64_u32_e32 v[98:99], v98
	v_add_f64 v[98:99], v[100:101], v[98:99]
	v_ldexp_f64 v[98:99], v[98:99], s93
	v_cvt_f32_f64_e32 v98, v[98:99]
	v_fmamk_f32 v98, v98, 0x3a000000, v189
	v_cmp_gt_f32_e32 vcc, s78, v98
	v_mul_f32_e32 v99, 0x4b800000, v98
	s_nop 0
	v_cndmask_b32_e32 v98, v98, v99, vcc
	v_rsq_f32_e32 v98, v98
	s_nop 0
	v_mul_f32_e32 v99, 0x45800000, v98
	v_cndmask_b32_e32 v98, v98, v99, vcc
	v_pk_mul_f32 v[82:83], v[82:83], v[98:99] op_sel_hi:[1,0]
	v_pk_mul_f32 v[80:81], v[80:81], v[98:99] op_sel_hi:[1,0]
	global_store_dwordx4 v[96:97], v[80:83], off offset:576
	v_pk_mul_f32 v[94:95], v[94:95], v[98:99] op_sel_hi:[1,0]
	v_pk_mul_f32 v[92:93], v[92:93], v[98:99] op_sel_hi:[1,0]
	v_or_b32_e32 v80, 48, v140
	v_pk_mul_f32 v[90:91], v[90:91], v[98:99] op_sel_hi:[1,0]
	v_pk_mul_f32 v[88:89], v[88:89], v[98:99] op_sel_hi:[1,0]
	v_pk_mul_f32 v[86:87], v[86:87], v[98:99] op_sel_hi:[1,0]
	v_pk_mul_f32 v[84:85], v[84:85], v[98:99] op_sel_hi:[1,0]
	v_ashrrev_i32_e32 v81, 31, v80
	global_store_dwordx4 v[96:97], v[92:95], off
	global_store_dwordx4 v[96:97], v[88:91], off offset:64
	global_store_dwordx4 v[96:97], v[84:87], off offset:512
	v_lshl_add_u64 v[82:83], v[80:81], 3, s[10:11]
	s_nop 1
	v_mov_b64_e32 v[82:83], v[212:213]
	v_lshlrev_b64 v[80:81], 10, v[80:81]
	v_lshl_add_u64 v[80:81], s[12:13], 0, v[80:81]
	v_lshl_add_u64 v[80:81], v[80:81], 0, v[138:139]
	v_cvt_f64_u32_e32 v[84:85], v83
	v_ldexp_f64 v[84:85], v[84:85], 32
	v_cvt_f64_u32_e32 v[82:83], v82
	v_add_f64 v[82:83], v[84:85], v[82:83]
	v_ldexp_f64 v[82:83], v[82:83], s93
	v_cvt_f32_f64_e32 v82, v[82:83]
	v_fmamk_f32 v82, v82, 0x3a000000, v189
	v_cmp_gt_f32_e32 vcc, s78, v82
	v_mul_f32_e32 v83, 0x4b800000, v82
	s_nop 0
	v_cndmask_b32_e32 v82, v82, v83, vcc
	v_rsq_f32_e32 v82, v82
	s_nop 0
	v_mul_f32_e32 v83, 0x45800000, v82
	v_cndmask_b32_e32 v82, v82, v83, vcc
	v_pk_mul_f32 v[78:79], v[78:79], v[82:83] op_sel_hi:[1,0]
	v_pk_mul_f32 v[76:77], v[76:77], v[82:83] op_sel_hi:[1,0]
	v_pk_mul_f32 v[74:75], v[74:75], v[82:83] op_sel_hi:[1,0]
	v_pk_mul_f32 v[72:73], v[72:73], v[82:83] op_sel_hi:[1,0]
	v_pk_mul_f32 v[70:71], v[70:71], v[82:83] op_sel_hi:[1,0]
	v_pk_mul_f32 v[68:69], v[68:69], v[82:83] op_sel_hi:[1,0]
	v_pk_mul_f32 v[66:67], v[66:67], v[82:83] op_sel_hi:[1,0]
	v_pk_mul_f32 v[64:65], v[64:65], v[82:83] op_sel_hi:[1,0]
	global_store_dwordx4 v[80:81], v[76:79], off
	global_store_dwordx4 v[80:81], v[72:75], off offset:64
	global_store_dwordx4 v[80:81], v[68:71], off offset:512
	global_store_dwordx4 v[80:81], v[64:67], off offset:576
	s_nop 1
	v_mov_b64_e32 v[64:65], v[214:215]
	v_cvt_f64_u32_e32 v[66:67], v65
	v_ldexp_f64 v[66:67], v[66:67], 32
	v_cvt_f64_u32_e32 v[64:65], v64
	v_add_f64 v[64:65], v[66:67], v[64:65]
	v_ldexp_f64 v[64:65], v[64:65], s93
	v_cvt_f32_f64_e32 v64, v[64:65]
	v_fmamk_f32 v64, v64, 0x3a000000, v189
	v_cmp_gt_f32_e32 vcc, s78, v64
	v_mul_f32_e32 v65, 0x4b800000, v64
	v_lshl_add_u64 v[66:67], v[134:135], 0, s[26:27]
	v_cndmask_b32_e32 v64, v64, v65, vcc
	v_rsq_f32_e32 v64, v64
	s_mov_b64 s[26:27], 0x24000
	v_mul_f32_e32 v65, 0x45800000, v64
	v_cndmask_b32_e32 v64, v64, v65, vcc
	v_add_co_u32_e32 v68, vcc, s15, v134
	v_pk_mul_f32 v[62:63], v[62:63], v[64:65] op_sel_hi:[1,0]
	v_pk_mul_f32 v[60:61], v[60:61], v[64:65] op_sel_hi:[1,0]
	v_addc_co_u32_e32 v69, vcc, 0, v135, vcc
	v_pk_mul_f32 v[58:59], v[58:59], v[64:65] op_sel_hi:[1,0]
; __device__ __forceinline__ float rinv_st(stat_t s, float invn) { return rsqrtf((float)((double)s * (1.0 / 4294967296.0)) * invn + 1e-6f); }
; #define PG8_WAIT_V(n) asm volatile("s_waitcnt vmcnt(" #n ")" ::: "memory")
; #define PG8_BAR __builtin_amdgcn_s_barrier()
; template <class Epi>
; __device__ __forceinline__ void gemm_phase(const int TID, const int BID, LAS unsigned char* lds, const Gemm g, const StaticOrder& S, const Epi& E) {
;     ...
;         if (!has_next) break;
; #pragma unroll
;         for (int a = 0; a < 2; ++a)
; #pragma unroll
;             for (int b = 0; b < 2; ++b)
; #pragma unroll
;                 for (int m = 0; m < 4; ++m)
; #pragma unroll
;                     for (int n = 0; n < 2; ++n) acc[a][b][m][n] = (f32x4){0.f, 0.f, 0.f, 0.f};
;         cur = nxt; cA = nA; cB = nB; ++ui;
;     }
;     PG8_WAIT_V(0);
;     if (wr == 0) PG8_BAR;
;     PG8_BAR;
;     __device__ __forceinline__ void operator()(const f32x4 (&acc)[2][2][4][2], const Unit& u, int wr, int wc, int fr, int fq) const {
;     ...
;             for (int m = 0; m < 4; ++m) {
;                 const int row = row0 + ai * HALF + m * 16; const float r = rinv_st(stats[row], 1.0f / 2048.0f);
;                 float* rowp = raw + (size_t)row * 256 + col0;
; #pragma unroll
;                 for (int bj = 0; bj < 2; ++bj)
; #pragma unroll
;                     for (int n = 0; n < 2; ++n) *(f32x4*)(rowp + bj * HALF + n * 16) = acc[ai][bj][m][n] * r;
	v_pk_mul_f32 v[56:57], v[56:57], v[64:65] op_sel_hi:[1,0]
	v_pk_mul_f32 v[54:55], v[54:55], v[64:65] op_sel_hi:[1,0]
	v_pk_mul_f32 v[52:53], v[52:53], v[64:65] op_sel_hi:[1,0]
	v_pk_mul_f32 v[50:51], v[50:51], v[64:65] op_sel_hi:[1,0]
	v_pk_mul_f32 v[48:49], v[48:49], v[64:65] op_sel_hi:[1,0]
	global_store_dwordx4 v[68:69], v[60:63], off
	global_store_dwordx4 v[66:67], v[56:59], off offset:64
	global_store_dwordx4 v[66:67], v[52:55], off offset:512
	global_store_dwordx4 v[66:67], v[48:51], off offset:576
	s_nop 1
	v_mov_b64_e32 v[48:49], v[216:217]
	s_mov_b32 s15, 0x24000
	v_cvt_f64_u32_e32 v[50:51], v49
	v_ldexp_f64 v[50:51], v[50:51], 32
	v_cvt_f64_u32_e32 v[48:49], v48
	v_add_f64 v[48:49], v[50:51], v[48:49]
	v_ldexp_f64 v[48:49], v[48:49], s93
	v_cvt_f32_f64_e32 v48, v[48:49]
	v_fmamk_f32 v48, v48, 0x3a000000, v189
	v_cmp_gt_f32_e32 vcc, s78, v48
	v_mul_f32_e32 v49, 0x4b800000, v48
	v_lshl_add_u64 v[50:51], v[134:135], 0, s[26:27]
	v_cndmask_b32_e32 v48, v48, v49, vcc
	v_rsq_f32_e32 v48, v48
	s_mov_b64 s[26:27], 0x28000
	v_mul_f32_e32 v49, 0x45800000, v48
	v_cndmask_b32_e32 v48, v48, v49, vcc
	v_add_co_u32_e32 v52, vcc, s15, v134
	v_pk_mul_f32 v[46:47], v[46:47], v[48:49] op_sel_hi:[1,0]
	v_pk_mul_f32 v[44:45], v[44:45], v[48:49] op_sel_hi:[1,0]
	v_addc_co_u32_e32 v53, vcc, 0, v135, vcc
	v_pk_mul_f32 v[42:43], v[42:43], v[48:49] op_sel_hi:[1,0]
	v_pk_mul_f32 v[40:41], v[40:41], v[48:49] op_sel_hi:[1,0]
	v_pk_mul_f32 v[38:39], v[38:39], v[48:49] op_sel_hi:[1,0]
	v_pk_mul_f32 v[36:37], v[36:37], v[48:49] op_sel_hi:[1,0]
	v_pk_mul_f32 v[34:35], v[34:35], v[48:49] op_sel_hi:[1,0]
	v_pk_mul_f32 v[32:33], v[32:33], v[48:49] op_sel_hi:[1,0]
	global_store_dwordx4 v[52:53], v[44:47], off
	global_store_dwordx4 v[50:51], v[40:43], off offset:64
	global_store_dwordx4 v[50:51], v[36:39], off offset:512
	global_store_dwordx4 v[50:51], v[32:35], off offset:576
	s_nop 1
	v_mov_b64_e32 v[32:33], v[218:219]
	s_mov_b32 s15, 0x28000
	v_cvt_f64_u32_e32 v[34:35], v33
	v_ldexp_f64 v[34:35], v[34:35], 32
	v_cvt_f64_u32_e32 v[32:33], v32
	v_add_f64 v[32:33], v[34:35], v[32:33]
	v_ldexp_f64 v[32:33], v[32:33], s93
	v_cvt_f32_f64_e32 v32, v[32:33]
	v_fmamk_f32 v32, v32, 0x3a000000, v189
	v_cmp_gt_f32_e32 vcc, s78, v32
	v_mul_f32_e32 v33, 0x4b800000, v32
	v_lshl_add_u64 v[34:35], v[134:135], 0, s[26:27]
	v_cndmask_b32_e32 v32, v32, v33, vcc
	v_rsq_f32_e32 v32, v32
	s_mov_b64 s[26:27], 0x2c000
	v_mul_f32_e32 v33, 0x45800000, v32
	v_cndmask_b32_e32 v32, v32, v33, vcc
	v_add_co_u32_e32 v36, vcc, s15, v134
	v_pk_mul_f32 v[30:31], v[30:31], v[32:33] op_sel_hi:[1,0]
	v_pk_mul_f32 v[28:29], v[28:29], v[32:33] op_sel_hi:[1,0]
	v_addc_co_u32_e32 v37, vcc, 0, v135, vcc
	v_pk_mul_f32 v[26:27], v[26:27], v[32:33] op_sel_hi:[1,0]
	v_pk_mul_f32 v[24:25], v[24:25], v[32:33] op_sel_hi:[1,0]
	v_pk_mul_f32 v[22:23], v[22:23], v[32:33] op_sel_hi:[1,0]
	v_pk_mul_f32 v[20:21], v[20:21], v[32:33] op_sel_hi:[1,0]
	v_pk_mul_f32 v[18:19], v[18:19], v[32:33] op_sel_hi:[1,0]
	v_pk_mul_f32 v[16:17], v[16:17], v[32:33] op_sel_hi:[1,0]
	global_store_dwordx4 v[36:37], v[28:31], off
	global_store_dwordx4 v[34:35], v[24:27], off offset:64
	global_store_dwordx4 v[34:35], v[20:23], off offset:512
	global_store_dwordx4 v[34:35], v[16:19], off offset:576
	s_nop 1
	v_mov_b64_e32 v[16:17], v[220:221]
	s_mov_b32 s15, 0x2c000
	v_cvt_f64_u32_e32 v[18:19], v17
	v_ldexp_f64 v[18:19], v[18:19], 32
	v_cvt_f64_u32_e32 v[16:17], v16
	v_add_f64 v[16:17], v[18:19], v[16:17]
	v_ldexp_f64 v[16:17], v[16:17], s93
	v_cvt_f32_f64_e32 v16, v[16:17]
	v_fmamk_f32 v16, v16, 0x3a000000, v189
	v_cmp_gt_f32_e32 vcc, s78, v16
	v_mul_f32_e32 v17, 0x4b800000, v16
	v_lshl_add_u64 v[18:19], v[134:135], 0, s[26:27]
	v_cndmask_b32_e32 v16, v16, v17, vcc
	v_rsq_f32_e32 v16, v16
	s_mov_b64 s[26:27], s[20:21]
	v_mul_f32_e32 v17, 0x45800000, v16
	v_cndmask_b32_e32 v16, v16, v17, vcc
	v_add_co_u32_e32 v20, vcc, s15, v134
	v_pk_mul_f32 v[14:15], v[14:15], v[16:17] op_sel_hi:[1,0]
	s_nop 0
	v_addc_co_u32_e32 v21, vcc, 0, v135, vcc
	v_pk_mul_f32 v[12:13], v[12:13], v[16:17] op_sel_hi:[1,0]
	v_pk_mul_f32 v[10:11], v[10:11], v[16:17] op_sel_hi:[1,0]
	v_pk_mul_f32 v[8:9], v[8:9], v[16:17] op_sel_hi:[1,0]
	v_pk_mul_f32 v[6:7], v[6:7], v[16:17] op_sel_hi:[1,0]
	v_pk_mul_f32 v[4:5], v[4:5], v[16:17] op_sel_hi:[1,0]
	v_pk_mul_f32 v[2:3], v[2:3], v[16:17] op_sel_hi:[1,0]
	v_pk_mul_f32 v[0:1], v[0:1], v[16:17] op_sel_hi:[1,0]
	s_and_b64 vcc, exec, s[18:19]
	global_store_dwordx4 v[20:21], v[12:15], off
	global_store_dwordx4 v[18:19], v[8:11], off offset:64
	global_store_dwordx4 v[18:19], v[4:7], off offset:512
	global_store_dwordx4 v[18:19], v[0:3], off offset:576
	s_cbranch_vccz .LBB0_815
	s_waitcnt vmcnt(0)
	s_cmpk_gt_u32 s42, 0xff
	s_cbranch_scc1 .LBB0_805
	s_barrier
	s_branch .LBB0_805

; #define PG8_STAGE(bufoff, gbase, voff) do { _Pragma("unroll") for (int _i = 0; _i < 2; ++_i) \
;         __builtin_amdgcn_global_load_lds((const unsigned*)((const char*)(gbase) + (voff)[_i]), (LAS unsigned*)(lds + (bufoff) + ldsw + _i * 8192), 16, 0, 0); } while (0)
; #define PG8_LDA(dst, b, h) do { _Pragma("unroll") for (int m = 0; m < 4; ++m) _Pragma("unroll") for (int k = 0; k < 2; ++k) dst[m][k] = *(const LAS bf16x8*)(lds + PG8_SA(b, h) + aoff + m * 2048 + k * 1024); } while (0)
; #define PG8_LDB(dst, b, h) do { _Pragma("unroll") for (int n = 0; n < 2; ++n) _Pragma("unroll") for (int k = 0; k < 2; ++k) dst[n][k] = *(const LAS bf16x8*)(lds + PG8_SB(b, h) + boff + n * 2048 + k * 1024); } while (0)
; #define PG8_MMA(ai, bj, At, Bt) do { __builtin_amdgcn_s_setprio(1); _Pragma("unroll") for (int m = 0; m < 4; ++m) _Pragma("unroll") for (int n = 0; n < 2; ++n) _Pragma("unroll") for (int k = 0; k < 2; ++k) \
;         acc[ai][bj][m][n] = __builtin_amdgcn_mfma_f32_16x16x32_bf16(Bt[n][k], At[m][k], acc[ai][bj][m][n], 0, 0, 0); __builtin_amdgcn_s_setprio(0); } while (0)
; #define PG8_WAIT_L(n) asm volatile("s_waitcnt lgkmcnt(" #n ")" ::: "memory")
; #define PG8_BAR __builtin_amdgcn_s_barrier()
; #define PG8_SCHED __builtin_amdgcn_sched_barrier(0)
; template <class Epi>
; __device__ __forceinline__ void gemm_phase(const int TID, const int BID, LAS unsigned char* lds, const Gemm g, const StaticOrder& S, const Epi& E) {
;     ...
;         for (int t = 0; t < nt; t += 2) {
;             const bool last = (t == nt - 2);
;             const char* a1 = cA + (size_t)(t + 1) * kstep;
;             const char* a2 = last ? nA : cA + (size_t)(t + 2) * kstep; const char* b2 = last ? nB : cB + (size_t)(t + 2) * kstep;
;             const char* a3 = a2 + kstep; const char* b3 = b2 + kstep;
;             PG8_LDB(B0, 0, 0); PG8_SCHED; PG8_LDA(At, 0, 0); PG8_STAGE(PG8_SA(1, 1), a1 + hstepA, voffA);
;             PG8_WAIT_L(8); PG8_BAR; PG8_WAIT_L(0); PG8_MMA(0, 0, At, B0); PG8_BAR; PG8_SCHED;
;             PG8_LDB(B1, 0, 1); PG8_STAGE(PG8_SB(0, 0), b2, voffB);
;             PG8_BAR; PG8_WAIT_L(0); PG8_MMA(0, 1, At, B1); PG8_BAR;
;             PG8_LDA(At, 0, 1); PG8_STAGE(PG8_SA(0, 0), a2, voffA);
;             PG8_BAR; PG8_WAIT_L(0); PG8_MMA(1, 0, At, B0); PG8_BAR; PG8_SCHED;
.LBB0_864:
	v_add_u32_e32 v36, s43, v172
	ds_read_b128 v[8:11], v36
	ds_read_b128 v[12:15], v36 offset:1024
	ds_read_b128 v[32:35], v36 offset:2048
	ds_read_b128 v[36:39], v36 offset:3072
	s_add_u32 s36, s34, 0xfff80080
	s_addc_u32 s37, s35, -1
	s_cmp_eq_u32 s31, 28
	s_cselect_b32 s39, s0, s37
	s_cselect_b32 s38, s1, s36
	s_cselect_b32 s37, s4, s29
	s_cselect_b32 s36, s21, s23
	v_lshl_add_u64 v[158:159], s[34:35], 0, v[150:151]
	s_add_i32 m0, s46, 0xc000
	ds_read_b128 v[154:157], v174
	ds_read_b128 v[176:179], v174 offset:1024
	ds_read_b128 v[180:183], v174 offset:2048
	ds_read_b128 v[196:199], v174 offset:3072
	ds_read_b128 v[208:211], v174 offset:4096
	ds_read_b128 v[212:215], v174 offset:5120
	ds_read_b128 v[216:219], v174 offset:6144
	ds_read_b128 v[220:223], v174 offset:7168
	global_load_lds_dwordx4 v[158:159], off
	v_lshl_add_u64 v[158:159], s[34:35], 0, v[152:153]
	s_add_i32 m0, s46, 0xe000
	s_nop 0
	global_load_lds_dwordx4 v[158:159], off
	s_waitcnt lgkmcnt(8)
	s_barrier
	s_waitcnt lgkmcnt(0)
	s_setprio 1
	s_waitcnt lgkmcnt(0)
	v_mfma_f32_16x16x32_bf16 v[140:143], v[8:11], v[154:157], v[140:143]
	v_mfma_f32_16x16x32_bf16 v[136:139], v[32:35], v[154:157], v[136:139]
	v_mfma_f32_16x16x32_bf16 v[124:127], v[8:11], v[180:183], v[124:127]
	v_mfma_f32_16x16x32_bf16 v[120:123], v[32:35], v[180:183], v[120:123]
	v_mfma_f32_16x16x32_bf16 v[108:111], v[8:11], v[208:211], v[108:111]
	v_mfma_f32_16x16x32_bf16 v[104:107], v[32:35], v[208:211], v[104:107]
	v_mfma_f32_16x16x32_bf16 v[92:95], v[8:11], v[216:219], v[92:95]
	v_mfma_f32_16x16x32_bf16 v[88:91], v[32:35], v[216:219], v[88:91]
	v_mfma_f32_16x16x32_bf16 v[140:143], v[12:15], v[176:179], v[140:143]
	v_mfma_f32_16x16x32_bf16 v[136:139], v[36:39], v[176:179], v[136:139]
	v_mfma_f32_16x16x32_bf16 v[124:127], v[12:15], v[196:199], v[124:127]
	v_mfma_f32_16x16x32_bf16 v[120:123], v[36:39], v[196:199], v[120:123]
	v_mfma_f32_16x16x32_bf16 v[108:111], v[12:15], v[212:215], v[108:111]
	v_mfma_f32_16x16x32_bf16 v[104:107], v[36:39], v[212:215], v[104:107]
	v_mfma_f32_16x16x32_bf16 v[92:95], v[12:15], v[220:223], v[92:95]
	v_mfma_f32_16x16x32_bf16 v[88:91], v[36:39], v[220:223], v[88:91]
	s_setprio 0
	s_barrier
	v_add_u32_e32 v158, s48, v172
	s_mov_b32 m0, s44
	ds_read_b128 v[224:227], v158
	ds_read_b128 v[228:231], v158 offset:1024
	ds_read_b128 v[232:235], v158 offset:2048
	ds_read_b128 v[236:239], v158 offset:3072
	v_lshl_add_u64 v[158:159], s[36:37], 0, v[160:161]
	global_load_lds_dwordx4 v[158:159], off
	v_lshl_add_u64 v[166:167], s[36:37], 0, v[148:149]
	s_mov_b32 m0, s45
	s_nop 0
	global_load_lds_dwordx4 v[166:167], off
	s_barrier
	s_waitcnt lgkmcnt(0)
	s_setprio 1
	s_waitcnt lgkmcnt(0)
	v_mfma_f32_16x16x32_bf16 v[132:135], v[224:227], v[154:157], v[132:135]
	v_mfma_f32_16x16x32_bf16 v[128:131], v[232:235], v[154:157], v[128:131]
	v_mfma_f32_16x16x32_bf16 v[116:119], v[224:227], v[180:183], v[116:119]
	v_mfma_f32_16x16x32_bf16 v[112:115], v[232:235], v[180:183], v[112:115]
	v_mfma_f32_16x16x32_bf16 v[100:103], v[224:227], v[208:211], v[100:103]
	v_mfma_f32_16x16x32_bf16 v[96:99], v[232:235], v[208:211], v[96:99]
	v_mfma_f32_16x16x32_bf16 v[84:87], v[224:227], v[216:219], v[84:87]
	v_mfma_f32_16x16x32_bf16 v[80:83], v[232:235], v[216:219], v[80:83]
	v_mfma_f32_16x16x32_bf16 v[132:135], v[228:231], v[176:179], v[132:135]
	v_mfma_f32_16x16x32_bf16 v[128:131], v[236:239], v[176:179], v[128:131]
	v_mfma_f32_16x16x32_bf16 v[116:119], v[228:231], v[196:199], v[116:119]
	v_mfma_f32_16x16x32_bf16 v[112:115], v[236:239], v[196:199], v[112:115]
	v_mfma_f32_16x16x32_bf16 v[100:103], v[228:231], v[212:215], v[100:103]
	v_mfma_f32_16x16x32_bf16 v[96:99], v[236:239], v[212:215], v[96:99]
	v_mfma_f32_16x16x32_bf16 v[84:87], v[228:231], v[220:223], v[84:87]
	v_mfma_f32_16x16x32_bf16 v[80:83], v[236:239], v[220:223], v[80:83]
	s_setprio 0
	s_mov_b32 m0, s46
	v_lshl_add_u64 v[170:171], s[38:39], 0, v[144:145]
	s_barrier
	ds_read_b128 v[154:157], v174 offset:16384
	ds_read_b128 v[176:179], v174 offset:17408
	ds_read_b128 v[180:183], v174 offset:18432
	ds_read_b128 v[196:199], v174 offset:19456
	ds_read_b128 v[208:211], v174 offset:20480
	ds_read_b128 v[212:215], v174 offset:21504
	ds_read_b128 v[216:219], v174 offset:22528
	ds_read_b128 v[220:223], v174 offset:23552
	global_load_lds_dwordx4 v[170:171], off
	v_lshl_add_u64 v[184:185], s[38:39], 0, v[146:147]
	s_mov_b32 m0, s47
	s_nop 0
	global_load_lds_dwordx4 v[184:185], off
	s_barrier
	s_waitcnt lgkmcnt(0)
	s_setprio 1
	s_waitcnt lgkmcnt(0)
	v_mfma_f32_16x16x32_bf16 v[76:79], v[8:11], v[154:157], v[76:79]
	v_mfma_f32_16x16x32_bf16 v[72:75], v[32:35], v[154:157], v[72:75]
	v_mfma_f32_16x16x32_bf16 v[60:63], v[8:11], v[180:183], v[60:63]
	v_mfma_f32_16x16x32_bf16 v[56:59], v[32:35], v[180:183], v[56:59]
	v_mfma_f32_16x16x32_bf16 v[44:47], v[8:11], v[208:211], v[44:47]
	v_mfma_f32_16x16x32_bf16 v[40:43], v[32:35], v[208:211], v[40:43]
	v_mfma_f32_16x16x32_bf16 v[8:11], v[8:11], v[216:219], v[20:23]
	v_mfma_f32_16x16x32_bf16 v[76:79], v[12:15], v[176:179], v[76:79]
	v_mfma_f32_16x16x32_bf16 v[72:75], v[36:39], v[176:179], v[72:75]
	v_mfma_f32_16x16x32_bf16 v[60:63], v[12:15], v[196:199], v[60:63]
	v_mfma_f32_16x16x32_bf16 v[56:59], v[36:39], v[196:199], v[56:59]
	v_mfma_f32_16x16x32_bf16 v[44:47], v[12:15], v[212:215], v[44:47]
	v_mfma_f32_16x16x32_bf16 v[40:43], v[36:39], v[212:215], v[40:43]
	v_mfma_f32_16x16x32_bf16 v[8:11], v[12:15], v[220:223], v[8:11]
	v_mfma_f32_16x16x32_bf16 v[12:15], v[32:35], v[216:219], v[16:19]
	v_mfma_f32_16x16x32_bf16 v[12:15], v[36:39], v[220:223], v[12:15]
	s_setprio 0
	s_barrier
; #define PG8_STAGE(bufoff, gbase, voff) do { _Pragma("unroll") for (int _i = 0; _i < 2; ++_i) \
;         __builtin_amdgcn_global_load_lds((const unsigned*)((const char*)(gbase) + (voff)[_i]), (LAS unsigned*)(lds + (bufoff) + ldsw + _i * 8192), 16, 0, 0); } while (0)
; #define PG8_LDA(dst, b, h) do { _Pragma("unroll") for (int m = 0; m < 4; ++m) _Pragma("unroll") for (int k = 0; k < 2; ++k) dst[m][k] = *(const LAS bf16x8*)(lds + PG8_SA(b, h) + aoff + m * 2048 + k * 1024); } while (0)
; #define PG8_LDB(dst, b, h) do { _Pragma("unroll") for (int n = 0; n < 2; ++n) _Pragma("unroll") for (int k = 0; k < 2; ++k) dst[n][k] = *(const LAS bf16x8*)(lds + PG8_SB(b, h) + boff + n * 2048 + k * 1024); } while (0)
; #define PG8_MMA(ai, bj, At, Bt) do { __builtin_amdgcn_s_setprio(1); _Pragma("unroll") for (int m = 0; m < 4; ++m) _Pragma("unroll") for (int n = 0; n < 2; ++n) _Pragma("unroll") for (int k = 0; k < 2; ++k) \
;         acc[ai][bj][m][n] = __builtin_amdgcn_mfma_f32_16x16x32_bf16(Bt[n][k], At[m][k], acc[ai][bj][m][n], 0, 0, 0); __builtin_amdgcn_s_setprio(0); } while (0)
; #define PG8_WAIT_V(n) asm volatile("s_waitcnt vmcnt(" #n ")" ::: "memory")
; #define PG8_WAIT_L(n) asm volatile("s_waitcnt lgkmcnt(" #n ")" ::: "memory")
; #define PG8_BAR __builtin_amdgcn_s_barrier()
; #define PG8_SCHED __builtin_amdgcn_sched_barrier(0)
; template <class Epi>
; __device__ __forceinline__ void gemm_phase(const int TID, const int BID, LAS unsigned char* lds, const Gemm g, const StaticOrder& S, const Epi& E) {
;     ...
;             PG8_STAGE(PG8_SB(0, 1), b2 + hstepB, voffB);
;             PG8_WAIT_V(6); PG8_BAR; PG8_MMA(1, 1, At, B1); PG8_BAR;
;             PG8_LDB(B0, 1, 0); PG8_SCHED; PG8_LDA(At, 1, 0); PG8_STAGE(PG8_SA(0, 1), a2 + hstepA, voffA);
;             PG8_WAIT_L(8); PG8_BAR; PG8_WAIT_L(0); PG8_MMA(0, 0, At, B0); PG8_BAR; PG8_SCHED;
;             PG8_LDB(B1, 1, 1); PG8_STAGE(PG8_SB(1, 0), b3, voffB);
;             PG8_BAR; PG8_WAIT_L(0); PG8_MMA(0, 1, At, B1); PG8_BAR;
;             PG8_LDA(At, 1, 1); PG8_STAGE(PG8_SA(1, 0), a3, voffA);
	s_add_u32 s66, s36, 0x80000
	s_addc_u32 s67, s37, 0
	s_mov_b32 m0, s49
	v_lshl_add_u64 v[16:17], s[66:67], 0, v[160:161]
	global_load_lds_dwordx4 v[16:17], off
	v_lshl_add_u64 v[16:17], s[66:67], 0, v[148:149]
	s_mov_b32 m0, s50
	s_nop 0
	global_load_lds_dwordx4 v[16:17], off
	s_waitcnt vmcnt(6)
	s_barrier
	s_setprio 1
	v_mfma_f32_16x16x32_bf16 v[16:19], v[224:227], v[154:157], v[68:71]
	v_mfma_f32_16x16x32_bf16 v[32:35], v[228:231], v[176:179], v[16:19]
	v_mfma_f32_16x16x32_bf16 v[16:19], v[232:235], v[154:157], v[64:67]
	v_mfma_f32_16x16x32_bf16 v[36:39], v[236:239], v[176:179], v[16:19]
	v_mfma_f32_16x16x32_bf16 v[16:19], v[224:227], v[180:183], v[52:55]
	v_mfma_f32_16x16x32_bf16 v[52:55], v[228:231], v[196:199], v[16:19]
	v_mfma_f32_16x16x32_bf16 v[16:19], v[232:235], v[180:183], v[48:51]
	v_mfma_f32_16x16x32_bf16 v[48:51], v[236:239], v[196:199], v[16:19]
	v_mfma_f32_16x16x32_bf16 v[16:19], v[224:227], v[208:211], v[28:31]
	v_mfma_f32_16x16x32_bf16 v[28:31], v[228:231], v[212:215], v[16:19]
	v_mfma_f32_16x16x32_bf16 v[16:19], v[232:235], v[208:211], v[24:27]
	v_mfma_f32_16x16x32_bf16 v[4:7], v[224:227], v[216:219], v[4:7]
	v_mfma_f32_16x16x32_bf16 v[0:3], v[232:235], v[216:219], v[0:3]
	v_mfma_f32_16x16x32_bf16 v[24:27], v[236:239], v[212:215], v[16:19]
	v_mfma_f32_16x16x32_bf16 v[4:7], v[228:231], v[220:223], v[4:7]
	v_mfma_f32_16x16x32_bf16 v[0:3], v[236:239], v[220:223], v[0:3]
	s_setprio 0
	v_add_u32_e32 v68, s53, v172
	s_barrier
	ds_read_b128 v[16:19], v68
	ds_read_b128 v[20:23], v68 offset:1024
	ds_read_b128 v[64:67], v68 offset:2048
	ds_read_b128 v[68:71], v68 offset:3072
	s_add_u32 s38, s38, 0x80000
	s_addc_u32 s39, s39, 0
	s_mov_b32 m0, s51
	v_lshl_add_u64 v[200:201], s[38:39], 0, v[144:145]
	ds_read_b128 v[154:157], v174 offset:32768
	ds_read_b128 v[176:179], v174 offset:33792
	ds_read_b128 v[180:183], v174 offset:34816
	ds_read_b128 v[196:199], v174 offset:35840
	ds_read_b128 v[208:211], v174 offset:36864
	ds_read_b128 v[212:215], v174 offset:37888
	ds_read_b128 v[216:219], v174 offset:38912
	ds_read_b128 v[220:223], v174 offset:39936
	global_load_lds_dwordx4 v[200:201], off
	v_lshl_add_u64 v[200:201], s[38:39], 0, v[146:147]
	s_mov_b32 m0, s52
	s_nop 0
	global_load_lds_dwordx4 v[200:201], off
	s_waitcnt lgkmcnt(8)
	s_barrier
	s_waitcnt lgkmcnt(0)
	s_setprio 1
	s_waitcnt lgkmcnt(0)
	v_mfma_f32_16x16x32_bf16 v[140:143], v[16:19], v[154:157], v[140:143]
	v_mfma_f32_16x16x32_bf16 v[136:139], v[64:67], v[154:157], v[136:139]
	v_mfma_f32_16x16x32_bf16 v[124:127], v[16:19], v[180:183], v[124:127]
	v_mfma_f32_16x16x32_bf16 v[120:123], v[64:67], v[180:183], v[120:123]
	v_mfma_f32_16x16x32_bf16 v[108:111], v[16:19], v[208:211], v[108:111]
	v_mfma_f32_16x16x32_bf16 v[104:107], v[64:67], v[208:211], v[104:107]
	v_mfma_f32_16x16x32_bf16 v[92:95], v[16:19], v[216:219], v[92:95]
	v_mfma_f32_16x16x32_bf16 v[88:91], v[64:67], v[216:219], v[88:91]
	v_mfma_f32_16x16x32_bf16 v[140:143], v[20:23], v[176:179], v[140:143]
	v_mfma_f32_16x16x32_bf16 v[136:139], v[68:71], v[176:179], v[136:139]
	v_mfma_f32_16x16x32_bf16 v[124:127], v[20:23], v[196:199], v[124:127]
	v_mfma_f32_16x16x32_bf16 v[120:123], v[68:71], v[196:199], v[120:123]
	v_mfma_f32_16x16x32_bf16 v[108:111], v[20:23], v[212:215], v[108:111]
	v_mfma_f32_16x16x32_bf16 v[104:107], v[68:71], v[212:215], v[104:107]
	v_mfma_f32_16x16x32_bf16 v[92:95], v[20:23], v[220:223], v[92:95]
	v_mfma_f32_16x16x32_bf16 v[88:91], v[68:71], v[220:223], v[88:91]
	s_setprio 0
	s_barrier
	s_mov_b32 m0, s54
	v_add_u32_e32 v168, s58, v172
	v_lshl_add_u64 v[158:159], v[158:159], 0, s[90:91]
	ds_read_b128 v[224:227], v168
	ds_read_b128 v[228:231], v168 offset:1024
	ds_read_b128 v[232:235], v168 offset:2048
	ds_read_b128 v[236:239], v168 offset:3072
	global_load_lds_dwordx4 v[158:159], off
	v_lshl_add_u64 v[158:159], v[166:167], 0, s[90:91]
	s_mov_b32 m0, s55
	s_nop 0
	global_load_lds_dwordx4 v[158:159], off
	s_barrier
	s_waitcnt lgkmcnt(0)
	s_setprio 1
	s_waitcnt lgkmcnt(0)
	v_mfma_f32_16x16x32_bf16 v[132:135], v[224:227], v[154:157], v[132:135]
	v_mfma_f32_16x16x32_bf16 v[128:131], v[232:235], v[154:157], v[128:131]
	v_mfma_f32_16x16x32_bf16 v[116:119], v[224:227], v[180:183], v[116:119]
	v_mfma_f32_16x16x32_bf16 v[112:115], v[232:235], v[180:183], v[112:115]
	v_mfma_f32_16x16x32_bf16 v[100:103], v[224:227], v[208:211], v[100:103]
	v_mfma_f32_16x16x32_bf16 v[96:99], v[232:235], v[208:211], v[96:99]
	v_mfma_f32_16x16x32_bf16 v[84:87], v[224:227], v[216:219], v[84:87]
	v_mfma_f32_16x16x32_bf16 v[80:83], v[232:235], v[216:219], v[80:83]
	v_mfma_f32_16x16x32_bf16 v[132:135], v[228:231], v[176:179], v[132:135]
	v_mfma_f32_16x16x32_bf16 v[128:131], v[236:239], v[176:179], v[128:131]
	v_mfma_f32_16x16x32_bf16 v[116:119], v[228:231], v[196:199], v[116:119]
	v_mfma_f32_16x16x32_bf16 v[112:115], v[236:239], v[196:199], v[112:115]
	v_mfma_f32_16x16x32_bf16 v[100:103], v[228:231], v[212:215], v[100:103]
	v_mfma_f32_16x16x32_bf16 v[96:99], v[236:239], v[212:215], v[96:99]
	v_mfma_f32_16x16x32_bf16 v[84:87], v[228:231], v[220:223], v[84:87]
	v_mfma_f32_16x16x32_bf16 v[80:83], v[236:239], v[220:223], v[80:83]
	s_setprio 0
	s_mov_b32 m0, s56
	v_lshl_add_u64 v[158:159], v[170:171], 0, s[90:91]
	s_barrier
	ds_read_b128 v[154:157], v174 offset:49152
	ds_read_b128 v[176:179], v174 offset:50176
	ds_read_b128 v[180:183], v174 offset:51200
	ds_read_b128 v[196:199], v174 offset:52224
	ds_read_b128 v[208:211], v174 offset:53248
	ds_read_b128 v[212:215], v174 offset:54272
	ds_read_b128 v[216:219], v174 offset:55296
	ds_read_b128 v[220:223], v174 offset:56320
	global_load_lds_dwordx4 v[158:159], off
	v_lshl_add_u64 v[158:159], v[184:185], 0, s[90:91]
	s_mov_b32 m0, s57
	s_nop 0
	global_load_lds_dwordx4 v[158:159], off
	s_barrier
; __device__ __forceinline__ float rinv_st(stat_t s, float invn) { return rsqrtf((float)((double)s * (1.0 / 4294967296.0)) * invn + 1e-6f); }
; #define PG8_STAGE(bufoff, gbase, voff) do { _Pragma("unroll") for (int _i = 0; _i < 2; ++_i) \
;         __builtin_amdgcn_global_load_lds((const unsigned*)((const char*)(gbase) + (voff)[_i]), (LAS unsigned*)(lds + (bufoff) + ldsw + _i * 8192), 16, 0, 0); } while (0)
; #define PG8_MMA(ai, bj, At, Bt) do { __builtin_amdgcn_s_setprio(1); _Pragma("unroll") for (int m = 0; m < 4; ++m) _Pragma("unroll") for (int n = 0; n < 2; ++n) _Pragma("unroll") for (int k = 0; k < 2; ++k) \
;         acc[ai][bj][m][n] = __builtin_amdgcn_mfma_f32_16x16x32_bf16(Bt[n][k], At[m][k], acc[ai][bj][m][n], 0, 0, 0); __builtin_amdgcn_s_setprio(0); } while (0)
; #define PG8_WAIT_V(n) asm volatile("s_waitcnt vmcnt(" #n ")" ::: "memory")
; template <class Epi>
; __device__ __forceinline__ void gemm_phase(const int TID, const int BID, LAS unsigned char* lds, const Gemm g, const StaticOrder& S, const Epi& E) {
;     ...
;             PG8_BAR; PG8_WAIT_L(0); PG8_MMA(1, 0, At, B0); PG8_BAR; PG8_SCHED;
;             PG8_STAGE(PG8_SB(1, 1), b3 + hstepB, voffB);
;             PG8_WAIT_V(6); PG8_BAR; PG8_MMA(1, 1, At, B1); PG8_BAR;
;     __device__ __forceinline__ void operator()(const f32x4 (&acc)[2][2][4][2], const Unit& u, int wr, int wc, int fr, int fq) const {
;         const int row0 = u.pm * BM + wr * 64 + fr, col0 = u.pn * BM + wc * 32 + 8 * fq;
;         f32x4 bv[2][2];
; #pragma unroll
;         for (int bj = 0; bj < 2; ++bj)
; #pragma unroll
;             for (int n = 0; n < 2; ++n) bv[bj][n] = *(const f32x4*)(bias + col0 + bj * HALF + 4 * n);
;         const bool isv = u.pn >= 8;
; #pragma unroll
;         for (int ai = 0; ai < 2; ++ai)
; #pragma unroll
;             for (int m = 0; m < 4; ++m) {
;                 const int row = row0 + ai * HALF + m * 16; const float r = rinv_st(stats[row], 1.0f / 2048.0f);
;                 bf16_t* rowp = uv + (size_t)row * 4096 + col0; float ss = 0.f;
; #pragma unroll
;                 for (int bj = 0; bj < 2; ++bj) {
;                     const f32x4 v0 = acc[ai][bj][m][0] * r + bv[bj][0], v1 = acc[ai][bj][m][1] * r + bv[bj][1];
;                     const f32x2 a = gelu_pk((f32x2){v0[0], v0[1]}), b = gelu_pk((f32x2){v0[2], v0[3]}), c = gelu_pk((f32x2){v1[0], v1[1]}), d = gelu_pk((f32x2){v1[2], v1[3]});
	s_waitcnt lgkmcnt(0)
	s_setprio 1
	s_waitcnt lgkmcnt(0)
	v_mfma_f32_16x16x32_bf16 v[76:79], v[16:19], v[154:157], v[76:79]
	v_mfma_f32_16x16x32_bf16 v[60:63], v[16:19], v[180:183], v[60:63]
	v_mfma_f32_16x16x32_bf16 v[44:47], v[16:19], v[208:211], v[44:47]
	v_mfma_f32_16x16x32_bf16 v[8:11], v[16:19], v[216:219], v[8:11]
	v_mfma_f32_16x16x32_bf16 v[76:79], v[20:23], v[176:179], v[76:79]
	v_mfma_f32_16x16x32_bf16 v[72:75], v[64:67], v[154:157], v[72:75]
	v_mfma_f32_16x16x32_bf16 v[60:63], v[20:23], v[196:199], v[60:63]
	v_mfma_f32_16x16x32_bf16 v[56:59], v[64:67], v[180:183], v[56:59]
	v_mfma_f32_16x16x32_bf16 v[44:47], v[20:23], v[212:215], v[44:47]
	v_mfma_f32_16x16x32_bf16 v[40:43], v[64:67], v[208:211], v[40:43]
	v_mfma_f32_16x16x32_bf16 v[20:23], v[20:23], v[220:223], v[8:11]
	v_mfma_f32_16x16x32_bf16 v[8:11], v[64:67], v[216:219], v[12:15]
	v_mfma_f32_16x16x32_bf16 v[72:75], v[68:71], v[176:179], v[72:75]
	v_mfma_f32_16x16x32_bf16 v[56:59], v[68:71], v[196:199], v[56:59]
	v_mfma_f32_16x16x32_bf16 v[40:43], v[68:71], v[212:215], v[40:43]
	v_mfma_f32_16x16x32_bf16 v[16:19], v[68:71], v[220:223], v[8:11]
	s_setprio 0
	s_barrier
	s_add_u32 s36, s36, 0x80080
	s_addc_u32 s37, s37, 0
	s_mov_b32 m0, s59
	v_lshl_add_u64 v[8:9], s[36:37], 0, v[160:161]
	global_load_lds_dwordx4 v[8:9], off
	v_lshl_add_u64 v[8:9], s[36:37], 0, v[148:149]
	s_mov_b32 m0, s60
	s_nop 0
	global_load_lds_dwordx4 v[8:9], off
	s_waitcnt vmcnt(6)
	s_barrier
	s_setprio 1
	v_mfma_f32_16x16x32_bf16 v[8:11], v[224:227], v[154:157], v[32:35]
	v_mfma_f32_16x16x32_bf16 v[68:71], v[228:231], v[176:179], v[8:11]
	v_mfma_f32_16x16x32_bf16 v[8:11], v[232:235], v[154:157], v[36:39]
	v_mfma_f32_16x16x32_bf16 v[64:67], v[236:239], v[176:179], v[8:11]
	v_mfma_f32_16x16x32_bf16 v[8:11], v[224:227], v[180:183], v[52:55]
	v_mfma_f32_16x16x32_bf16 v[52:55], v[228:231], v[196:199], v[8:11]
	v_mfma_f32_16x16x32_bf16 v[8:11], v[232:235], v[180:183], v[48:51]
	v_mfma_f32_16x16x32_bf16 v[48:51], v[236:239], v[196:199], v[8:11]
	v_mfma_f32_16x16x32_bf16 v[8:11], v[224:227], v[208:211], v[28:31]
	v_mfma_f32_16x16x32_bf16 v[28:31], v[228:231], v[212:215], v[8:11]
	v_mfma_f32_16x16x32_bf16 v[8:11], v[232:235], v[208:211], v[24:27]
	v_mfma_f32_16x16x32_bf16 v[4:7], v[224:227], v[216:219], v[4:7]
	v_mfma_f32_16x16x32_bf16 v[0:3], v[232:235], v[216:219], v[0:3]
	v_mfma_f32_16x16x32_bf16 v[24:27], v[236:239], v[212:215], v[8:11]
	v_mfma_f32_16x16x32_bf16 v[4:7], v[228:231], v[220:223], v[4:7]
	v_mfma_f32_16x16x32_bf16 v[0:3], v[236:239], v[220:223], v[0:3]
	s_setprio 0
	s_add_i32 s31, s31, 2
	s_add_u32 s34, s34, 0x100
	s_addc_u32 s35, s35, 0
	s_add_u32 s23, s23, 0x100
	s_addc_u32 s29, s29, 0
	s_cmp_gt_u32 s31, 29
	s_barrier
	s_cbranch_scc0 .LBB0_864
	v_readlane_b32 s0, v254, 32
	v_readlane_b32 s1, v254, 33
	s_load_dwordx2 s[0:1], s[0:1], 0x50
	v_lshl_or_b32 v154, s30, 8, v173
	v_lshl_add_u32 v156, s28, 8, v169
	v_ashrrev_i32_e32 v155, 31, v154
	v_ashrrev_i32_e32 v157, 31, v156
	s_waitcnt lgkmcnt(0)
	v_lshl_add_u64 v[12:13], v[154:155], 2, s[0:1]
	v_lshl_add_u64 v[158:159], v[156:157], 3, s[16:17]
	global_load_dwordx4 v[32:35], v[12:13], off offset:16
	global_load_dwordx4 v[36:39], v[12:13], off
	global_load_dwordx4 v[8:11], v[12:13], off offset:528
	s_nop 0
	global_load_dwordx4 v[12:15], v[12:13], off offset:512
	s_cmp_gt_i32 s30, 7
	global_load_dwordx2 v[166:167], v[158:159], off
	global_load_dwordx2 v[208:209], v[158:159], off offset:128
	global_load_dwordx2 v[210:211], v[158:159], off offset:256
	global_load_dwordx2 v[212:213], v[158:159], off offset:384
	global_load_dwordx2 v[214:215], v[158:159], off offset:1024
	global_load_dwordx2 v[216:217], v[158:159], off offset:1152
	global_load_dwordx2 v[218:219], v[158:159], off offset:1280
	global_load_dwordx2 v[220:221], v[158:159], off offset:1408
	s_mov_b32 s30, 0xbf38aa3b
	s_cselect_b64 s[0:1], -1, 0
	s_and_b64 s[28:29], s[8:9], s[0:1]
	s_mov_b32 s0, 0xbe11a98e
	s_mov_b32 s4, 0x3e027906
	s_waitcnt vmcnt(0)
	v_cvt_f64_u32_e32 v[170:171], v167
	v_ldexp_f64 v[170:171], v[170:171], 32
	v_cvt_f64_u32_e32 v[166:167], v166
	v_add_f64 v[166:167], v[170:171], v[166:167]
	v_ldexp_f64 v[166:167], v[166:167], s93
	v_cvt_f32_f64_e32 v166, v[166:167]
	v_fmamk_f32 v166, v166, 0x3a000000, v189
	v_cmp_gt_f32_e32 vcc, s78, v166
	v_mul_f32_e32 v167, 0x4b800000, v166
	s_nop 0
	v_cndmask_b32_e32 v166, v166, v167, vcc
	v_rsq_f32_e32 v166, v166
	s_nop 0
	v_mul_f32_e32 v167, 0x45800000, v166
	v_cndmask_b32_e32 v168, v166, v167, vcc
	v_pk_fma_f32 v[170:171], v[140:141], v[168:169], v[36:37] op_sel_hi:[1,0,1]
	v_pk_fma_f32 v[140:141], v[136:137], v[168:169], v[32:33] op_sel_hi:[1,0,1]
	v_and_b32_e32 v137, 0x7fffffff, v171
	v_and_b32_e32 v136, 0x7fffffff, v170
	v_pk_fma_f32 v[136:137], v[136:137], s[64:65], 1.0 op_sel_hi:[1,0,0]
	v_pk_mul_f32 v[180:181], v[170:171], v[170:171]
	v_rcp_f32_e32 v176, v136
	v_rcp_f32_e32 v177, v137
	v_mov_b64_e32 v[136:137], s[80:81]
	v_pk_mul_f32 v[180:181], v[180:181], s[30:31] op_sel_hi:[1,0]
	v_cmp_gt_f32_e32 vcc, 0, v170
	v_pk_fma_f32 v[178:179], v[176:177], s[74:75], v[136:137] op_sel_hi:[1,0,0]
	v_exp_f32_e32 v180, v180
	v_pk_fma_f32 v[178:179], v[176:177], v[178:179], s[86:87] op_sel_hi:[1,1,0]
	v_exp_f32_e32 v181, v181
	v_pk_fma_f32 v[178:179], v[176:177], v[178:179], s[0:1] op_sel_hi:[1,1,0]
	v_pk_fma_f32 v[142:143], v[142:143], v[168:169], v[38:39] op_sel_hi:[1,0,1]
	v_pk_fma_f32 v[178:179], v[176:177], v[178:179], s[4:5] op_sel_hi:[1,1,0]
	v_pk_fma_f32 v[138:139], v[138:139], v[168:169], v[34:35] op_sel_hi:[1,0,1]
	v_pk_mul_f32 v[176:177], v[176:177], v[178:179]
	v_pk_mul_f32 v[178:179], v[142:143], v[142:143]
; __device__ __forceinline__ unsigned cvt_pk_bf16(float lo, float hi) { unsigned r; asm volatile("v_cvt_pk_bf16_f32 %0, %1, %2" : "=v"(r) : "v"(lo), "v"(hi)); return r; }
;     __device__ __forceinline__ void operator()(const f32x4 (&acc)[2][2][4][2], const Unit& u, int wr, int wc, int fr, int fq) const {
;     ...
;                 for (int bj = 0; bj < 2; ++bj) {
;                     const f32x4 v0 = acc[ai][bj][m][0] * r + bv[bj][0], v1 = acc[ai][bj][m][1] * r + bv[bj][1];
;                     const f32x2 a = gelu_pk((f32x2){v0[0], v0[1]}), b = gelu_pk((f32x2){v0[2], v0[3]}), c = gelu_pk((f32x2){v1[0], v1[1]}), d = gelu_pk((f32x2){v1[2], v1[3]});
;                     ss += a.x * a.x + a.y * a.y + b.x * b.x + b.y * b.y + c.x * c.x + c.y * c.y + d.x * d.x + d.y * d.y;
;                     u32x4 w; w.x = cvt_pk_bf16(a.x, a.y); w.y = cvt_pk_bf16(b.x, b.y); w.z = cvt_pk_bf16(c.x, c.y); w.w = cvt_pk_bf16(d.x, d.y);
;                     *(u32x4*)(rowp + bj * HALF) = w;
	v_pk_mul_f32 v[176:177], v[180:181], v[176:177]
	v_pk_mul_f32 v[178:179], v[178:179], s[30:31] op_sel_hi:[1,0]
	v_pk_mul_f32 v[180:181], v[170:171], v[176:177]
	v_pk_fma_f32 v[176:177], v[170:171], v[176:177], v[170:171] neg_lo:[1,0,0] neg_hi:[1,0,0]
	v_exp_f32_e32 v178, v178
	v_cndmask_b32_e32 v170, v176, v180, vcc
	v_cmp_gt_f32_e32 vcc, 0, v171
	v_and_b32_e32 v176, 0x7fffffff, v142
	v_exp_f32_e32 v179, v179
	v_cndmask_b32_e32 v171, v177, v181, vcc
	v_and_b32_e32 v177, 0x7fffffff, v143
	v_pk_fma_f32 v[176:177], v[176:177], s[64:65], 1.0 op_sel_hi:[1,0,0]
	v_cmp_gt_f32_e32 vcc, 0, v142
	v_rcp_f32_e32 v176, v176
	v_rcp_f32_e32 v177, v177
	v_lshlrev_b64 v[166:167], 13, v[156:157]
	v_lshl_add_u64 v[166:167], s[14:15], 0, v[166:167]
	v_lshl_add_u64 v[166:167], v[154:155], 1, v[166:167]
	v_pk_fma_f32 v[180:181], v[176:177], s[74:75], v[136:137] op_sel_hi:[1,0,0]
	v_pk_fma_f32 v[132:133], v[132:133], v[168:169], v[12:13] op_sel_hi:[1,0,1]
	v_pk_fma_f32 v[180:181], v[176:177], v[180:181], s[86:87] op_sel_hi:[1,1,0]
	v_pk_fma_f32 v[134:135], v[134:135], v[168:169], v[14:15] op_sel_hi:[1,0,1]
	v_pk_fma_f32 v[180:181], v[176:177], v[180:181], s[0:1] op_sel_hi:[1,1,0]
	v_pk_fma_f32 v[128:129], v[128:129], v[168:169], v[8:9] op_sel_hi:[1,0,1]
	v_pk_fma_f32 v[180:181], v[176:177], v[180:181], s[4:5] op_sel_hi:[1,1,0]
	v_pk_fma_f32 v[130:131], v[130:131], v[168:169], v[10:11] op_sel_hi:[1,0,1]
	v_pk_mul_f32 v[176:177], v[176:177], v[180:181]
	s_nop 0
	v_pk_mul_f32 v[176:177], v[178:179], v[176:177]
	s_nop 0
	v_pk_mul_f32 v[178:179], v[142:143], v[176:177]
	v_pk_fma_f32 v[176:177], v[142:143], v[176:177], v[142:143] neg_lo:[1,0,0] neg_hi:[1,0,0]
	v_and_b32_e32 v142, 0x7fffffff, v140
	v_cndmask_b32_e32 v175, v176, v178, vcc
	v_cmp_gt_f32_e32 vcc, 0, v143
	v_and_b32_e32 v143, 0x7fffffff, v141
	v_pk_fma_f32 v[142:143], v[142:143], s[64:65], 1.0 op_sel_hi:[1,0,0]
	v_cndmask_b32_e32 v180, v177, v179, vcc
	v_rcp_f32_e32 v142, v142
	v_rcp_f32_e32 v143, v143
	v_pk_mul_f32 v[178:179], v[140:141], v[140:141]
	v_cmp_gt_f32_e32 vcc, 0, v140
	v_pk_mul_f32 v[178:179], v[178:179], s[30:31] op_sel_hi:[1,0]
	v_pk_fma_f32 v[176:177], v[142:143], s[74:75], v[136:137] op_sel_hi:[1,0,0]
	v_exp_f32_e32 v178, v178
	v_pk_fma_f32 v[176:177], v[142:143], v[176:177], s[86:87] op_sel_hi:[1,1,0]
	v_exp_f32_e32 v179, v179
	v_pk_fma_f32 v[176:177], v[142:143], v[176:177], s[0:1] op_sel_hi:[1,1,0]
	s_nop 0
	v_pk_fma_f32 v[176:177], v[142:143], v[176:177], s[4:5] op_sel_hi:[1,1,0]
	s_nop 0
	v_pk_mul_f32 v[142:143], v[142:143], v[176:177]
	v_pk_mul_f32 v[176:177], v[138:139], v[138:139]
	v_pk_mul_f32 v[142:143], v[178:179], v[142:143]
	s_nop 0
	v_pk_mul_f32 v[178:179], v[140:141], v[142:143]
	v_pk_fma_f32 v[142:143], v[140:141], v[142:143], v[140:141] neg_lo:[1,0,0] neg_hi:[1,0,0]
	v_and_b32_e32 v140, 0x7fffffff, v138
	v_cndmask_b32_e32 v178, v142, v178, vcc
	v_cmp_gt_f32_e32 vcc, 0, v141
	v_and_b32_e32 v141, 0x7fffffff, v139
	v_pk_fma_f32 v[140:141], v[140:141], s[64:65], 1.0 op_sel_hi:[1,0,0]
	v_cndmask_b32_e32 v179, v143, v179, vcc
	v_rcp_f32_e32 v140, v140
	v_rcp_f32_e32 v141, v141
	v_cmp_gt_f32_e32 vcc, 0, v138
	v_pk_fma_f32 v[142:143], v[140:141], s[74:75], v[136:137] op_sel_hi:[1,0,0]
	s_nop 0
	v_pk_fma_f32 v[142:143], v[140:141], v[142:143], s[86:87] op_sel_hi:[1,1,0]
	s_nop 0
	v_pk_fma_f32 v[142:143], v[140:141], v[142:143], s[0:1] op_sel_hi:[1,1,0]
	s_nop 0
	v_pk_fma_f32 v[142:143], v[140:141], v[142:143], s[4:5] op_sel_hi:[1,1,0]
	s_nop 0
	v_pk_mul_f32 v[140:141], v[140:141], v[142:143]
	v_pk_mul_f32 v[142:143], v[176:177], s[30:31] op_sel_hi:[1,0]
	v_mul_f32_e32 v176, v171, v171
	v_exp_f32_e32 v142, v142
	v_exp_f32_e32 v143, v143
	v_fmac_f32_e32 v176, v170, v170
	v_fmac_f32_e32 v176, v175, v175
	v_fmac_f32_e32 v176, v180, v180
	v_pk_mul_f32 v[140:141], v[142:143], v[140:141]
	v_fmac_f32_e32 v176, v178, v178
	v_pk_mul_f32 v[142:143], v[138:139], v[140:141]
	v_pk_fma_f32 v[140:141], v[138:139], v[140:141], v[138:139] neg_lo:[1,0,0] neg_hi:[1,0,0]
	v_fmac_f32_e32 v176, v179, v179
	v_cndmask_b32_e32 v142, v140, v142, vcc
	v_cmp_gt_f32_e32 vcc, 0, v139
	v_fmac_f32_e32 v176, v142, v142
	v_cvt_pk_bf16_f32 v138, v170, v171
	v_cvt_pk_bf16_f32 v139, v175, v180
	v_cvt_pk_bf16_f32 v140, v178, v179
	s_nop 0
	v_cndmask_b32_e32 v141, v141, v143, vcc
	v_fmac_f32_e32 v176, v141, v141
	v_cvt_pk_bf16_f32 v141, v142, v141
	global_store_dwordx4 v[166:167], v[138:141], off
	v_pk_mul_f32 v[142:143], v[132:133], v[132:133]
	v_cmp_gt_f32_e32 vcc, 0, v132
	v_and_b32_e32 v139, 0x7fffffff, v133
	v_and_b32_e32 v138, 0x7fffffff, v132
	v_pk_fma_f32 v[138:139], v[138:139], s[64:65], 1.0 op_sel_hi:[1,0,0]
	v_pk_mul_f32 v[142:143], v[142:143], s[30:31] op_sel_hi:[1,0]
	v_rcp_f32_e32 v138, v138
	v_rcp_f32_e32 v139, v139
	v_exp_f32_e32 v142, v142
	v_exp_f32_e32 v143, v143
	v_pk_fma_f32 v[140:141], v[138:139], s[74:75], v[136:137] op_sel_hi:[1,0,0]
	s_nop 0
	v_pk_fma_f32 v[140:141], v[138:139], v[140:141], s[86:87] op_sel_hi:[1,1,0]
	s_nop 0
	v_pk_fma_f32 v[140:141], v[138:139], v[140:141], s[0:1] op_sel_hi:[1,1,0]
	s_nop 0
	v_pk_fma_f32 v[140:141], v[138:139], v[140:141], s[4:5] op_sel_hi:[1,1,0]
	s_nop 0
	v_pk_mul_f32 v[138:139], v[138:139], v[140:141]
	v_pk_mul_f32 v[140:141], v[134:135], v[134:135]
	v_pk_mul_f32 v[138:139], v[142:143], v[138:139]
	s_nop 0
	v_pk_mul_f32 v[142:143], v[132:133], v[138:139]
	v_pk_fma_f32 v[138:139], v[132:133], v[138:139], v[132:133] neg_lo:[1,0,0] neg_hi:[1,0,0]
	v_and_b32_e32 v132, 0x7fffffff, v134
	v_cndmask_b32_e32 v142, v138, v142, vcc
	v_cmp_gt_f32_e32 vcc, 0, v133
	v_and_b32_e32 v133, 0x7fffffff, v135
	v_pk_fma_f32 v[132:133], v[132:133], s[64:65], 1.0 op_sel_hi:[1,0,0]
; __device__ __forceinline__ unsigned cvt_pk_bf16(float lo, float hi) { unsigned r; asm volatile("v_cvt_pk_bf16_f32 %0, %1, %2" : "=v"(r) : "v"(lo), "v"(hi)); return r; }
; __device__ __forceinline__ void stat_add(stat_t* p, float ss) { __hip_atomic_fetch_add(p, (stat_t)((double)ss * 4294967296.0), __ATOMIC_RELAXED, __HIP_MEMORY_SCOPE_AGENT); }
;     __device__ __forceinline__ void operator()(const f32x4 (&acc)[2][2][4][2], const Unit& u, int wr, int wc, int fr, int fq) const {
;     ...
;                 for (int bj = 0; bj < 2; ++bj) {
;                     const f32x4 v0 = acc[ai][bj][m][0] * r + bv[bj][0], v1 = acc[ai][bj][m][1] * r + bv[bj][1];
;                     const f32x2 a = gelu_pk((f32x2){v0[0], v0[1]}), b = gelu_pk((f32x2){v0[2], v0[3]}), c = gelu_pk((f32x2){v1[0], v1[1]}), d = gelu_pk((f32x2){v1[2], v1[3]});
;                     ss += a.x * a.x + a.y * a.y + b.x * b.x + b.y * b.y + c.x * c.x + c.y * c.y + d.x * d.x + d.y * d.y;
;                     u32x4 w; w.x = cvt_pk_bf16(a.x, a.y); w.y = cvt_pk_bf16(b.x, b.y); w.z = cvt_pk_bf16(c.x, c.y); w.w = cvt_pk_bf16(d.x, d.y);
;                     *(u32x4*)(rowp + bj * HALF) = w;
;                 }
;                 ss += __shfl_xor(ss, 16); ss += __shfl_xor(ss, 32);
;                 if (isv && fq == 0) stat_add(stats_v + row, ss);
	v_cndmask_b32_e32 v143, v139, v143, vcc
	v_rcp_f32_e32 v132, v132
	v_rcp_f32_e32 v133, v133
	v_cmp_gt_f32_e32 vcc, 0, v134
	v_pk_fma_f32 v[138:139], v[132:133], s[74:75], v[136:137] op_sel_hi:[1,0,0]
	s_nop 0
	v_pk_fma_f32 v[138:139], v[132:133], v[138:139], s[86:87] op_sel_hi:[1,1,0]
	s_nop 0
	v_pk_fma_f32 v[138:139], v[132:133], v[138:139], s[0:1] op_sel_hi:[1,1,0]
	s_nop 0
	v_pk_fma_f32 v[138:139], v[132:133], v[138:139], s[4:5] op_sel_hi:[1,1,0]
	s_nop 0
	v_pk_mul_f32 v[132:133], v[132:133], v[138:139]
	v_pk_mul_f32 v[138:139], v[140:141], s[30:31] op_sel_hi:[1,0]
	s_nop 0
	v_exp_f32_e32 v138, v138
	v_exp_f32_e32 v139, v139
	s_nop 0
	v_pk_mul_f32 v[132:133], v[138:139], v[132:133]
	s_nop 0
	v_pk_mul_f32 v[138:139], v[134:135], v[132:133]
	v_pk_fma_f32 v[132:133], v[134:135], v[132:133], v[134:135] neg_lo:[1,0,0] neg_hi:[1,0,0]
	s_nop 0
	v_cndmask_b32_e32 v140, v132, v138, vcc
	v_cmp_gt_f32_e32 vcc, 0, v135
	v_and_b32_e32 v132, 0x7fffffff, v128
	s_nop 0
	v_cndmask_b32_e32 v141, v133, v139, vcc
	v_and_b32_e32 v133, 0x7fffffff, v129
	v_pk_fma_f32 v[132:133], v[132:133], s[64:65], 1.0 op_sel_hi:[1,0,0]
	v_pk_mul_f32 v[138:139], v[128:129], v[128:129]
	v_rcp_f32_e32 v132, v132
	v_rcp_f32_e32 v133, v133
	v_pk_mul_f32 v[138:139], v[138:139], s[30:31] op_sel_hi:[1,0]
	v_cmp_gt_f32_e32 vcc, 0, v128
	v_exp_f32_e32 v138, v138
	v_pk_fma_f32 v[134:135], v[132:133], s[74:75], v[136:137] op_sel_hi:[1,0,0]
	v_exp_f32_e32 v139, v139
	v_pk_fma_f32 v[134:135], v[132:133], v[134:135], s[86:87] op_sel_hi:[1,1,0]
	s_nop 0
	v_pk_fma_f32 v[134:135], v[132:133], v[134:135], s[0:1] op_sel_hi:[1,1,0]
	s_nop 0
	v_pk_fma_f32 v[134:135], v[132:133], v[134:135], s[4:5] op_sel_hi:[1,1,0]
	s_nop 0
	v_pk_mul_f32 v[132:133], v[132:133], v[134:135]
	v_pk_mul_f32 v[134:135], v[130:131], v[130:131]
	v_pk_mul_f32 v[132:133], v[138:139], v[132:133]
	s_nop 0
	v_pk_mul_f32 v[138:139], v[128:129], v[132:133]
	v_pk_fma_f32 v[132:133], v[128:129], v[132:133], v[128:129] neg_lo:[1,0,0] neg_hi:[1,0,0]
	v_and_b32_e32 v128, 0x7fffffff, v130
	v_cndmask_b32_e32 v138, v132, v138, vcc
	v_cmp_gt_f32_e32 vcc, 0, v129
	v_and_b32_e32 v129, 0x7fffffff, v131
	v_pk_fma_f32 v[128:129], v[128:129], s[64:65], 1.0 op_sel_hi:[1,0,0]
	v_cndmask_b32_e32 v139, v133, v139, vcc
	v_rcp_f32_e32 v128, v128
	v_rcp_f32_e32 v129, v129
	v_cmp_gt_f32_e32 vcc, 0, v130
	v_pk_fma_f32 v[132:133], v[128:129], s[74:75], v[136:137] op_sel_hi:[1,0,0]
	s_nop 0
	v_pk_fma_f32 v[132:133], v[128:129], v[132:133], s[86:87] op_sel_hi:[1,1,0]
	s_nop 0
	v_pk_fma_f32 v[132:133], v[128:129], v[132:133], s[0:1] op_sel_hi:[1,1,0]
	s_nop 0
	v_pk_fma_f32 v[132:133], v[128:129], v[132:133], s[4:5] op_sel_hi:[1,1,0]
	s_nop 0
	v_pk_mul_f32 v[128:129], v[128:129], v[132:133]
	v_pk_mul_f32 v[132:133], v[134:135], s[30:31] op_sel_hi:[1,0]
	s_nop 0
	v_exp_f32_e32 v132, v132
	v_exp_f32_e32 v133, v133
	s_nop 0
	v_pk_mul_f32 v[128:129], v[132:133], v[128:129]
	s_nop 0
	v_pk_mul_f32 v[132:133], v[130:131], v[128:129]
	v_pk_fma_f32 v[128:129], v[130:131], v[128:129], v[130:131] neg_lo:[1,0,0] neg_hi:[1,0,0]
	s_nop 0
	v_cndmask_b32_e32 v132, v128, v132, vcc
	v_mul_f32_e32 v128, v143, v143
	v_fmac_f32_e32 v128, v142, v142
	v_fmac_f32_e32 v128, v140, v140
	v_fmac_f32_e32 v128, v141, v141
	v_fmac_f32_e32 v128, v138, v138
	v_cmp_gt_f32_e32 vcc, 0, v131
	v_fmac_f32_e32 v128, v139, v139
	v_fmac_f32_e32 v128, v132, v132
	v_cndmask_b32_e32 v131, v129, v133, vcc
	v_fmac_f32_e32 v128, v131, v131
	v_add_f32_e32 v134, v176, v128
	v_cvt_pk_bf16_f32 v128, v142, v143
	v_cvt_pk_bf16_f32 v129, v140, v141
	v_cvt_pk_bf16_f32 v130, v138, v139
	v_cvt_pk_bf16_f32 v131, v132, v131
	global_store_dwordx4 v[166:167], v[128:131], off offset:256
	s_nop 1
	v_and_b32_e32 v129, 64, v190
	v_xor_b32_e32 v128, 16, v190
	v_add_u32_e32 v129, 64, v129
	v_cmp_lt_i32_e32 vcc, v128, v129
	v_xor_b32_e32 v130, 32, v190
	s_nop 0
	v_cndmask_b32_e32 v128, v190, v128, vcc
	v_lshlrev_b32_e32 v133, 2, v128
	ds_bpermute_b32 v128, v133, v134
	v_cmp_lt_i32_e32 vcc, v130, v129
	s_waitcnt lgkmcnt(0)
	v_add_f32_e32 v128, v134, v128
	v_cndmask_b32_e32 v129, v190, v130, vcc
	v_lshlrev_b32_e32 v134, 2, v129
	ds_bpermute_b32 v129, v134, v128
	s_and_saveexec_b64 s[30:31], s[28:29]
	s_cbranch_execz .LBB0_867
	s_waitcnt lgkmcnt(0)
	v_add_f32_e32 v128, v128, v129
	v_cvt_f64_f32_e32 v[128:129], v128
	v_ldexp_f64 v[128:129], v[128:129], 32
	v_trunc_f64_e32 v[128:129], v[128:129]
	v_ldexp_f64 v[136:137], v[128:129], s93
	v_floor_f64_e32 v[136:137], v[136:137]
	v_fmac_f64_e32 v[128:129], 0xc1f00000, v[136:137]
	v_lshl_add_u64 v[130:131], v[156:157], 3, s[18:19]
	v_cvt_u32_f64_e32 v128, v[128:129]
	v_cvt_u32_f64_e32 v129, v[136:137]
	global_atomic_add_x2 v[130:131], v[128:129], off
; __device__ __forceinline__ float rinv_st(stat_t s, float invn) { return rsqrtf((float)((double)s * (1.0 / 4294967296.0)) * invn + 1e-6f); }
;     __device__ __forceinline__ void operator()(const f32x4 (&acc)[2][2][4][2], const Unit& u, int wr, int wc, int fr, int fq) const {
;     ...
;             for (int m = 0; m < 4; ++m) {
;                 const int row = row0 + ai * HALF + m * 16; const float r = rinv_st(stats[row], 1.0f / 2048.0f);
;                 bf16_t* rowp = uv + (size_t)row * 4096 + col0; float ss = 0.f;
; #pragma unroll
;                 for (int bj = 0; bj < 2; ++bj) {
;                     const f32x4 v0 = acc[ai][bj][m][0] * r + bv[bj][0], v1 = acc[ai][bj][m][1] * r + bv[bj][1];
;                     const f32x2 a = gelu_pk((f32x2){v0[0], v0[1]}), b = gelu_pk((f32x2){v0[2], v0[3]}), c = gelu_pk((f32x2){v1[0], v1[1]}), d = gelu_pk((f32x2){v1[2], v1[3]});
.LBB0_867:
	s_or_b64 exec, exec, s[30:31]
	v_or_b32_e32 v128, 16, v156
	s_waitcnt lgkmcnt(0)
	v_ashrrev_i32_e32 v129, 31, v128
	v_lshl_add_u64 v[130:131], v[128:129], 3, s[16:17]
	s_nop 1
	v_mov_b64_e32 v[130:131], v[208:209]
	s_mov_b32 s30, 0xbf38aa3b
	v_cvt_f64_u32_e32 v[136:137], v131
	v_ldexp_f64 v[136:137], v[136:137], 32
	v_cvt_f64_u32_e32 v[130:131], v130
	v_add_f64 v[130:131], v[136:137], v[130:131]
	v_ldexp_f64 v[130:131], v[130:131], s93
	v_cvt_f32_f64_e32 v130, v[130:131]
	v_fmamk_f32 v130, v130, 0x3a000000, v189
	v_cmp_gt_f32_e32 vcc, s78, v130
	v_mul_f32_e32 v131, 0x4b800000, v130
	s_nop 0
	v_cndmask_b32_e32 v130, v130, v131, vcc
	v_rsq_f32_e32 v130, v130
	s_nop 0
	v_mul_f32_e32 v131, 0x45800000, v130
	v_cndmask_b32_e32 v132, v130, v131, vcc
	v_pk_fma_f32 v[124:125], v[124:125], v[132:133], v[36:37] op_sel_hi:[1,0,1]
	v_pk_fma_f32 v[136:137], v[120:121], v[132:133], v[32:33] op_sel_hi:[1,0,1]
	v_and_b32_e32 v121, 0x7fffffff, v125
	v_and_b32_e32 v120, 0x7fffffff, v124
	v_pk_fma_f32 v[120:121], v[120:121], s[64:65], 1.0 op_sel_hi:[1,0,0]
	v_pk_mul_f32 v[142:143], v[124:125], v[124:125]
	v_rcp_f32_e32 v138, v120
	v_rcp_f32_e32 v139, v121
	v_mov_b64_e32 v[120:121], s[80:81]
	v_pk_mul_f32 v[142:143], v[142:143], s[30:31] op_sel_hi:[1,0]
	v_pk_fma_f32 v[126:127], v[126:127], v[132:133], v[38:39] op_sel_hi:[1,0,1]
	v_pk_fma_f32 v[140:141], v[138:139], s[74:75], v[120:121] op_sel_hi:[1,0,0]
	v_exp_f32_e32 v142, v142
	v_pk_fma_f32 v[140:141], v[138:139], v[140:141], s[86:87] op_sel_hi:[1,1,0]
	v_exp_f32_e32 v143, v143
	v_pk_fma_f32 v[140:141], v[138:139], v[140:141], s[0:1] op_sel_hi:[1,1,0]
	v_cmp_gt_f32_e32 vcc, 0, v124
	v_pk_fma_f32 v[140:141], v[138:139], v[140:141], s[4:5] op_sel_hi:[1,1,0]
	v_pk_fma_f32 v[122:123], v[122:123], v[132:133], v[34:35] op_sel_hi:[1,0,1]
	v_pk_mul_f32 v[138:139], v[138:139], v[140:141]
	v_pk_mul_f32 v[140:141], v[126:127], v[126:127]
	v_pk_mul_f32 v[138:139], v[142:143], v[138:139]
	v_lshlrev_b64 v[130:131], 13, v[128:129]
	v_pk_mul_f32 v[142:143], v[124:125], v[138:139]
	v_pk_fma_f32 v[138:139], v[124:125], v[138:139], v[124:125] neg_lo:[1,0,0] neg_hi:[1,0,0]
	v_and_b32_e32 v124, 0x7fffffff, v126
	v_cndmask_b32_e32 v135, v138, v142, vcc
	v_cmp_gt_f32_e32 vcc, 0, v125
	v_and_b32_e32 v125, 0x7fffffff, v127
	v_pk_fma_f32 v[124:125], v[124:125], s[64:65], 1.0 op_sel_hi:[1,0,0]
	v_cndmask_b32_e32 v142, v139, v143, vcc
	v_rcp_f32_e32 v124, v124
	v_rcp_f32_e32 v125, v125
	v_cmp_gt_f32_e32 vcc, 0, v126
	v_lshl_add_u64 v[130:131], s[14:15], 0, v[130:131]
	v_lshl_add_u64 v[130:131], v[154:155], 1, v[130:131]
	v_pk_fma_f32 v[138:139], v[124:125], s[74:75], v[120:121] op_sel_hi:[1,0,0]
	v_pk_fma_f32 v[116:117], v[116:117], v[132:133], v[12:13] op_sel_hi:[1,0,1]
	v_pk_fma_f32 v[138:139], v[124:125], v[138:139], s[86:87] op_sel_hi:[1,1,0]
	v_pk_fma_f32 v[118:119], v[118:119], v[132:133], v[14:15] op_sel_hi:[1,0,1]
	v_pk_fma_f32 v[138:139], v[124:125], v[138:139], s[0:1] op_sel_hi:[1,1,0]
	v_pk_fma_f32 v[114:115], v[114:115], v[132:133], v[10:11] op_sel_hi:[1,0,1]
	v_pk_fma_f32 v[138:139], v[124:125], v[138:139], s[4:5] op_sel_hi:[1,1,0]
	v_pk_fma_f32 v[112:113], v[112:113], v[132:133], v[8:9] op_sel_hi:[1,0,1]
	v_pk_mul_f32 v[124:125], v[124:125], v[138:139]
	v_pk_mul_f32 v[138:139], v[140:141], s[30:31] op_sel_hi:[1,0]
	s_nop 0
	v_exp_f32_e32 v138, v138
	v_exp_f32_e32 v139, v139
	s_nop 0
	v_pk_mul_f32 v[124:125], v[138:139], v[124:125]
	s_nop 0
	v_pk_mul_f32 v[138:139], v[126:127], v[124:125]
	v_pk_fma_f32 v[124:125], v[126:127], v[124:125], v[126:127] neg_lo:[1,0,0] neg_hi:[1,0,0]
	s_nop 0
	v_cndmask_b32_e32 v140, v124, v138, vcc
	v_cmp_gt_f32_e32 vcc, 0, v127
	v_and_b32_e32 v124, 0x7fffffff, v136
	s_nop 0
	v_cndmask_b32_e32 v141, v125, v139, vcc
	v_and_b32_e32 v125, 0x7fffffff, v137
	v_pk_fma_f32 v[124:125], v[124:125], s[64:65], 1.0 op_sel_hi:[1,0,0]
	v_pk_mul_f32 v[138:139], v[136:137], v[136:137]
	v_rcp_f32_e32 v124, v124
	v_rcp_f32_e32 v125, v125
	v_pk_mul_f32 v[138:139], v[138:139], s[30:31] op_sel_hi:[1,0]
	v_cmp_gt_f32_e32 vcc, 0, v136
	v_exp_f32_e32 v138, v138
	v_pk_fma_f32 v[126:127], v[124:125], s[74:75], v[120:121] op_sel_hi:[1,0,0]
	v_exp_f32_e32 v139, v139
	v_pk_fma_f32 v[126:127], v[124:125], v[126:127], s[86:87] op_sel_hi:[1,1,0]
	s_nop 0
	v_pk_fma_f32 v[126:127], v[124:125], v[126:127], s[0:1] op_sel_hi:[1,1,0]
	s_nop 0
	v_pk_fma_f32 v[126:127], v[124:125], v[126:127], s[4:5] op_sel_hi:[1,1,0]
	s_nop 0
	v_pk_mul_f32 v[124:125], v[124:125], v[126:127]
	v_pk_mul_f32 v[126:127], v[122:123], v[122:123]
	v_pk_mul_f32 v[124:125], v[138:139], v[124:125]
	v_pk_mul_f32 v[126:127], v[126:127], s[30:31] op_sel_hi:[1,0]
	v_pk_mul_f32 v[138:139], v[136:137], v[124:125]
	v_pk_fma_f32 v[124:125], v[136:137], v[124:125], v[136:137] neg_lo:[1,0,0] neg_hi:[1,0,0]
	v_exp_f32_e32 v126, v126
	v_cndmask_b32_e32 v138, v124, v138, vcc
	v_cmp_gt_f32_e32 vcc, 0, v137
	v_and_b32_e32 v124, 0x7fffffff, v122
	v_exp_f32_e32 v127, v127
	v_cndmask_b32_e32 v139, v125, v139, vcc
	v_and_b32_e32 v125, 0x7fffffff, v123
	v_pk_fma_f32 v[124:125], v[124:125], s[64:65], 1.0 op_sel_hi:[1,0,0]
	v_cmp_gt_f32_e32 vcc, 0, v122
	v_rcp_f32_e32 v124, v124
	v_rcp_f32_e32 v125, v125
	s_nop 0
	v_pk_fma_f32 v[136:137], v[124:125], s[74:75], v[120:121] op_sel_hi:[1,0,0]
	s_nop 0
	v_pk_fma_f32 v[136:137], v[124:125], v[136:137], s[86:87] op_sel_hi:[1,1,0]
	s_nop 0
	v_pk_fma_f32 v[136:137], v[124:125], v[136:137], s[0:1] op_sel_hi:[1,1,0]
	s_nop 0
	v_pk_fma_f32 v[136:137], v[124:125], v[136:137], s[4:5] op_sel_hi:[1,1,0]
	s_nop 0
	v_pk_mul_f32 v[124:125], v[124:125], v[136:137]
	s_nop 0
	v_pk_mul_f32 v[124:125], v[126:127], v[124:125]
	s_nop 0
; __device__ __forceinline__ unsigned cvt_pk_bf16(float lo, float hi) { unsigned r; asm volatile("v_cvt_pk_bf16_f32 %0, %1, %2" : "=v"(r) : "v"(lo), "v"(hi)); return r; }
; __device__ __forceinline__ void stat_add(stat_t* p, float ss) { __hip_atomic_fetch_add(p, (stat_t)((double)ss * 4294967296.0), __ATOMIC_RELAXED, __HIP_MEMORY_SCOPE_AGENT); }
;     __device__ __forceinline__ void operator()(const f32x4 (&acc)[2][2][4][2], const Unit& u, int wr, int wc, int fr, int fq) const {
;     ...
;                 for (int bj = 0; bj < 2; ++bj) {
;                     const f32x4 v0 = acc[ai][bj][m][0] * r + bv[bj][0], v1 = acc[ai][bj][m][1] * r + bv[bj][1];
;                     const f32x2 a = gelu_pk((f32x2){v0[0], v0[1]}), b = gelu_pk((f32x2){v0[2], v0[3]}), c = gelu_pk((f32x2){v1[0], v1[1]}), d = gelu_pk((f32x2){v1[2], v1[3]});
;                     ss += a.x * a.x + a.y * a.y + b.x * b.x + b.y * b.y + c.x * c.x + c.y * c.y + d.x * d.x + d.y * d.y;
;                     u32x4 w; w.x = cvt_pk_bf16(a.x, a.y); w.y = cvt_pk_bf16(b.x, b.y); w.z = cvt_pk_bf16(c.x, c.y); w.w = cvt_pk_bf16(d.x, d.y);
;                     *(u32x4*)(rowp + bj * HALF) = w;
;                 }
;                 ss += __shfl_xor(ss, 16); ss += __shfl_xor(ss, 32);
;                 if (isv && fq == 0) stat_add(stats_v + row, ss);
	v_pk_mul_f32 v[126:127], v[122:123], v[124:125]
	v_pk_fma_f32 v[124:125], v[122:123], v[124:125], v[122:123] neg_lo:[1,0,0] neg_hi:[1,0,0]
	v_mul_f32_e32 v122, v142, v142
	v_cndmask_b32_e32 v136, v124, v126, vcc
	v_cmp_gt_f32_e32 vcc, 0, v123
	v_cvt_pk_bf16_f32 v124, v135, v142
	v_fmac_f32_e32 v122, v135, v135
	v_fmac_f32_e32 v122, v140, v140
	v_cndmask_b32_e32 v123, v125, v127, vcc
	v_cvt_pk_bf16_f32 v125, v140, v141
	v_cvt_pk_bf16_f32 v126, v138, v139
	v_cvt_pk_bf16_f32 v127, v136, v123
	global_store_dwordx4 v[130:131], v[124:127], off
	v_fmac_f32_e32 v122, v141, v141
	v_fmac_f32_e32 v122, v138, v138
	v_and_b32_e32 v125, 0x7fffffff, v117
	v_and_b32_e32 v124, 0x7fffffff, v116
	v_pk_fma_f32 v[124:125], v[124:125], s[64:65], 1.0 op_sel_hi:[1,0,0]
	v_fmac_f32_e32 v122, v139, v139
	v_rcp_f32_e32 v124, v124
	v_rcp_f32_e32 v125, v125
	v_fmac_f32_e32 v122, v136, v136
	v_pk_mul_f32 v[136:137], v[116:117], v[116:117]
	v_cmp_gt_f32_e32 vcc, 0, v116
	v_pk_fma_f32 v[126:127], v[124:125], s[74:75], v[120:121] op_sel_hi:[1,0,0]
	v_pk_mul_f32 v[136:137], v[136:137], s[30:31] op_sel_hi:[1,0]
	v_pk_fma_f32 v[126:127], v[124:125], v[126:127], s[86:87] op_sel_hi:[1,1,0]
	v_exp_f32_e32 v136, v136
	v_exp_f32_e32 v137, v137
	v_pk_fma_f32 v[126:127], v[124:125], v[126:127], s[0:1] op_sel_hi:[1,1,0]
	v_fmac_f32_e32 v122, v123, v123
	v_pk_fma_f32 v[126:127], v[124:125], v[126:127], s[4:5] op_sel_hi:[1,1,0]
	s_nop 0
	v_pk_mul_f32 v[124:125], v[124:125], v[126:127]
	v_pk_mul_f32 v[126:127], v[118:119], v[118:119]
	v_pk_mul_f32 v[124:125], v[136:137], v[124:125]
	s_nop 0
	v_pk_mul_f32 v[136:137], v[116:117], v[124:125]
	v_pk_fma_f32 v[124:125], v[116:117], v[124:125], v[116:117] neg_lo:[1,0,0] neg_hi:[1,0,0]
	v_and_b32_e32 v116, 0x7fffffff, v118
	v_cndmask_b32_e32 v123, v124, v136, vcc
	v_cmp_gt_f32_e32 vcc, 0, v117
	v_and_b32_e32 v117, 0x7fffffff, v119
	v_pk_fma_f32 v[116:117], v[116:117], s[64:65], 1.0 op_sel_hi:[1,0,0]
	v_cndmask_b32_e32 v132, v125, v137, vcc
	v_rcp_f32_e32 v116, v116
	v_rcp_f32_e32 v117, v117
	v_cmp_gt_f32_e32 vcc, 0, v118
	v_pk_fma_f32 v[124:125], v[116:117], s[74:75], v[120:121] op_sel_hi:[1,0,0]
	s_nop 0
	v_pk_fma_f32 v[124:125], v[116:117], v[124:125], s[86:87] op_sel_hi:[1,1,0]
	s_nop 0
	v_pk_fma_f32 v[124:125], v[116:117], v[124:125], s[0:1] op_sel_hi:[1,1,0]
	s_nop 0
	v_pk_fma_f32 v[124:125], v[116:117], v[124:125], s[4:5] op_sel_hi:[1,1,0]
	s_nop 0
	v_pk_mul_f32 v[116:117], v[116:117], v[124:125]
	v_pk_mul_f32 v[124:125], v[126:127], s[30:31] op_sel_hi:[1,0]
	s_nop 0
	v_exp_f32_e32 v124, v124
	v_exp_f32_e32 v125, v125
	s_nop 0
	v_pk_mul_f32 v[116:117], v[124:125], v[116:117]
	s_nop 0
	v_pk_mul_f32 v[124:125], v[118:119], v[116:117]
	v_pk_fma_f32 v[116:117], v[118:119], v[116:117], v[118:119] neg_lo:[1,0,0] neg_hi:[1,0,0]
	s_nop 0
	v_cndmask_b32_e32 v126, v116, v124, vcc
	v_cmp_gt_f32_e32 vcc, 0, v119
	v_and_b32_e32 v116, 0x7fffffff, v112
	s_nop 0
	v_cndmask_b32_e32 v127, v117, v125, vcc
	v_and_b32_e32 v117, 0x7fffffff, v113
	v_pk_fma_f32 v[116:117], v[116:117], s[64:65], 1.0 op_sel_hi:[1,0,0]
	v_pk_mul_f32 v[124:125], v[112:113], v[112:113]
	v_rcp_f32_e32 v116, v116
	v_rcp_f32_e32 v117, v117
	v_pk_mul_f32 v[124:125], v[124:125], s[30:31] op_sel_hi:[1,0]
	v_cmp_gt_f32_e32 vcc, 0, v112
	v_exp_f32_e32 v124, v124
	v_pk_fma_f32 v[118:119], v[116:117], s[74:75], v[120:121] op_sel_hi:[1,0,0]
	v_exp_f32_e32 v125, v125
	v_pk_fma_f32 v[118:119], v[116:117], v[118:119], s[86:87] op_sel_hi:[1,1,0]
	s_nop 0
	v_pk_fma_f32 v[118:119], v[116:117], v[118:119], s[0:1] op_sel_hi:[1,1,0]
	s_nop 0
	v_pk_fma_f32 v[118:119], v[116:117], v[118:119], s[4:5] op_sel_hi:[1,1,0]
	s_nop 0
	v_pk_mul_f32 v[116:117], v[116:117], v[118:119]
	v_pk_mul_f32 v[118:119], v[114:115], v[114:115]
	v_pk_mul_f32 v[116:117], v[124:125], v[116:117]
	s_nop 0
	v_pk_mul_f32 v[124:125], v[112:113], v[116:117]
	v_pk_fma_f32 v[116:117], v[112:113], v[116:117], v[112:113] neg_lo:[1,0,0] neg_hi:[1,0,0]
	v_and_b32_e32 v112, 0x7fffffff, v114
	v_cndmask_b32_e32 v124, v116, v124, vcc
	v_cmp_gt_f32_e32 vcc, 0, v113
	v_and_b32_e32 v113, 0x7fffffff, v115
	v_pk_fma_f32 v[112:113], v[112:113], s[64:65], 1.0 op_sel_hi:[1,0,0]
	v_cndmask_b32_e32 v125, v117, v125, vcc
	v_rcp_f32_e32 v112, v112
	v_rcp_f32_e32 v113, v113
	v_cmp_gt_f32_e32 vcc, 0, v114
	v_pk_fma_f32 v[116:117], v[112:113], s[74:75], v[120:121] op_sel_hi:[1,0,0]
	s_nop 0
	v_pk_fma_f32 v[116:117], v[112:113], v[116:117], s[86:87] op_sel_hi:[1,1,0]
	s_nop 0
	v_pk_fma_f32 v[116:117], v[112:113], v[116:117], s[0:1] op_sel_hi:[1,1,0]
	s_nop 0
	v_pk_fma_f32 v[116:117], v[112:113], v[116:117], s[4:5] op_sel_hi:[1,1,0]
	s_nop 0
	v_pk_mul_f32 v[112:113], v[112:113], v[116:117]
	v_pk_mul_f32 v[116:117], v[118:119], s[30:31] op_sel_hi:[1,0]
	s_nop 0
	v_exp_f32_e32 v116, v116
	v_exp_f32_e32 v117, v117
	s_nop 0
	v_pk_mul_f32 v[112:113], v[116:117], v[112:113]
	s_nop 0
	v_pk_mul_f32 v[116:117], v[114:115], v[112:113]
	v_pk_fma_f32 v[112:113], v[114:115], v[112:113], v[114:115] neg_lo:[1,0,0] neg_hi:[1,0,0]
	s_nop 0
	v_cndmask_b32_e32 v116, v112, v116, vcc
	v_mul_f32_e32 v112, v132, v132
	v_fmac_f32_e32 v112, v123, v123
	v_fmac_f32_e32 v112, v126, v126
	v_fmac_f32_e32 v112, v127, v127
	v_fmac_f32_e32 v112, v124, v124
	v_cmp_gt_f32_e32 vcc, 0, v115
	v_fmac_f32_e32 v112, v125, v125
	v_fmac_f32_e32 v112, v116, v116
	v_cndmask_b32_e32 v115, v113, v117, vcc
	v_fmac_f32_e32 v112, v115, v115
	v_add_f32_e32 v117, v122, v112
	v_cvt_pk_bf16_f32 v112, v123, v132
	v_cvt_pk_bf16_f32 v113, v126, v127
	v_cvt_pk_bf16_f32 v114, v124, v125
	v_cvt_pk_bf16_f32 v115, v116, v115
	global_store_dwordx4 v[130:131], v[112:115], off offset:256
	ds_bpermute_b32 v112, v133, v117
	s_waitcnt lgkmcnt(0)
	v_add_f32_e32 v112, v117, v112
	ds_bpermute_b32 v113, v134, v112
	s_and_saveexec_b64 s[30:31], s[28:29]
	s_cbranch_execz .LBB0_869
	s_waitcnt lgkmcnt(0)
	v_add_f32_e32 v112, v112, v113
	v_cvt_f64_f32_e32 v[112:113], v112
	v_ldexp_f64 v[112:113], v[112:113], 32
	v_trunc_f64_e32 v[112:113], v[112:113]
	v_ldexp_f64 v[116:117], v[112:113], s93
	v_floor_f64_e32 v[116:117], v[116:117]
	v_fmac_f64_e32 v[112:113], 0xc1f00000, v[116:117]
	v_lshl_add_u64 v[114:115], v[128:129], 3, s[18:19]
	v_cvt_u32_f64_e32 v112, v[112:113]
	v_cvt_u32_f64_e32 v113, v[116:117]
	global_atomic_add_x2 v[114:115], v[112:113], off
; __device__ __forceinline__ float rinv_st(stat_t s, float invn) { return rsqrtf((float)((double)s * (1.0 / 4294967296.0)) * invn + 1e-6f); }
;     __device__ __forceinline__ void operator()(const f32x4 (&acc)[2][2][4][2], const Unit& u, int wr, int wc, int fr, int fq) const {
;     ...
;             for (int m = 0; m < 4; ++m) {
;                 const int row = row0 + ai * HALF + m * 16; const float r = rinv_st(stats[row], 1.0f / 2048.0f);
;                 bf16_t* rowp = uv + (size_t)row * 4096 + col0; float ss = 0.f;
; #pragma unroll
;                 for (int bj = 0; bj < 2; ++bj) {
;                     const f32x4 v0 = acc[ai][bj][m][0] * r + bv[bj][0], v1 = acc[ai][bj][m][1] * r + bv[bj][1];
;                     const f32x2 a = gelu_pk((f32x2){v0[0], v0[1]}), b = gelu_pk((f32x2){v0[2], v0[3]}), c = gelu_pk((f32x2){v1[0], v1[1]}), d = gelu_pk((f32x2){v1[2], v1[3]});
.LBB0_869:
	s_or_b64 exec, exec, s[30:31]
	v_or_b32_e32 v112, 32, v156
	s_waitcnt lgkmcnt(0)
	v_ashrrev_i32_e32 v113, 31, v112
	v_lshl_add_u64 v[114:115], v[112:113], 3, s[16:17]
	s_nop 1
	v_mov_b64_e32 v[114:115], v[210:211]
	s_mov_b32 s30, 0xbf38aa3b
	v_cvt_f64_u32_e32 v[116:117], v115
	v_ldexp_f64 v[116:117], v[116:117], 32
	v_cvt_f64_u32_e32 v[114:115], v114
	v_add_f64 v[114:115], v[116:117], v[114:115]
	v_ldexp_f64 v[114:115], v[114:115], s93
	v_cvt_f32_f64_e32 v114, v[114:115]
	v_fmamk_f32 v114, v114, 0x3a000000, v189
	v_cmp_gt_f32_e32 vcc, s78, v114
	v_mul_f32_e32 v115, 0x4b800000, v114
	s_nop 0
	v_cndmask_b32_e32 v114, v114, v115, vcc
	v_rsq_f32_e32 v114, v114
	s_nop 0
	v_mul_f32_e32 v115, 0x45800000, v114
	v_cndmask_b32_e32 v116, v114, v115, vcc
	v_pk_fma_f32 v[108:109], v[108:109], v[116:117], v[36:37] op_sel_hi:[1,0,1]
	v_pk_fma_f32 v[118:119], v[104:105], v[116:117], v[32:33] op_sel_hi:[1,0,1]
	v_and_b32_e32 v105, 0x7fffffff, v109
	v_and_b32_e32 v104, 0x7fffffff, v108
	v_pk_fma_f32 v[104:105], v[104:105], s[64:65], 1.0 op_sel_hi:[1,0,0]
	v_pk_mul_f32 v[124:125], v[108:109], v[108:109]
	v_rcp_f32_e32 v120, v104
	v_rcp_f32_e32 v121, v105
	v_mov_b64_e32 v[104:105], s[80:81]
	v_pk_mul_f32 v[124:125], v[124:125], s[30:31] op_sel_hi:[1,0]
	v_pk_fma_f32 v[110:111], v[110:111], v[116:117], v[38:39] op_sel_hi:[1,0,1]
	v_pk_fma_f32 v[122:123], v[120:121], s[74:75], v[104:105] op_sel_hi:[1,0,0]
	v_exp_f32_e32 v124, v124
	v_pk_fma_f32 v[122:123], v[120:121], v[122:123], s[86:87] op_sel_hi:[1,1,0]
	v_exp_f32_e32 v125, v125
	v_pk_fma_f32 v[122:123], v[120:121], v[122:123], s[0:1] op_sel_hi:[1,1,0]
	v_cmp_gt_f32_e32 vcc, 0, v108
	v_pk_fma_f32 v[122:123], v[120:121], v[122:123], s[4:5] op_sel_hi:[1,1,0]
	v_pk_fma_f32 v[106:107], v[106:107], v[116:117], v[34:35] op_sel_hi:[1,0,1]
	v_pk_mul_f32 v[120:121], v[120:121], v[122:123]
	v_pk_mul_f32 v[122:123], v[110:111], v[110:111]
	v_pk_mul_f32 v[120:121], v[124:125], v[120:121]
	v_lshlrev_b64 v[114:115], 13, v[112:113]
	v_pk_mul_f32 v[124:125], v[108:109], v[120:121]
	v_pk_fma_f32 v[120:121], v[108:109], v[120:121], v[108:109] neg_lo:[1,0,0] neg_hi:[1,0,0]
	v_and_b32_e32 v108, 0x7fffffff, v110
	v_cndmask_b32_e32 v117, v120, v124, vcc
	v_cmp_gt_f32_e32 vcc, 0, v109
	v_and_b32_e32 v109, 0x7fffffff, v111
	v_pk_fma_f32 v[108:109], v[108:109], s[64:65], 1.0 op_sel_hi:[1,0,0]
	v_cndmask_b32_e32 v124, v121, v125, vcc
	v_rcp_f32_e32 v108, v108
	v_rcp_f32_e32 v109, v109
	v_cmp_gt_f32_e32 vcc, 0, v110
	v_lshl_add_u64 v[114:115], s[14:15], 0, v[114:115]
	v_lshl_add_u64 v[114:115], v[154:155], 1, v[114:115]
	v_pk_fma_f32 v[120:121], v[108:109], s[74:75], v[104:105] op_sel_hi:[1,0,0]
	v_pk_fma_f32 v[100:101], v[100:101], v[116:117], v[12:13] op_sel_hi:[1,0,1]
	v_pk_fma_f32 v[120:121], v[108:109], v[120:121], s[86:87] op_sel_hi:[1,1,0]
	v_pk_fma_f32 v[102:103], v[102:103], v[116:117], v[14:15] op_sel_hi:[1,0,1]
	v_pk_fma_f32 v[120:121], v[108:109], v[120:121], s[0:1] op_sel_hi:[1,1,0]
	v_pk_fma_f32 v[98:99], v[98:99], v[116:117], v[10:11] op_sel_hi:[1,0,1]
	v_pk_fma_f32 v[120:121], v[108:109], v[120:121], s[4:5] op_sel_hi:[1,1,0]
	v_pk_fma_f32 v[96:97], v[96:97], v[116:117], v[8:9] op_sel_hi:[1,0,1]
	v_pk_mul_f32 v[108:109], v[108:109], v[120:121]
	v_pk_mul_f32 v[120:121], v[122:123], s[30:31] op_sel_hi:[1,0]
	s_nop 0
	v_exp_f32_e32 v120, v120
	v_exp_f32_e32 v121, v121
	s_nop 0
	v_pk_mul_f32 v[108:109], v[120:121], v[108:109]
	s_nop 0
	v_pk_mul_f32 v[120:121], v[110:111], v[108:109]
	v_pk_fma_f32 v[108:109], v[110:111], v[108:109], v[110:111] neg_lo:[1,0,0] neg_hi:[1,0,0]
	s_nop 0
	v_cndmask_b32_e32 v122, v108, v120, vcc
	v_cmp_gt_f32_e32 vcc, 0, v111
	v_and_b32_e32 v108, 0x7fffffff, v118
	s_nop 0
	v_cndmask_b32_e32 v123, v109, v121, vcc
	v_and_b32_e32 v109, 0x7fffffff, v119
	v_pk_fma_f32 v[108:109], v[108:109], s[64:65], 1.0 op_sel_hi:[1,0,0]
	v_pk_mul_f32 v[120:121], v[118:119], v[118:119]
	v_rcp_f32_e32 v108, v108
	v_rcp_f32_e32 v109, v109
	v_pk_mul_f32 v[120:121], v[120:121], s[30:31] op_sel_hi:[1,0]
	v_cmp_gt_f32_e32 vcc, 0, v118
	v_exp_f32_e32 v120, v120
	v_pk_fma_f32 v[110:111], v[108:109], s[74:75], v[104:105] op_sel_hi:[1,0,0]
	v_exp_f32_e32 v121, v121
	v_pk_fma_f32 v[110:111], v[108:109], v[110:111], s[86:87] op_sel_hi:[1,1,0]
	s_nop 0
	v_pk_fma_f32 v[110:111], v[108:109], v[110:111], s[0:1] op_sel_hi:[1,1,0]
	s_nop 0
	v_pk_fma_f32 v[110:111], v[108:109], v[110:111], s[4:5] op_sel_hi:[1,1,0]
	s_nop 0
	v_pk_mul_f32 v[108:109], v[108:109], v[110:111]
	v_pk_mul_f32 v[110:111], v[106:107], v[106:107]
	v_pk_mul_f32 v[108:109], v[120:121], v[108:109]
	v_pk_mul_f32 v[110:111], v[110:111], s[30:31] op_sel_hi:[1,0]
	v_pk_mul_f32 v[120:121], v[118:119], v[108:109]
	v_pk_fma_f32 v[108:109], v[118:119], v[108:109], v[118:119] neg_lo:[1,0,0] neg_hi:[1,0,0]
	v_exp_f32_e32 v110, v110
	v_cndmask_b32_e32 v120, v108, v120, vcc
	v_cmp_gt_f32_e32 vcc, 0, v119
	v_and_b32_e32 v108, 0x7fffffff, v106
	v_exp_f32_e32 v111, v111
	v_cndmask_b32_e32 v121, v109, v121, vcc
	v_and_b32_e32 v109, 0x7fffffff, v107
	v_pk_fma_f32 v[108:109], v[108:109], s[64:65], 1.0 op_sel_hi:[1,0,0]
	v_cmp_gt_f32_e32 vcc, 0, v106
	v_rcp_f32_e32 v108, v108
	v_rcp_f32_e32 v109, v109
	s_nop 0
	v_pk_fma_f32 v[118:119], v[108:109], s[74:75], v[104:105] op_sel_hi:[1,0,0]
	s_nop 0
	v_pk_fma_f32 v[118:119], v[108:109], v[118:119], s[86:87] op_sel_hi:[1,1,0]
	s_nop 0
	v_pk_fma_f32 v[118:119], v[108:109], v[118:119], s[0:1] op_sel_hi:[1,1,0]
	s_nop 0
	v_pk_fma_f32 v[118:119], v[108:109], v[118:119], s[4:5] op_sel_hi:[1,1,0]
	s_nop 0
	v_pk_mul_f32 v[108:109], v[108:109], v[118:119]
	s_nop 0
	v_pk_mul_f32 v[108:109], v[110:111], v[108:109]
	s_nop 0
; __device__ __forceinline__ unsigned cvt_pk_bf16(float lo, float hi) { unsigned r; asm volatile("v_cvt_pk_bf16_f32 %0, %1, %2" : "=v"(r) : "v"(lo), "v"(hi)); return r; }
; __device__ __forceinline__ void stat_add(stat_t* p, float ss) { __hip_atomic_fetch_add(p, (stat_t)((double)ss * 4294967296.0), __ATOMIC_RELAXED, __HIP_MEMORY_SCOPE_AGENT); }
;     __device__ __forceinline__ void operator()(const f32x4 (&acc)[2][2][4][2], const Unit& u, int wr, int wc, int fr, int fq) const {
;     ...
;                 for (int bj = 0; bj < 2; ++bj) {
;                     const f32x4 v0 = acc[ai][bj][m][0] * r + bv[bj][0], v1 = acc[ai][bj][m][1] * r + bv[bj][1];
;                     const f32x2 a = gelu_pk((f32x2){v0[0], v0[1]}), b = gelu_pk((f32x2){v0[2], v0[3]}), c = gelu_pk((f32x2){v1[0], v1[1]}), d = gelu_pk((f32x2){v1[2], v1[3]});
;                     ss += a.x * a.x + a.y * a.y + b.x * b.x + b.y * b.y + c.x * c.x + c.y * c.y + d.x * d.x + d.y * d.y;
;                     u32x4 w; w.x = cvt_pk_bf16(a.x, a.y); w.y = cvt_pk_bf16(b.x, b.y); w.z = cvt_pk_bf16(c.x, c.y); w.w = cvt_pk_bf16(d.x, d.y);
;                     *(u32x4*)(rowp + bj * HALF) = w;
;                 }
;                 ss += __shfl_xor(ss, 16); ss += __shfl_xor(ss, 32);
;                 if (isv && fq == 0) stat_add(stats_v + row, ss);
	v_pk_mul_f32 v[110:111], v[106:107], v[108:109]
	v_pk_fma_f32 v[108:109], v[106:107], v[108:109], v[106:107] neg_lo:[1,0,0] neg_hi:[1,0,0]
	v_mul_f32_e32 v106, v124, v124
	v_cndmask_b32_e32 v118, v108, v110, vcc
	v_cmp_gt_f32_e32 vcc, 0, v107
	v_cvt_pk_bf16_f32 v108, v117, v124
	v_fmac_f32_e32 v106, v117, v117
	v_pk_mul_f32 v[116:117], v[100:101], v[100:101]
	v_cndmask_b32_e32 v107, v109, v111, vcc
	v_cvt_pk_bf16_f32 v109, v122, v123
	v_cvt_pk_bf16_f32 v110, v120, v121
	v_cvt_pk_bf16_f32 v111, v118, v107
	global_store_dwordx4 v[114:115], v[108:111], off
	v_pk_mul_f32 v[116:117], v[116:117], s[30:31] op_sel_hi:[1,0]
	v_fmac_f32_e32 v106, v122, v122
	v_and_b32_e32 v109, 0x7fffffff, v101
	v_and_b32_e32 v108, 0x7fffffff, v100
	v_pk_fma_f32 v[108:109], v[108:109], s[64:65], 1.0 op_sel_hi:[1,0,0]
	v_exp_f32_e32 v116, v116
	v_rcp_f32_e32 v108, v108
	v_rcp_f32_e32 v109, v109
	v_exp_f32_e32 v117, v117
	v_fmac_f32_e32 v106, v123, v123
	v_fmac_f32_e32 v106, v120, v120
	v_pk_fma_f32 v[110:111], v[108:109], s[74:75], v[104:105] op_sel_hi:[1,0,0]
	v_fmac_f32_e32 v106, v121, v121
	v_pk_fma_f32 v[110:111], v[108:109], v[110:111], s[86:87] op_sel_hi:[1,1,0]
	v_fmac_f32_e32 v106, v118, v118
	v_pk_fma_f32 v[110:111], v[108:109], v[110:111], s[0:1] op_sel_hi:[1,1,0]
	v_cmp_gt_f32_e32 vcc, 0, v100
	v_pk_fma_f32 v[110:111], v[108:109], v[110:111], s[4:5] op_sel_hi:[1,1,0]
	v_fmac_f32_e32 v106, v107, v107
	v_pk_mul_f32 v[108:109], v[108:109], v[110:111]
	v_pk_mul_f32 v[110:111], v[102:103], v[102:103]
	v_pk_mul_f32 v[108:109], v[116:117], v[108:109]
	s_nop 0
	v_pk_mul_f32 v[116:117], v[100:101], v[108:109]
	v_pk_fma_f32 v[108:109], v[100:101], v[108:109], v[100:101] neg_lo:[1,0,0] neg_hi:[1,0,0]
	v_and_b32_e32 v100, 0x7fffffff, v102
	v_cndmask_b32_e32 v107, v108, v116, vcc
	v_cmp_gt_f32_e32 vcc, 0, v101
	v_and_b32_e32 v101, 0x7fffffff, v103
	v_pk_fma_f32 v[100:101], v[100:101], s[64:65], 1.0 op_sel_hi:[1,0,0]
	v_cndmask_b32_e32 v116, v109, v117, vcc
	v_rcp_f32_e32 v100, v100
	v_rcp_f32_e32 v101, v101
	v_cmp_gt_f32_e32 vcc, 0, v102
	v_pk_fma_f32 v[108:109], v[100:101], s[74:75], v[104:105] op_sel_hi:[1,0,0]
	s_nop 0
	v_pk_fma_f32 v[108:109], v[100:101], v[108:109], s[86:87] op_sel_hi:[1,1,0]
	s_nop 0
	v_pk_fma_f32 v[108:109], v[100:101], v[108:109], s[0:1] op_sel_hi:[1,1,0]
	s_nop 0
	v_pk_fma_f32 v[108:109], v[100:101], v[108:109], s[4:5] op_sel_hi:[1,1,0]
	s_nop 0
	v_pk_mul_f32 v[100:101], v[100:101], v[108:109]
	v_pk_mul_f32 v[108:109], v[110:111], s[30:31] op_sel_hi:[1,0]
	s_nop 0
	v_exp_f32_e32 v108, v108
	v_exp_f32_e32 v109, v109
	s_nop 0
	v_pk_mul_f32 v[100:101], v[108:109], v[100:101]
	s_nop 0
	v_pk_mul_f32 v[108:109], v[102:103], v[100:101]
	v_pk_fma_f32 v[100:101], v[102:103], v[100:101], v[102:103] neg_lo:[1,0,0] neg_hi:[1,0,0]
	s_nop 0
	v_cndmask_b32_e32 v110, v100, v108, vcc
	v_cmp_gt_f32_e32 vcc, 0, v103
	v_and_b32_e32 v100, 0x7fffffff, v96
	s_nop 0
	v_cndmask_b32_e32 v111, v101, v109, vcc
	v_and_b32_e32 v101, 0x7fffffff, v97
	v_pk_fma_f32 v[100:101], v[100:101], s[64:65], 1.0 op_sel_hi:[1,0,0]
	v_pk_mul_f32 v[108:109], v[96:97], v[96:97]
	v_rcp_f32_e32 v100, v100
	v_rcp_f32_e32 v101, v101
	v_pk_mul_f32 v[108:109], v[108:109], s[30:31] op_sel_hi:[1,0]
	v_cmp_gt_f32_e32 vcc, 0, v96
	v_exp_f32_e32 v108, v108
	v_pk_fma_f32 v[102:103], v[100:101], s[74:75], v[104:105] op_sel_hi:[1,0,0]
	v_exp_f32_e32 v109, v109
	v_pk_fma_f32 v[102:103], v[100:101], v[102:103], s[86:87] op_sel_hi:[1,1,0]
	s_nop 0
	v_pk_fma_f32 v[102:103], v[100:101], v[102:103], s[0:1] op_sel_hi:[1,1,0]
	s_nop 0
	v_pk_fma_f32 v[102:103], v[100:101], v[102:103], s[4:5] op_sel_hi:[1,1,0]
	s_nop 0
	v_pk_mul_f32 v[100:101], v[100:101], v[102:103]
	v_pk_mul_f32 v[102:103], v[98:99], v[98:99]
	v_pk_mul_f32 v[100:101], v[108:109], v[100:101]
	s_nop 0
	v_pk_mul_f32 v[108:109], v[96:97], v[100:101]
	v_pk_fma_f32 v[100:101], v[96:97], v[100:101], v[96:97] neg_lo:[1,0,0] neg_hi:[1,0,0]
	v_and_b32_e32 v96, 0x7fffffff, v98
	v_cndmask_b32_e32 v108, v100, v108, vcc
	v_cmp_gt_f32_e32 vcc, 0, v97
	v_and_b32_e32 v97, 0x7fffffff, v99
	v_pk_fma_f32 v[96:97], v[96:97], s[64:65], 1.0 op_sel_hi:[1,0,0]
	v_cndmask_b32_e32 v109, v101, v109, vcc
	v_rcp_f32_e32 v96, v96
	v_rcp_f32_e32 v97, v97
	v_cmp_gt_f32_e32 vcc, 0, v98
	v_pk_fma_f32 v[100:101], v[96:97], s[74:75], v[104:105] op_sel_hi:[1,0,0]
	s_nop 0
	v_pk_fma_f32 v[100:101], v[96:97], v[100:101], s[86:87] op_sel_hi:[1,1,0]
	s_nop 0
	v_pk_fma_f32 v[100:101], v[96:97], v[100:101], s[0:1] op_sel_hi:[1,1,0]
	s_nop 0
	v_pk_fma_f32 v[100:101], v[96:97], v[100:101], s[4:5] op_sel_hi:[1,1,0]
	s_nop 0
	v_pk_mul_f32 v[96:97], v[96:97], v[100:101]
	v_pk_mul_f32 v[100:101], v[102:103], s[30:31] op_sel_hi:[1,0]
	s_nop 0
	v_exp_f32_e32 v100, v100
	v_exp_f32_e32 v101, v101
	s_nop 0
	v_pk_mul_f32 v[96:97], v[100:101], v[96:97]
	s_nop 0
	v_pk_mul_f32 v[100:101], v[98:99], v[96:97]
	v_pk_fma_f32 v[96:97], v[98:99], v[96:97], v[98:99] neg_lo:[1,0,0] neg_hi:[1,0,0]
	s_nop 0
	v_cndmask_b32_e32 v100, v96, v100, vcc
	v_mul_f32_e32 v96, v116, v116
	v_fmac_f32_e32 v96, v107, v107
	v_fmac_f32_e32 v96, v110, v110
	v_fmac_f32_e32 v96, v111, v111
	v_fmac_f32_e32 v96, v108, v108
	v_cmp_gt_f32_e32 vcc, 0, v99
	v_fmac_f32_e32 v96, v109, v109
	v_fmac_f32_e32 v96, v100, v100
	v_cndmask_b32_e32 v99, v97, v101, vcc
	v_fmac_f32_e32 v96, v99, v99
	v_add_f32_e32 v101, v106, v96
	v_cvt_pk_bf16_f32 v96, v107, v116
	v_cvt_pk_bf16_f32 v97, v110, v111
	v_cvt_pk_bf16_f32 v98, v108, v109
	v_cvt_pk_bf16_f32 v99, v100, v99
	global_store_dwordx4 v[114:115], v[96:99], off offset:256
	ds_bpermute_b32 v96, v133, v101
	s_waitcnt lgkmcnt(0)
	v_add_f32_e32 v96, v101, v96
	ds_bpermute_b32 v97, v134, v96
	s_and_saveexec_b64 s[30:31], s[28:29]
	s_cbranch_execz .LBB0_871
	s_waitcnt lgkmcnt(0)
	v_add_f32_e32 v96, v96, v97
	v_cvt_f64_f32_e32 v[96:97], v96
	v_ldexp_f64 v[96:97], v[96:97], 32
	v_trunc_f64_e32 v[96:97], v[96:97]
	v_ldexp_f64 v[100:101], v[96:97], s93
	v_floor_f64_e32 v[100:101], v[100:101]
	v_fmac_f64_e32 v[96:97], 0xc1f00000, v[100:101]
	v_lshl_add_u64 v[98:99], v[112:113], 3, s[18:19]
	v_cvt_u32_f64_e32 v96, v[96:97]
	v_cvt_u32_f64_e32 v97, v[100:101]
	global_atomic_add_x2 v[98:99], v[96:97], off
; __device__ __forceinline__ float rinv_st(stat_t s, float invn) { return rsqrtf((float)((double)s * (1.0 / 4294967296.0)) * invn + 1e-6f); }
;     __device__ __forceinline__ void operator()(const f32x4 (&acc)[2][2][4][2], const Unit& u, int wr, int wc, int fr, int fq) const {
;     ...
;             for (int m = 0; m < 4; ++m) {
;                 const int row = row0 + ai * HALF + m * 16; const float r = rinv_st(stats[row], 1.0f / 2048.0f);
;                 bf16_t* rowp = uv + (size_t)row * 4096 + col0; float ss = 0.f;
; #pragma unroll
;                 for (int bj = 0; bj < 2; ++bj) {
;                     const f32x4 v0 = acc[ai][bj][m][0] * r + bv[bj][0], v1 = acc[ai][bj][m][1] * r + bv[bj][1];
;                     const f32x2 a = gelu_pk((f32x2){v0[0], v0[1]}), b = gelu_pk((f32x2){v0[2], v0[3]}), c = gelu_pk((f32x2){v1[0], v1[1]}), d = gelu_pk((f32x2){v1[2], v1[3]});
.LBB0_871:
	s_or_b64 exec, exec, s[30:31]
	v_or_b32_e32 v96, 48, v156
	s_waitcnt lgkmcnt(0)
	v_ashrrev_i32_e32 v97, 31, v96
	v_lshl_add_u64 v[98:99], v[96:97], 3, s[16:17]
	s_nop 1
	v_mov_b64_e32 v[98:99], v[212:213]
	s_mov_b32 s30, 0xbf38aa3b
	v_cvt_f64_u32_e32 v[100:101], v99
	v_ldexp_f64 v[100:101], v[100:101], 32
	v_cvt_f64_u32_e32 v[98:99], v98
	v_add_f64 v[98:99], v[100:101], v[98:99]
	v_ldexp_f64 v[98:99], v[98:99], s93
	v_cvt_f32_f64_e32 v98, v[98:99]
	v_fmamk_f32 v98, v98, 0x3a000000, v189
	v_cmp_gt_f32_e32 vcc, s78, v98
	v_mul_f32_e32 v99, 0x4b800000, v98
	s_nop 0
	v_cndmask_b32_e32 v98, v98, v99, vcc
	v_rsq_f32_e32 v98, v98
	s_nop 0
	v_mul_f32_e32 v99, 0x45800000, v98
	v_cndmask_b32_e32 v100, v98, v99, vcc
	v_pk_fma_f32 v[92:93], v[92:93], v[100:101], v[36:37] op_sel_hi:[1,0,1]
	v_pk_fma_f32 v[102:103], v[88:89], v[100:101], v[32:33] op_sel_hi:[1,0,1]
	v_and_b32_e32 v89, 0x7fffffff, v93
	v_and_b32_e32 v88, 0x7fffffff, v92
	v_pk_fma_f32 v[88:89], v[88:89], s[64:65], 1.0 op_sel_hi:[1,0,0]
	v_pk_mul_f32 v[108:109], v[92:93], v[92:93]
	v_rcp_f32_e32 v104, v88
	v_rcp_f32_e32 v105, v89
	v_mov_b64_e32 v[88:89], s[80:81]
	v_pk_mul_f32 v[108:109], v[108:109], s[30:31] op_sel_hi:[1,0]
	v_pk_fma_f32 v[94:95], v[94:95], v[100:101], v[38:39] op_sel_hi:[1,0,1]
	v_pk_fma_f32 v[106:107], v[104:105], s[74:75], v[88:89] op_sel_hi:[1,0,0]
	v_exp_f32_e32 v108, v108
	v_pk_fma_f32 v[106:107], v[104:105], v[106:107], s[86:87] op_sel_hi:[1,1,0]
	v_exp_f32_e32 v109, v109
	v_pk_fma_f32 v[106:107], v[104:105], v[106:107], s[0:1] op_sel_hi:[1,1,0]
	v_cmp_gt_f32_e32 vcc, 0, v92
	v_pk_fma_f32 v[106:107], v[104:105], v[106:107], s[4:5] op_sel_hi:[1,1,0]
	v_pk_fma_f32 v[90:91], v[90:91], v[100:101], v[34:35] op_sel_hi:[1,0,1]
	v_pk_mul_f32 v[104:105], v[104:105], v[106:107]
	v_pk_mul_f32 v[106:107], v[94:95], v[94:95]
	v_pk_mul_f32 v[104:105], v[108:109], v[104:105]
	v_lshlrev_b64 v[98:99], 13, v[96:97]
	v_pk_mul_f32 v[108:109], v[92:93], v[104:105]
	v_pk_fma_f32 v[104:105], v[92:93], v[104:105], v[92:93] neg_lo:[1,0,0] neg_hi:[1,0,0]
	v_and_b32_e32 v92, 0x7fffffff, v94
	v_cndmask_b32_e32 v101, v104, v108, vcc
	v_cmp_gt_f32_e32 vcc, 0, v93
	v_and_b32_e32 v93, 0x7fffffff, v95
	v_pk_fma_f32 v[92:93], v[92:93], s[64:65], 1.0 op_sel_hi:[1,0,0]
	v_cndmask_b32_e32 v108, v105, v109, vcc
	v_rcp_f32_e32 v92, v92
	v_rcp_f32_e32 v93, v93
	v_cmp_gt_f32_e32 vcc, 0, v94
	v_lshl_add_u64 v[98:99], s[14:15], 0, v[98:99]
	v_lshl_add_u64 v[98:99], v[154:155], 1, v[98:99]
	v_pk_fma_f32 v[104:105], v[92:93], s[74:75], v[88:89] op_sel_hi:[1,0,0]
	v_pk_fma_f32 v[84:85], v[84:85], v[100:101], v[12:13] op_sel_hi:[1,0,1]
	v_pk_fma_f32 v[104:105], v[92:93], v[104:105], s[86:87] op_sel_hi:[1,1,0]
	v_pk_fma_f32 v[86:87], v[86:87], v[100:101], v[14:15] op_sel_hi:[1,0,1]
	v_pk_fma_f32 v[104:105], v[92:93], v[104:105], s[0:1] op_sel_hi:[1,1,0]
	v_pk_fma_f32 v[82:83], v[82:83], v[100:101], v[10:11] op_sel_hi:[1,0,1]
	v_pk_fma_f32 v[104:105], v[92:93], v[104:105], s[4:5] op_sel_hi:[1,1,0]
	v_pk_fma_f32 v[80:81], v[80:81], v[100:101], v[8:9] op_sel_hi:[1,0,1]
	v_pk_mul_f32 v[92:93], v[92:93], v[104:105]
	v_pk_mul_f32 v[104:105], v[106:107], s[30:31] op_sel_hi:[1,0]
	s_nop 0
	v_exp_f32_e32 v104, v104
	v_exp_f32_e32 v105, v105
	s_nop 0
	v_pk_mul_f32 v[92:93], v[104:105], v[92:93]
	s_nop 0
	v_pk_mul_f32 v[104:105], v[94:95], v[92:93]
	v_pk_fma_f32 v[92:93], v[94:95], v[92:93], v[94:95] neg_lo:[1,0,0] neg_hi:[1,0,0]
	s_nop 0
	v_cndmask_b32_e32 v106, v92, v104, vcc
	v_cmp_gt_f32_e32 vcc, 0, v95
	v_and_b32_e32 v92, 0x7fffffff, v102
	s_nop 0
	v_cndmask_b32_e32 v107, v93, v105, vcc
	v_and_b32_e32 v93, 0x7fffffff, v103
	v_pk_fma_f32 v[92:93], v[92:93], s[64:65], 1.0 op_sel_hi:[1,0,0]
	v_pk_mul_f32 v[104:105], v[102:103], v[102:103]
	v_rcp_f32_e32 v92, v92
	v_rcp_f32_e32 v93, v93
	v_pk_mul_f32 v[104:105], v[104:105], s[30:31] op_sel_hi:[1,0]
	v_cmp_gt_f32_e32 vcc, 0, v102
	v_exp_f32_e32 v104, v104
	v_pk_fma_f32 v[94:95], v[92:93], s[74:75], v[88:89] op_sel_hi:[1,0,0]
	v_exp_f32_e32 v105, v105
	v_pk_fma_f32 v[94:95], v[92:93], v[94:95], s[86:87] op_sel_hi:[1,1,0]
	s_nop 0
	v_pk_fma_f32 v[94:95], v[92:93], v[94:95], s[0:1] op_sel_hi:[1,1,0]
	s_nop 0
	v_pk_fma_f32 v[94:95], v[92:93], v[94:95], s[4:5] op_sel_hi:[1,1,0]
	s_nop 0
	v_pk_mul_f32 v[92:93], v[92:93], v[94:95]
	v_pk_mul_f32 v[94:95], v[90:91], v[90:91]
	v_pk_mul_f32 v[92:93], v[104:105], v[92:93]
	v_pk_mul_f32 v[94:95], v[94:95], s[30:31] op_sel_hi:[1,0]
	v_pk_mul_f32 v[104:105], v[102:103], v[92:93]
	v_pk_fma_f32 v[92:93], v[102:103], v[92:93], v[102:103] neg_lo:[1,0,0] neg_hi:[1,0,0]
	v_exp_f32_e32 v94, v94
	v_cndmask_b32_e32 v104, v92, v104, vcc
	v_cmp_gt_f32_e32 vcc, 0, v103
	v_and_b32_e32 v92, 0x7fffffff, v90
	v_exp_f32_e32 v95, v95
	v_cndmask_b32_e32 v105, v93, v105, vcc
	v_and_b32_e32 v93, 0x7fffffff, v91
	v_pk_fma_f32 v[92:93], v[92:93], s[64:65], 1.0 op_sel_hi:[1,0,0]
	v_cmp_gt_f32_e32 vcc, 0, v90
	v_rcp_f32_e32 v92, v92
	v_rcp_f32_e32 v93, v93
	s_nop 0
	v_pk_fma_f32 v[102:103], v[92:93], s[74:75], v[88:89] op_sel_hi:[1,0,0]
	s_nop 0
	v_pk_fma_f32 v[102:103], v[92:93], v[102:103], s[86:87] op_sel_hi:[1,1,0]
	s_nop 0
	v_pk_fma_f32 v[102:103], v[92:93], v[102:103], s[0:1] op_sel_hi:[1,1,0]
	s_nop 0
	v_pk_fma_f32 v[102:103], v[92:93], v[102:103], s[4:5] op_sel_hi:[1,1,0]
	s_nop 0
	v_pk_mul_f32 v[92:93], v[92:93], v[102:103]
	s_nop 0
	v_pk_mul_f32 v[92:93], v[94:95], v[92:93]
	s_nop 0
	v_pk_mul_f32 v[94:95], v[90:91], v[92:93]
	v_pk_fma_f32 v[92:93], v[90:91], v[92:93], v[90:91] neg_lo:[1,0,0] neg_hi:[1,0,0]
	v_mul_f32_e32 v90, v108, v108
	v_cndmask_b32_e32 v102, v92, v94, vcc
	v_cmp_gt_f32_e32 vcc, 0, v91
	v_cvt_pk_bf16_f32 v92, v101, v108
; __device__ __forceinline__ unsigned cvt_pk_bf16(float lo, float hi) { unsigned r; asm volatile("v_cvt_pk_bf16_f32 %0, %1, %2" : "=v"(r) : "v"(lo), "v"(hi)); return r; }
; __device__ __forceinline__ void stat_add(stat_t* p, float ss) { __hip_atomic_fetch_add(p, (stat_t)((double)ss * 4294967296.0), __ATOMIC_RELAXED, __HIP_MEMORY_SCOPE_AGENT); }
;     __device__ __forceinline__ void operator()(const f32x4 (&acc)[2][2][4][2], const Unit& u, int wr, int wc, int fr, int fq) const {
;     ...
;                 for (int bj = 0; bj < 2; ++bj) {
;                     const f32x4 v0 = acc[ai][bj][m][0] * r + bv[bj][0], v1 = acc[ai][bj][m][1] * r + bv[bj][1];
;                     const f32x2 a = gelu_pk((f32x2){v0[0], v0[1]}), b = gelu_pk((f32x2){v0[2], v0[3]}), c = gelu_pk((f32x2){v1[0], v1[1]}), d = gelu_pk((f32x2){v1[2], v1[3]});
;                     ss += a.x * a.x + a.y * a.y + b.x * b.x + b.y * b.y + c.x * c.x + c.y * c.y + d.x * d.x + d.y * d.y;
;                     u32x4 w; w.x = cvt_pk_bf16(a.x, a.y); w.y = cvt_pk_bf16(b.x, b.y); w.z = cvt_pk_bf16(c.x, c.y); w.w = cvt_pk_bf16(d.x, d.y);
;                     *(u32x4*)(rowp + bj * HALF) = w;
;                 }
;                 ss += __shfl_xor(ss, 16); ss += __shfl_xor(ss, 32);
;                 if (isv && fq == 0) stat_add(stats_v + row, ss);
	v_fmac_f32_e32 v90, v101, v101
	v_pk_mul_f32 v[100:101], v[84:85], v[84:85]
	v_cndmask_b32_e32 v91, v93, v95, vcc
	v_cvt_pk_bf16_f32 v93, v106, v107
	v_cvt_pk_bf16_f32 v94, v104, v105
	v_cvt_pk_bf16_f32 v95, v102, v91
	global_store_dwordx4 v[98:99], v[92:95], off
	v_pk_mul_f32 v[100:101], v[100:101], s[30:31] op_sel_hi:[1,0]
	v_fmac_f32_e32 v90, v106, v106
	v_and_b32_e32 v93, 0x7fffffff, v85
	v_and_b32_e32 v92, 0x7fffffff, v84
	v_pk_fma_f32 v[92:93], v[92:93], s[64:65], 1.0 op_sel_hi:[1,0,0]
	v_exp_f32_e32 v100, v100
	v_rcp_f32_e32 v92, v92
	v_rcp_f32_e32 v93, v93
	v_exp_f32_e32 v101, v101
	v_fmac_f32_e32 v90, v107, v107
	v_fmac_f32_e32 v90, v104, v104
	v_pk_fma_f32 v[94:95], v[92:93], s[74:75], v[88:89] op_sel_hi:[1,0,0]
	v_fmac_f32_e32 v90, v105, v105
	v_pk_fma_f32 v[94:95], v[92:93], v[94:95], s[86:87] op_sel_hi:[1,1,0]
	v_fmac_f32_e32 v90, v102, v102
	v_pk_fma_f32 v[94:95], v[92:93], v[94:95], s[0:1] op_sel_hi:[1,1,0]
	v_cmp_gt_f32_e32 vcc, 0, v84
	v_pk_fma_f32 v[94:95], v[92:93], v[94:95], s[4:5] op_sel_hi:[1,1,0]
	v_fmac_f32_e32 v90, v91, v91
	v_pk_mul_f32 v[92:93], v[92:93], v[94:95]
	v_pk_mul_f32 v[94:95], v[86:87], v[86:87]
	v_pk_mul_f32 v[92:93], v[100:101], v[92:93]
	s_nop 0
	v_pk_mul_f32 v[100:101], v[84:85], v[92:93]
	v_pk_fma_f32 v[92:93], v[84:85], v[92:93], v[84:85] neg_lo:[1,0,0] neg_hi:[1,0,0]
	v_and_b32_e32 v84, 0x7fffffff, v86
	v_cndmask_b32_e32 v91, v92, v100, vcc
	v_cmp_gt_f32_e32 vcc, 0, v85
	v_and_b32_e32 v85, 0x7fffffff, v87
	v_pk_fma_f32 v[84:85], v[84:85], s[64:65], 1.0 op_sel_hi:[1,0,0]
	v_cndmask_b32_e32 v100, v93, v101, vcc
	v_rcp_f32_e32 v84, v84
	v_rcp_f32_e32 v85, v85
	v_cmp_gt_f32_e32 vcc, 0, v86
	v_pk_fma_f32 v[92:93], v[84:85], s[74:75], v[88:89] op_sel_hi:[1,0,0]
	s_nop 0
	v_pk_fma_f32 v[92:93], v[84:85], v[92:93], s[86:87] op_sel_hi:[1,1,0]
	s_nop 0
	v_pk_fma_f32 v[92:93], v[84:85], v[92:93], s[0:1] op_sel_hi:[1,1,0]
	s_nop 0
	v_pk_fma_f32 v[92:93], v[84:85], v[92:93], s[4:5] op_sel_hi:[1,1,0]
	s_nop 0
	v_pk_mul_f32 v[84:85], v[84:85], v[92:93]
	v_pk_mul_f32 v[92:93], v[94:95], s[30:31] op_sel_hi:[1,0]
	s_nop 0
	v_exp_f32_e32 v92, v92
	v_exp_f32_e32 v93, v93
	s_nop 0
	v_pk_mul_f32 v[84:85], v[92:93], v[84:85]
	s_nop 0
	v_pk_mul_f32 v[92:93], v[86:87], v[84:85]
	v_pk_fma_f32 v[84:85], v[86:87], v[84:85], v[86:87] neg_lo:[1,0,0] neg_hi:[1,0,0]
	s_nop 0
	v_cndmask_b32_e32 v94, v84, v92, vcc
	v_cmp_gt_f32_e32 vcc, 0, v87
	v_and_b32_e32 v84, 0x7fffffff, v80
	s_nop 0
	v_cndmask_b32_e32 v95, v85, v93, vcc
	v_and_b32_e32 v85, 0x7fffffff, v81
	v_pk_fma_f32 v[84:85], v[84:85], s[64:65], 1.0 op_sel_hi:[1,0,0]
	v_pk_mul_f32 v[92:93], v[80:81], v[80:81]
	v_rcp_f32_e32 v84, v84
	v_rcp_f32_e32 v85, v85
	v_pk_mul_f32 v[92:93], v[92:93], s[30:31] op_sel_hi:[1,0]
	v_cmp_gt_f32_e32 vcc, 0, v80
	v_exp_f32_e32 v92, v92
	v_pk_fma_f32 v[86:87], v[84:85], s[74:75], v[88:89] op_sel_hi:[1,0,0]
	v_exp_f32_e32 v93, v93
	v_pk_fma_f32 v[86:87], v[84:85], v[86:87], s[86:87] op_sel_hi:[1,1,0]
	s_nop 0
	v_pk_fma_f32 v[86:87], v[84:85], v[86:87], s[0:1] op_sel_hi:[1,1,0]
	s_nop 0
	v_pk_fma_f32 v[86:87], v[84:85], v[86:87], s[4:5] op_sel_hi:[1,1,0]
	s_nop 0
	v_pk_mul_f32 v[84:85], v[84:85], v[86:87]
	v_pk_mul_f32 v[86:87], v[82:83], v[82:83]
	v_pk_mul_f32 v[84:85], v[92:93], v[84:85]
	s_nop 0
	v_pk_mul_f32 v[92:93], v[80:81], v[84:85]
	v_pk_fma_f32 v[84:85], v[80:81], v[84:85], v[80:81] neg_lo:[1,0,0] neg_hi:[1,0,0]
	v_and_b32_e32 v80, 0x7fffffff, v82
	v_cndmask_b32_e32 v92, v84, v92, vcc
	v_cmp_gt_f32_e32 vcc, 0, v81
	v_and_b32_e32 v81, 0x7fffffff, v83
	v_pk_fma_f32 v[80:81], v[80:81], s[64:65], 1.0 op_sel_hi:[1,0,0]
	v_cndmask_b32_e32 v93, v85, v93, vcc
	v_rcp_f32_e32 v80, v80
	v_rcp_f32_e32 v81, v81
	v_cmp_gt_f32_e32 vcc, 0, v82
	v_pk_fma_f32 v[84:85], v[80:81], s[74:75], v[88:89] op_sel_hi:[1,0,0]
	s_nop 0
	v_pk_fma_f32 v[84:85], v[80:81], v[84:85], s[86:87] op_sel_hi:[1,1,0]
	s_nop 0
	v_pk_fma_f32 v[84:85], v[80:81], v[84:85], s[0:1] op_sel_hi:[1,1,0]
	s_nop 0
	v_pk_fma_f32 v[84:85], v[80:81], v[84:85], s[4:5] op_sel_hi:[1,1,0]
	s_nop 0
	v_pk_mul_f32 v[80:81], v[80:81], v[84:85]
	v_pk_mul_f32 v[84:85], v[86:87], s[30:31] op_sel_hi:[1,0]
	s_nop 0
	v_exp_f32_e32 v84, v84
	v_exp_f32_e32 v85, v85
	s_nop 0
	v_pk_mul_f32 v[80:81], v[84:85], v[80:81]
	s_nop 0
	v_pk_mul_f32 v[84:85], v[82:83], v[80:81]
	v_pk_fma_f32 v[80:81], v[82:83], v[80:81], v[82:83] neg_lo:[1,0,0] neg_hi:[1,0,0]
	s_nop 0
	v_cndmask_b32_e32 v84, v80, v84, vcc
	v_mul_f32_e32 v80, v100, v100
	v_fmac_f32_e32 v80, v91, v91
	v_fmac_f32_e32 v80, v94, v94
	v_fmac_f32_e32 v80, v95, v95
	v_fmac_f32_e32 v80, v92, v92
	v_cmp_gt_f32_e32 vcc, 0, v83
	v_fmac_f32_e32 v80, v93, v93
	v_fmac_f32_e32 v80, v84, v84
	v_cndmask_b32_e32 v83, v81, v85, vcc
	v_fmac_f32_e32 v80, v83, v83
	v_add_f32_e32 v85, v90, v80
	v_cvt_pk_bf16_f32 v80, v91, v100
	v_cvt_pk_bf16_f32 v81, v94, v95
	v_cvt_pk_bf16_f32 v82, v92, v93
	v_cvt_pk_bf16_f32 v83, v84, v83
	global_store_dwordx4 v[98:99], v[80:83], off offset:256
	ds_bpermute_b32 v80, v133, v85
	s_waitcnt lgkmcnt(0)
	v_add_f32_e32 v80, v85, v80
	ds_bpermute_b32 v81, v134, v80
	s_and_saveexec_b64 s[30:31], s[28:29]
	s_cbranch_execz .LBB0_873
	s_waitcnt lgkmcnt(0)
	v_add_f32_e32 v80, v80, v81
	v_cvt_f64_f32_e32 v[80:81], v80
	v_ldexp_f64 v[80:81], v[80:81], 32
	v_trunc_f64_e32 v[80:81], v[80:81]
	v_ldexp_f64 v[84:85], v[80:81], s93
	v_floor_f64_e32 v[84:85], v[84:85]
	v_fmac_f64_e32 v[80:81], 0xc1f00000, v[84:85]
	v_lshl_add_u64 v[82:83], v[96:97], 3, s[18:19]
	v_cvt_u32_f64_e32 v80, v[80:81]
	v_cvt_u32_f64_e32 v81, v[84:85]
	global_atomic_add_x2 v[82:83], v[80:81], off
; __device__ __forceinline__ float rinv_st(stat_t s, float invn) { return rsqrtf((float)((double)s * (1.0 / 4294967296.0)) * invn + 1e-6f); }
;     __device__ __forceinline__ void operator()(const f32x4 (&acc)[2][2][4][2], const Unit& u, int wr, int wc, int fr, int fq) const {
;     ...
;             for (int m = 0; m < 4; ++m) {
;                 const int row = row0 + ai * HALF + m * 16; const float r = rinv_st(stats[row], 1.0f / 2048.0f);
;                 bf16_t* rowp = uv + (size_t)row * 4096 + col0; float ss = 0.f;
; #pragma unroll
;                 for (int bj = 0; bj < 2; ++bj) {
;                     const f32x4 v0 = acc[ai][bj][m][0] * r + bv[bj][0], v1 = acc[ai][bj][m][1] * r + bv[bj][1];
;                     const f32x2 a = gelu_pk((f32x2){v0[0], v0[1]}), b = gelu_pk((f32x2){v0[2], v0[3]}), c = gelu_pk((f32x2){v1[0], v1[1]}), d = gelu_pk((f32x2){v1[2], v1[3]});
.LBB0_873:
	s_or_b64 exec, exec, s[30:31]
	s_nop 1
	v_mov_b64_e32 v[82:83], v[214:215]
	s_mov_b32 s30, 0xbf38aa3b
	v_add_u32_e32 v80, 0x80, v156
	s_waitcnt lgkmcnt(0)
	v_ashrrev_i32_e32 v81, 31, v80
	v_cvt_f64_u32_e32 v[84:85], v83
	v_ldexp_f64 v[84:85], v[84:85], 32
	v_cvt_f64_u32_e32 v[82:83], v82
	v_add_f64 v[82:83], v[84:85], v[82:83]
	v_ldexp_f64 v[82:83], v[82:83], s93
	v_cvt_f32_f64_e32 v82, v[82:83]
	v_fmamk_f32 v82, v82, 0x3a000000, v189
	v_cmp_gt_f32_e32 vcc, s78, v82
	v_mul_f32_e32 v83, 0x4b800000, v82
	s_nop 0
	v_cndmask_b32_e32 v82, v82, v83, vcc
	v_rsq_f32_e32 v82, v82
	s_nop 0
	v_mul_f32_e32 v83, 0x45800000, v82
	v_cndmask_b32_e32 v84, v82, v83, vcc
	v_pk_fma_f32 v[86:87], v[76:77], v[84:85], v[36:37] op_sel_hi:[1,0,1]
	v_pk_fma_f32 v[76:77], v[72:73], v[84:85], v[32:33] op_sel_hi:[1,0,1]
	v_and_b32_e32 v73, 0x7fffffff, v87
	v_and_b32_e32 v72, 0x7fffffff, v86
	v_pk_fma_f32 v[72:73], v[72:73], s[64:65], 1.0 op_sel_hi:[1,0,0]
	v_pk_mul_f32 v[92:93], v[86:87], v[86:87]
	v_rcp_f32_e32 v88, v72
	v_rcp_f32_e32 v89, v73
	v_mov_b64_e32 v[72:73], s[80:81]
	v_pk_mul_f32 v[92:93], v[92:93], s[30:31] op_sel_hi:[1,0]
	v_cmp_gt_f32_e32 vcc, 0, v86
	v_pk_fma_f32 v[90:91], v[88:89], s[74:75], v[72:73] op_sel_hi:[1,0,0]
	v_exp_f32_e32 v92, v92
	v_pk_fma_f32 v[90:91], v[88:89], v[90:91], s[86:87] op_sel_hi:[1,1,0]
	v_exp_f32_e32 v93, v93
	v_pk_fma_f32 v[90:91], v[88:89], v[90:91], s[0:1] op_sel_hi:[1,1,0]
	v_pk_fma_f32 v[78:79], v[78:79], v[84:85], v[38:39] op_sel_hi:[1,0,1]
	v_pk_fma_f32 v[90:91], v[88:89], v[90:91], s[4:5] op_sel_hi:[1,1,0]
	v_pk_fma_f32 v[74:75], v[74:75], v[84:85], v[34:35] op_sel_hi:[1,0,1]
	v_pk_mul_f32 v[88:89], v[88:89], v[90:91]
	v_pk_mul_f32 v[90:91], v[78:79], v[78:79]
	v_pk_mul_f32 v[88:89], v[92:93], v[88:89]
	v_pk_mul_f32 v[90:91], v[90:91], s[30:31] op_sel_hi:[1,0]
	v_pk_mul_f32 v[92:93], v[86:87], v[88:89]
	v_pk_fma_f32 v[88:89], v[86:87], v[88:89], v[86:87] neg_lo:[1,0,0] neg_hi:[1,0,0]
	v_exp_f32_e32 v90, v90
	v_cndmask_b32_e32 v85, v88, v92, vcc
	v_cmp_gt_f32_e32 vcc, 0, v87
	v_and_b32_e32 v88, 0x7fffffff, v78
	v_exp_f32_e32 v91, v91
	v_cndmask_b32_e32 v86, v89, v93, vcc
	v_and_b32_e32 v89, 0x7fffffff, v79
	v_pk_fma_f32 v[88:89], v[88:89], s[64:65], 1.0 op_sel_hi:[1,0,0]
	v_cmp_gt_f32_e32 vcc, 0, v78
	v_rcp_f32_e32 v88, v88
	v_rcp_f32_e32 v89, v89
	v_lshlrev_b64 v[82:83], 13, v[80:81]
	v_lshl_add_u64 v[82:83], s[14:15], 0, v[82:83]
	v_lshl_add_u64 v[82:83], v[154:155], 1, v[82:83]
	v_pk_fma_f32 v[92:93], v[88:89], s[74:75], v[72:73] op_sel_hi:[1,0,0]
	v_pk_fma_f32 v[68:69], v[68:69], v[84:85], v[12:13] op_sel_hi:[1,0,1]
	v_pk_fma_f32 v[92:93], v[88:89], v[92:93], s[86:87] op_sel_hi:[1,1,0]
	v_pk_fma_f32 v[70:71], v[70:71], v[84:85], v[14:15] op_sel_hi:[1,0,1]
	v_pk_fma_f32 v[92:93], v[88:89], v[92:93], s[0:1] op_sel_hi:[1,1,0]
	v_pk_fma_f32 v[64:65], v[64:65], v[84:85], v[8:9] op_sel_hi:[1,0,1]
	v_pk_fma_f32 v[92:93], v[88:89], v[92:93], s[4:5] op_sel_hi:[1,1,0]
	v_pk_fma_f32 v[66:67], v[66:67], v[84:85], v[10:11] op_sel_hi:[1,0,1]
	v_pk_mul_f32 v[88:89], v[88:89], v[92:93]
	v_pk_mul_f32 v[92:93], v[76:77], v[76:77]
	v_pk_mul_f32 v[88:89], v[90:91], v[88:89]
	v_pk_mul_f32 v[92:93], v[92:93], s[30:31] op_sel_hi:[1,0]
	v_pk_mul_f32 v[90:91], v[78:79], v[88:89]
	v_pk_fma_f32 v[88:89], v[78:79], v[88:89], v[78:79] neg_lo:[1,0,0] neg_hi:[1,0,0]
	v_exp_f32_e32 v92, v92
	v_cndmask_b32_e32 v78, v88, v90, vcc
	v_cmp_gt_f32_e32 vcc, 0, v79
	v_and_b32_e32 v88, 0x7fffffff, v76
	v_exp_f32_e32 v93, v93
	v_cndmask_b32_e32 v79, v89, v91, vcc
	v_and_b32_e32 v89, 0x7fffffff, v77
	v_pk_fma_f32 v[88:89], v[88:89], s[64:65], 1.0 op_sel_hi:[1,0,0]
	v_cmp_gt_f32_e32 vcc, 0, v76
	v_rcp_f32_e32 v88, v88
	v_rcp_f32_e32 v89, v89
	s_nop 0
	v_pk_fma_f32 v[90:91], v[88:89], s[74:75], v[72:73] op_sel_hi:[1,0,0]
	s_nop 0
	v_pk_fma_f32 v[90:91], v[88:89], v[90:91], s[86:87] op_sel_hi:[1,1,0]
	s_nop 0
	v_pk_fma_f32 v[90:91], v[88:89], v[90:91], s[0:1] op_sel_hi:[1,1,0]
	s_nop 0
	v_pk_fma_f32 v[90:91], v[88:89], v[90:91], s[4:5] op_sel_hi:[1,1,0]
	s_nop 0
	v_pk_mul_f32 v[88:89], v[88:89], v[90:91]
	v_pk_mul_f32 v[90:91], v[74:75], v[74:75]
	v_pk_mul_f32 v[88:89], v[92:93], v[88:89]
	s_nop 0
	v_pk_mul_f32 v[92:93], v[76:77], v[88:89]
	v_pk_fma_f32 v[88:89], v[76:77], v[88:89], v[76:77] neg_lo:[1,0,0] neg_hi:[1,0,0]
	v_and_b32_e32 v76, 0x7fffffff, v74
	v_cndmask_b32_e32 v87, v88, v92, vcc
	v_cmp_gt_f32_e32 vcc, 0, v77
	v_and_b32_e32 v77, 0x7fffffff, v75
	v_pk_fma_f32 v[76:77], v[76:77], s[64:65], 1.0 op_sel_hi:[1,0,0]
	v_cndmask_b32_e32 v92, v89, v93, vcc
	v_rcp_f32_e32 v76, v76
	v_rcp_f32_e32 v77, v77
	v_cmp_gt_f32_e32 vcc, 0, v74
	v_pk_fma_f32 v[88:89], v[76:77], s[74:75], v[72:73] op_sel_hi:[1,0,0]
	s_nop 0
	v_pk_fma_f32 v[88:89], v[76:77], v[88:89], s[86:87] op_sel_hi:[1,1,0]
	s_nop 0
	v_pk_fma_f32 v[88:89], v[76:77], v[88:89], s[0:1] op_sel_hi:[1,1,0]
	s_nop 0
	v_pk_fma_f32 v[88:89], v[76:77], v[88:89], s[4:5] op_sel_hi:[1,1,0]
	s_nop 0
	v_pk_mul_f32 v[76:77], v[76:77], v[88:89]
	v_pk_mul_f32 v[88:89], v[90:91], s[30:31] op_sel_hi:[1,0]
	s_nop 0
	v_exp_f32_e32 v88, v88
	v_exp_f32_e32 v89, v89
	s_nop 0
	v_pk_mul_f32 v[76:77], v[88:89], v[76:77]
	s_nop 0
	v_pk_mul_f32 v[88:89], v[74:75], v[76:77]
	v_pk_fma_f32 v[76:77], v[74:75], v[76:77], v[74:75] neg_lo:[1,0,0] neg_hi:[1,0,0]
	v_cvt_pk_bf16_f32 v74, v85, v86
	s_nop 0
	v_cndmask_b32_e32 v88, v76, v88, vcc
	v_cmp_gt_f32_e32 vcc, 0, v75
	v_cvt_pk_bf16_f32 v75, v78, v79
	v_cvt_pk_bf16_f32 v76, v87, v92
	s_nop 1
	v_cndmask_b32_e32 v77, v77, v89, vcc
	v_mul_f32_e32 v89, v86, v86
	v_fmac_f32_e32 v89, v85, v85
	v_fmac_f32_e32 v89, v78, v78
	v_fmac_f32_e32 v89, v79, v79
	v_fmac_f32_e32 v89, v87, v87
; __device__ __forceinline__ unsigned cvt_pk_bf16(float lo, float hi) { unsigned r; asm volatile("v_cvt_pk_bf16_f32 %0, %1, %2" : "=v"(r) : "v"(lo), "v"(hi)); return r; }
; __device__ __forceinline__ void stat_add(stat_t* p, float ss) { __hip_atomic_fetch_add(p, (stat_t)((double)ss * 4294967296.0), __ATOMIC_RELAXED, __HIP_MEMORY_SCOPE_AGENT); }
;     __device__ __forceinline__ void operator()(const f32x4 (&acc)[2][2][4][2], const Unit& u, int wr, int wc, int fr, int fq) const {
;     ...
;                 for (int bj = 0; bj < 2; ++bj) {
;                     const f32x4 v0 = acc[ai][bj][m][0] * r + bv[bj][0], v1 = acc[ai][bj][m][1] * r + bv[bj][1];
;                     const f32x2 a = gelu_pk((f32x2){v0[0], v0[1]}), b = gelu_pk((f32x2){v0[2], v0[3]}), c = gelu_pk((f32x2){v1[0], v1[1]}), d = gelu_pk((f32x2){v1[2], v1[3]});
;                     ss += a.x * a.x + a.y * a.y + b.x * b.x + b.y * b.y + c.x * c.x + c.y * c.y + d.x * d.x + d.y * d.y;
;                     u32x4 w; w.x = cvt_pk_bf16(a.x, a.y); w.y = cvt_pk_bf16(b.x, b.y); w.z = cvt_pk_bf16(c.x, c.y); w.w = cvt_pk_bf16(d.x, d.y);
;                     *(u32x4*)(rowp + bj * HALF) = w;
;                 }
;                 ss += __shfl_xor(ss, 16); ss += __shfl_xor(ss, 32);
;                 if (isv && fq == 0) stat_add(stats_v + row, ss);
	v_fmac_f32_e32 v89, v92, v92
	v_fmac_f32_e32 v89, v88, v88
	v_fmac_f32_e32 v89, v77, v77
	v_cvt_pk_bf16_f32 v77, v88, v77
	global_store_dwordx4 v[82:83], v[74:77], off
	v_pk_mul_f32 v[78:79], v[68:69], v[68:69]
	v_cmp_gt_f32_e32 vcc, 0, v68
	v_and_b32_e32 v75, 0x7fffffff, v69
	v_and_b32_e32 v74, 0x7fffffff, v68
	v_pk_fma_f32 v[74:75], v[74:75], s[64:65], 1.0 op_sel_hi:[1,0,0]
	v_pk_mul_f32 v[78:79], v[78:79], s[30:31] op_sel_hi:[1,0]
	v_rcp_f32_e32 v74, v74
	v_rcp_f32_e32 v75, v75
	v_exp_f32_e32 v78, v78
	v_exp_f32_e32 v79, v79
	v_pk_fma_f32 v[76:77], v[74:75], s[74:75], v[72:73] op_sel_hi:[1,0,0]
	s_nop 0
	v_pk_fma_f32 v[76:77], v[74:75], v[76:77], s[86:87] op_sel_hi:[1,1,0]
	s_nop 0
	v_pk_fma_f32 v[76:77], v[74:75], v[76:77], s[0:1] op_sel_hi:[1,1,0]
	s_nop 0
	v_pk_fma_f32 v[76:77], v[74:75], v[76:77], s[4:5] op_sel_hi:[1,1,0]
	s_nop 0
	v_pk_mul_f32 v[74:75], v[74:75], v[76:77]
	v_pk_mul_f32 v[76:77], v[70:71], v[70:71]
	v_pk_mul_f32 v[74:75], v[78:79], v[74:75]
	s_nop 0
	v_pk_mul_f32 v[78:79], v[68:69], v[74:75]
	v_pk_fma_f32 v[74:75], v[68:69], v[74:75], v[68:69] neg_lo:[1,0,0] neg_hi:[1,0,0]
	v_and_b32_e32 v68, 0x7fffffff, v70
	v_cndmask_b32_e32 v78, v74, v78, vcc
	v_cmp_gt_f32_e32 vcc, 0, v69
	v_and_b32_e32 v69, 0x7fffffff, v71
	v_pk_fma_f32 v[68:69], v[68:69], s[64:65], 1.0 op_sel_hi:[1,0,0]
	v_cndmask_b32_e32 v79, v75, v79, vcc
	v_rcp_f32_e32 v68, v68
	v_rcp_f32_e32 v69, v69
	v_cmp_gt_f32_e32 vcc, 0, v70
	v_pk_fma_f32 v[74:75], v[68:69], s[74:75], v[72:73] op_sel_hi:[1,0,0]
	s_nop 0
	v_pk_fma_f32 v[74:75], v[68:69], v[74:75], s[86:87] op_sel_hi:[1,1,0]
	s_nop 0
	v_pk_fma_f32 v[74:75], v[68:69], v[74:75], s[0:1] op_sel_hi:[1,1,0]
	s_nop 0
	v_pk_fma_f32 v[74:75], v[68:69], v[74:75], s[4:5] op_sel_hi:[1,1,0]
	s_nop 0
	v_pk_mul_f32 v[68:69], v[68:69], v[74:75]
	v_pk_mul_f32 v[74:75], v[76:77], s[30:31] op_sel_hi:[1,0]
	s_nop 0
	v_exp_f32_e32 v74, v74
	v_exp_f32_e32 v75, v75
	s_nop 0
	v_pk_mul_f32 v[68:69], v[74:75], v[68:69]
	s_nop 0
	v_pk_mul_f32 v[74:75], v[70:71], v[68:69]
	v_pk_fma_f32 v[68:69], v[70:71], v[68:69], v[70:71] neg_lo:[1,0,0] neg_hi:[1,0,0]
	s_nop 0
	v_cndmask_b32_e32 v76, v68, v74, vcc
	v_cmp_gt_f32_e32 vcc, 0, v71
	v_and_b32_e32 v68, 0x7fffffff, v64
	s_nop 0
	v_cndmask_b32_e32 v77, v69, v75, vcc
	v_and_b32_e32 v69, 0x7fffffff, v65
	v_pk_fma_f32 v[68:69], v[68:69], s[64:65], 1.0 op_sel_hi:[1,0,0]
	v_pk_mul_f32 v[74:75], v[64:65], v[64:65]
	v_rcp_f32_e32 v68, v68
	v_rcp_f32_e32 v69, v69
	v_pk_mul_f32 v[74:75], v[74:75], s[30:31] op_sel_hi:[1,0]
	v_cmp_gt_f32_e32 vcc, 0, v64
	v_exp_f32_e32 v74, v74
	v_pk_fma_f32 v[70:71], v[68:69], s[74:75], v[72:73] op_sel_hi:[1,0,0]
	v_exp_f32_e32 v75, v75
	v_pk_fma_f32 v[70:71], v[68:69], v[70:71], s[86:87] op_sel_hi:[1,1,0]
	s_nop 0
	v_pk_fma_f32 v[70:71], v[68:69], v[70:71], s[0:1] op_sel_hi:[1,1,0]
	s_nop 0
	v_pk_fma_f32 v[70:71], v[68:69], v[70:71], s[4:5] op_sel_hi:[1,1,0]
	s_nop 0
	v_pk_mul_f32 v[68:69], v[68:69], v[70:71]
	v_pk_mul_f32 v[70:71], v[66:67], v[66:67]
	v_pk_mul_f32 v[68:69], v[74:75], v[68:69]
	s_nop 0
	v_pk_mul_f32 v[74:75], v[64:65], v[68:69]
	v_pk_fma_f32 v[68:69], v[64:65], v[68:69], v[64:65] neg_lo:[1,0,0] neg_hi:[1,0,0]
	v_and_b32_e32 v64, 0x7fffffff, v66
	v_cndmask_b32_e32 v74, v68, v74, vcc
	v_cmp_gt_f32_e32 vcc, 0, v65
	v_and_b32_e32 v65, 0x7fffffff, v67
	v_pk_fma_f32 v[64:65], v[64:65], s[64:65], 1.0 op_sel_hi:[1,0,0]
	v_cndmask_b32_e32 v75, v69, v75, vcc
	v_rcp_f32_e32 v64, v64
	v_rcp_f32_e32 v65, v65
	v_cmp_gt_f32_e32 vcc, 0, v66
	v_pk_fma_f32 v[68:69], v[64:65], s[74:75], v[72:73] op_sel_hi:[1,0,0]
	s_nop 0
	v_pk_fma_f32 v[68:69], v[64:65], v[68:69], s[86:87] op_sel_hi:[1,1,0]
	s_nop 0
	v_pk_fma_f32 v[68:69], v[64:65], v[68:69], s[0:1] op_sel_hi:[1,1,0]
	s_nop 0
	v_pk_fma_f32 v[68:69], v[64:65], v[68:69], s[4:5] op_sel_hi:[1,1,0]
	s_nop 0
	v_pk_mul_f32 v[64:65], v[64:65], v[68:69]
	v_pk_mul_f32 v[68:69], v[70:71], s[30:31] op_sel_hi:[1,0]
	s_nop 0
	v_exp_f32_e32 v68, v68
	v_exp_f32_e32 v69, v69
	s_nop 0
	v_pk_mul_f32 v[64:65], v[68:69], v[64:65]
	s_nop 0
	v_pk_mul_f32 v[68:69], v[66:67], v[64:65]
	v_pk_fma_f32 v[64:65], v[66:67], v[64:65], v[66:67] neg_lo:[1,0,0] neg_hi:[1,0,0]
	s_nop 0
	v_cndmask_b32_e32 v68, v64, v68, vcc
	v_mul_f32_e32 v64, v79, v79
	v_fmac_f32_e32 v64, v78, v78
	v_fmac_f32_e32 v64, v76, v76
	v_fmac_f32_e32 v64, v77, v77
	v_fmac_f32_e32 v64, v74, v74
	v_cmp_gt_f32_e32 vcc, 0, v67
	v_fmac_f32_e32 v64, v75, v75
	v_fmac_f32_e32 v64, v68, v68
	v_cndmask_b32_e32 v67, v65, v69, vcc
	v_fmac_f32_e32 v64, v67, v67
	v_add_f32_e32 v69, v89, v64
	v_cvt_pk_bf16_f32 v64, v78, v79
	v_cvt_pk_bf16_f32 v65, v76, v77
	v_cvt_pk_bf16_f32 v66, v74, v75
	v_cvt_pk_bf16_f32 v67, v68, v67
	global_store_dwordx4 v[82:83], v[64:67], off offset:256
	ds_bpermute_b32 v64, v133, v69
	s_waitcnt lgkmcnt(0)
	v_add_f32_e32 v64, v69, v64
	ds_bpermute_b32 v65, v134, v64
	s_and_saveexec_b64 s[30:31], s[28:29]
	s_cbranch_execz .LBB0_875
	s_waitcnt lgkmcnt(0)
	v_add_f32_e32 v64, v64, v65
	v_cvt_f64_f32_e32 v[64:65], v64
	v_ldexp_f64 v[64:65], v[64:65], 32
	v_trunc_f64_e32 v[64:65], v[64:65]
	v_ldexp_f64 v[68:69], v[64:65], s93
	v_floor_f64_e32 v[68:69], v[68:69]
	v_fmac_f64_e32 v[64:65], 0xc1f00000, v[68:69]
	v_lshl_add_u64 v[66:67], v[80:81], 3, s[18:19]
	v_cvt_u32_f64_e32 v64, v[64:65]
	v_cvt_u32_f64_e32 v65, v[68:69]
	global_atomic_add_x2 v[66:67], v[64:65], off
; __device__ __forceinline__ float rinv_st(stat_t s, float invn) { return rsqrtf((float)((double)s * (1.0 / 4294967296.0)) * invn + 1e-6f); }
;     __device__ __forceinline__ void operator()(const f32x4 (&acc)[2][2][4][2], const Unit& u, int wr, int wc, int fr, int fq) const {
;     ...
;             for (int m = 0; m < 4; ++m) {
;                 const int row = row0 + ai * HALF + m * 16; const float r = rinv_st(stats[row], 1.0f / 2048.0f);
;                 bf16_t* rowp = uv + (size_t)row * 4096 + col0; float ss = 0.f;
; #pragma unroll
;                 for (int bj = 0; bj < 2; ++bj) {
;                     const f32x4 v0 = acc[ai][bj][m][0] * r + bv[bj][0], v1 = acc[ai][bj][m][1] * r + bv[bj][1];
;                     const f32x2 a = gelu_pk((f32x2){v0[0], v0[1]}), b = gelu_pk((f32x2){v0[2], v0[3]}), c = gelu_pk((f32x2){v1[0], v1[1]}), d = gelu_pk((f32x2){v1[2], v1[3]});
.LBB0_875:
	s_or_b64 exec, exec, s[30:31]
	s_nop 1
	v_mov_b64_e32 v[66:67], v[216:217]
	s_mov_b32 s30, 0xbf38aa3b
	v_add_u32_e32 v64, 0x90, v156
	s_waitcnt lgkmcnt(0)
	v_ashrrev_i32_e32 v65, 31, v64
	v_cvt_f64_u32_e32 v[68:69], v67
	v_ldexp_f64 v[68:69], v[68:69], 32
	v_cvt_f64_u32_e32 v[66:67], v66
	v_add_f64 v[66:67], v[68:69], v[66:67]
	v_ldexp_f64 v[66:67], v[66:67], s93
	v_cvt_f32_f64_e32 v66, v[66:67]
	v_fmamk_f32 v66, v66, 0x3a000000, v189
	v_cmp_gt_f32_e32 vcc, s78, v66
	v_mul_f32_e32 v67, 0x4b800000, v66
	s_nop 0
	v_cndmask_b32_e32 v66, v66, v67, vcc
	v_rsq_f32_e32 v66, v66
	s_nop 0
	v_mul_f32_e32 v67, 0x45800000, v66
	v_cndmask_b32_e32 v68, v66, v67, vcc
	v_pk_fma_f32 v[70:71], v[60:61], v[68:69], v[36:37] op_sel_hi:[1,0,1]
	v_pk_fma_f32 v[60:61], v[56:57], v[68:69], v[32:33] op_sel_hi:[1,0,1]
	v_and_b32_e32 v57, 0x7fffffff, v71
	v_and_b32_e32 v56, 0x7fffffff, v70
	v_pk_fma_f32 v[56:57], v[56:57], s[64:65], 1.0 op_sel_hi:[1,0,0]
	v_pk_mul_f32 v[76:77], v[70:71], v[70:71]
	v_rcp_f32_e32 v72, v56
	v_rcp_f32_e32 v73, v57
	v_mov_b64_e32 v[56:57], s[80:81]
	v_pk_mul_f32 v[76:77], v[76:77], s[30:31] op_sel_hi:[1,0]
	v_cmp_gt_f32_e32 vcc, 0, v70
	v_pk_fma_f32 v[74:75], v[72:73], s[74:75], v[56:57] op_sel_hi:[1,0,0]
	v_exp_f32_e32 v76, v76
	v_pk_fma_f32 v[74:75], v[72:73], v[74:75], s[86:87] op_sel_hi:[1,1,0]
	v_exp_f32_e32 v77, v77
	v_pk_fma_f32 v[74:75], v[72:73], v[74:75], s[0:1] op_sel_hi:[1,1,0]
	v_pk_fma_f32 v[62:63], v[62:63], v[68:69], v[38:39] op_sel_hi:[1,0,1]
	v_pk_fma_f32 v[74:75], v[72:73], v[74:75], s[4:5] op_sel_hi:[1,1,0]
	v_pk_fma_f32 v[58:59], v[58:59], v[68:69], v[34:35] op_sel_hi:[1,0,1]
	v_pk_mul_f32 v[72:73], v[72:73], v[74:75]
	v_pk_mul_f32 v[74:75], v[62:63], v[62:63]
	v_pk_mul_f32 v[72:73], v[76:77], v[72:73]
	v_pk_mul_f32 v[74:75], v[74:75], s[30:31] op_sel_hi:[1,0]
	v_pk_mul_f32 v[76:77], v[70:71], v[72:73]
	v_pk_fma_f32 v[72:73], v[70:71], v[72:73], v[70:71] neg_lo:[1,0,0] neg_hi:[1,0,0]
	v_exp_f32_e32 v74, v74
	v_cndmask_b32_e32 v69, v72, v76, vcc
	v_cmp_gt_f32_e32 vcc, 0, v71
	v_and_b32_e32 v72, 0x7fffffff, v62
	v_exp_f32_e32 v75, v75
	v_cndmask_b32_e32 v70, v73, v77, vcc
	v_and_b32_e32 v73, 0x7fffffff, v63
	v_pk_fma_f32 v[72:73], v[72:73], s[64:65], 1.0 op_sel_hi:[1,0,0]
	v_cmp_gt_f32_e32 vcc, 0, v62
	v_rcp_f32_e32 v72, v72
	v_rcp_f32_e32 v73, v73
	v_lshlrev_b64 v[66:67], 13, v[64:65]
	v_lshl_add_u64 v[66:67], s[14:15], 0, v[66:67]
	v_lshl_add_u64 v[66:67], v[154:155], 1, v[66:67]
	v_pk_fma_f32 v[76:77], v[72:73], s[74:75], v[56:57] op_sel_hi:[1,0,0]
	v_pk_fma_f32 v[52:53], v[52:53], v[68:69], v[12:13] op_sel_hi:[1,0,1]
	v_pk_fma_f32 v[76:77], v[72:73], v[76:77], s[86:87] op_sel_hi:[1,1,0]
	v_pk_fma_f32 v[54:55], v[54:55], v[68:69], v[14:15] op_sel_hi:[1,0,1]
	v_pk_fma_f32 v[76:77], v[72:73], v[76:77], s[0:1] op_sel_hi:[1,1,0]
	v_pk_fma_f32 v[48:49], v[48:49], v[68:69], v[8:9] op_sel_hi:[1,0,1]
	v_pk_fma_f32 v[76:77], v[72:73], v[76:77], s[4:5] op_sel_hi:[1,1,0]
	v_pk_fma_f32 v[50:51], v[50:51], v[68:69], v[10:11] op_sel_hi:[1,0,1]
	v_pk_mul_f32 v[72:73], v[72:73], v[76:77]
	v_pk_mul_f32 v[76:77], v[60:61], v[60:61]
	v_pk_mul_f32 v[72:73], v[74:75], v[72:73]
	v_pk_mul_f32 v[76:77], v[76:77], s[30:31] op_sel_hi:[1,0]
	v_pk_mul_f32 v[74:75], v[62:63], v[72:73]
	v_pk_fma_f32 v[72:73], v[62:63], v[72:73], v[62:63] neg_lo:[1,0,0] neg_hi:[1,0,0]
	v_exp_f32_e32 v76, v76
	v_cndmask_b32_e32 v62, v72, v74, vcc
	v_cmp_gt_f32_e32 vcc, 0, v63
	v_and_b32_e32 v72, 0x7fffffff, v60
	v_exp_f32_e32 v77, v77
	v_cndmask_b32_e32 v63, v73, v75, vcc
	v_and_b32_e32 v73, 0x7fffffff, v61
	v_pk_fma_f32 v[72:73], v[72:73], s[64:65], 1.0 op_sel_hi:[1,0,0]
	v_cmp_gt_f32_e32 vcc, 0, v60
	v_rcp_f32_e32 v72, v72
	v_rcp_f32_e32 v73, v73
	s_nop 0
	v_pk_fma_f32 v[74:75], v[72:73], s[74:75], v[56:57] op_sel_hi:[1,0,0]
	s_nop 0
	v_pk_fma_f32 v[74:75], v[72:73], v[74:75], s[86:87] op_sel_hi:[1,1,0]
	s_nop 0
	v_pk_fma_f32 v[74:75], v[72:73], v[74:75], s[0:1] op_sel_hi:[1,1,0]
	s_nop 0
	v_pk_fma_f32 v[74:75], v[72:73], v[74:75], s[4:5] op_sel_hi:[1,1,0]
	s_nop 0
	v_pk_mul_f32 v[72:73], v[72:73], v[74:75]
	v_pk_mul_f32 v[74:75], v[58:59], v[58:59]
	v_pk_mul_f32 v[72:73], v[76:77], v[72:73]
	s_nop 0
	v_pk_mul_f32 v[76:77], v[60:61], v[72:73]
	v_pk_fma_f32 v[72:73], v[60:61], v[72:73], v[60:61] neg_lo:[1,0,0] neg_hi:[1,0,0]
	v_and_b32_e32 v60, 0x7fffffff, v58
	v_cndmask_b32_e32 v71, v72, v76, vcc
	v_cmp_gt_f32_e32 vcc, 0, v61
	v_and_b32_e32 v61, 0x7fffffff, v59
	v_pk_fma_f32 v[60:61], v[60:61], s[64:65], 1.0 op_sel_hi:[1,0,0]
	v_cndmask_b32_e32 v76, v73, v77, vcc
	v_rcp_f32_e32 v60, v60
	v_rcp_f32_e32 v61, v61
	v_cmp_gt_f32_e32 vcc, 0, v58
	v_pk_fma_f32 v[72:73], v[60:61], s[74:75], v[56:57] op_sel_hi:[1,0,0]
	s_nop 0
	v_pk_fma_f32 v[72:73], v[60:61], v[72:73], s[86:87] op_sel_hi:[1,1,0]
	s_nop 0
	v_pk_fma_f32 v[72:73], v[60:61], v[72:73], s[0:1] op_sel_hi:[1,1,0]
	s_nop 0
	v_pk_fma_f32 v[72:73], v[60:61], v[72:73], s[4:5] op_sel_hi:[1,1,0]
	s_nop 0
	v_pk_mul_f32 v[60:61], v[60:61], v[72:73]
	v_pk_mul_f32 v[72:73], v[74:75], s[30:31] op_sel_hi:[1,0]
	s_nop 0
	v_exp_f32_e32 v72, v72
	v_exp_f32_e32 v73, v73
	s_nop 0
	v_pk_mul_f32 v[60:61], v[72:73], v[60:61]
	s_nop 0
	v_pk_mul_f32 v[72:73], v[58:59], v[60:61]
	v_pk_fma_f32 v[60:61], v[58:59], v[60:61], v[58:59] neg_lo:[1,0,0] neg_hi:[1,0,0]
	v_cvt_pk_bf16_f32 v58, v69, v70
	s_nop 0
	v_cndmask_b32_e32 v72, v60, v72, vcc
	v_cmp_gt_f32_e32 vcc, 0, v59
	v_cvt_pk_bf16_f32 v59, v62, v63
	v_cvt_pk_bf16_f32 v60, v71, v76
	s_nop 1
	v_cndmask_b32_e32 v61, v61, v73, vcc
	v_mul_f32_e32 v73, v70, v70
	v_fmac_f32_e32 v73, v69, v69
	v_fmac_f32_e32 v73, v62, v62
	v_fmac_f32_e32 v73, v63, v63
	v_fmac_f32_e32 v73, v71, v71
; __device__ __forceinline__ unsigned cvt_pk_bf16(float lo, float hi) { unsigned r; asm volatile("v_cvt_pk_bf16_f32 %0, %1, %2" : "=v"(r) : "v"(lo), "v"(hi)); return r; }
; __device__ __forceinline__ void stat_add(stat_t* p, float ss) { __hip_atomic_fetch_add(p, (stat_t)((double)ss * 4294967296.0), __ATOMIC_RELAXED, __HIP_MEMORY_SCOPE_AGENT); }
;     __device__ __forceinline__ void operator()(const f32x4 (&acc)[2][2][4][2], const Unit& u, int wr, int wc, int fr, int fq) const {
;     ...
;                 for (int bj = 0; bj < 2; ++bj) {
;                     const f32x4 v0 = acc[ai][bj][m][0] * r + bv[bj][0], v1 = acc[ai][bj][m][1] * r + bv[bj][1];
;                     const f32x2 a = gelu_pk((f32x2){v0[0], v0[1]}), b = gelu_pk((f32x2){v0[2], v0[3]}), c = gelu_pk((f32x2){v1[0], v1[1]}), d = gelu_pk((f32x2){v1[2], v1[3]});
;                     ss += a.x * a.x + a.y * a.y + b.x * b.x + b.y * b.y + c.x * c.x + c.y * c.y + d.x * d.x + d.y * d.y;
;                     u32x4 w; w.x = cvt_pk_bf16(a.x, a.y); w.y = cvt_pk_bf16(b.x, b.y); w.z = cvt_pk_bf16(c.x, c.y); w.w = cvt_pk_bf16(d.x, d.y);
;                     *(u32x4*)(rowp + bj * HALF) = w;
;                 }
;                 ss += __shfl_xor(ss, 16); ss += __shfl_xor(ss, 32);
;                 if (isv && fq == 0) stat_add(stats_v + row, ss);
	v_fmac_f32_e32 v73, v76, v76
	v_fmac_f32_e32 v73, v72, v72
	v_fmac_f32_e32 v73, v61, v61
	v_cvt_pk_bf16_f32 v61, v72, v61
	global_store_dwordx4 v[66:67], v[58:61], off
	v_pk_mul_f32 v[62:63], v[52:53], v[52:53]
	v_cmp_gt_f32_e32 vcc, 0, v52
	v_and_b32_e32 v59, 0x7fffffff, v53
	v_and_b32_e32 v58, 0x7fffffff, v52
	v_pk_fma_f32 v[58:59], v[58:59], s[64:65], 1.0 op_sel_hi:[1,0,0]
	v_pk_mul_f32 v[62:63], v[62:63], s[30:31] op_sel_hi:[1,0]
	v_rcp_f32_e32 v58, v58
	v_rcp_f32_e32 v59, v59
	v_exp_f32_e32 v62, v62
	v_exp_f32_e32 v63, v63
	v_pk_fma_f32 v[60:61], v[58:59], s[74:75], v[56:57] op_sel_hi:[1,0,0]
	s_nop 0
	v_pk_fma_f32 v[60:61], v[58:59], v[60:61], s[86:87] op_sel_hi:[1,1,0]
	s_nop 0
	v_pk_fma_f32 v[60:61], v[58:59], v[60:61], s[0:1] op_sel_hi:[1,1,0]
	s_nop 0
	v_pk_fma_f32 v[60:61], v[58:59], v[60:61], s[4:5] op_sel_hi:[1,1,0]
	s_nop 0
	v_pk_mul_f32 v[58:59], v[58:59], v[60:61]
	v_pk_mul_f32 v[60:61], v[54:55], v[54:55]
	v_pk_mul_f32 v[58:59], v[62:63], v[58:59]
	s_nop 0
	v_pk_mul_f32 v[62:63], v[52:53], v[58:59]
	v_pk_fma_f32 v[58:59], v[52:53], v[58:59], v[52:53] neg_lo:[1,0,0] neg_hi:[1,0,0]
	v_and_b32_e32 v52, 0x7fffffff, v54
	v_cndmask_b32_e32 v62, v58, v62, vcc
	v_cmp_gt_f32_e32 vcc, 0, v53
	v_and_b32_e32 v53, 0x7fffffff, v55
	v_pk_fma_f32 v[52:53], v[52:53], s[64:65], 1.0 op_sel_hi:[1,0,0]
	v_cndmask_b32_e32 v63, v59, v63, vcc
	v_rcp_f32_e32 v52, v52
	v_rcp_f32_e32 v53, v53
	v_cmp_gt_f32_e32 vcc, 0, v54
	v_pk_fma_f32 v[58:59], v[52:53], s[74:75], v[56:57] op_sel_hi:[1,0,0]
	s_nop 0
	v_pk_fma_f32 v[58:59], v[52:53], v[58:59], s[86:87] op_sel_hi:[1,1,0]
	s_nop 0
	v_pk_fma_f32 v[58:59], v[52:53], v[58:59], s[0:1] op_sel_hi:[1,1,0]
	s_nop 0
	v_pk_fma_f32 v[58:59], v[52:53], v[58:59], s[4:5] op_sel_hi:[1,1,0]
	s_nop 0
	v_pk_mul_f32 v[52:53], v[52:53], v[58:59]
	v_pk_mul_f32 v[58:59], v[60:61], s[30:31] op_sel_hi:[1,0]
	s_nop 0
	v_exp_f32_e32 v58, v58
	v_exp_f32_e32 v59, v59
	s_nop 0
	v_pk_mul_f32 v[52:53], v[58:59], v[52:53]
	s_nop 0
	v_pk_mul_f32 v[58:59], v[54:55], v[52:53]
	v_pk_fma_f32 v[52:53], v[54:55], v[52:53], v[54:55] neg_lo:[1,0,0] neg_hi:[1,0,0]
	s_nop 0
	v_cndmask_b32_e32 v60, v52, v58, vcc
	v_cmp_gt_f32_e32 vcc, 0, v55
	v_and_b32_e32 v52, 0x7fffffff, v48
	s_nop 0
	v_cndmask_b32_e32 v61, v53, v59, vcc
	v_and_b32_e32 v53, 0x7fffffff, v49
	v_pk_fma_f32 v[52:53], v[52:53], s[64:65], 1.0 op_sel_hi:[1,0,0]
	v_pk_mul_f32 v[58:59], v[48:49], v[48:49]
	v_rcp_f32_e32 v52, v52
	v_rcp_f32_e32 v53, v53
	v_pk_mul_f32 v[58:59], v[58:59], s[30:31] op_sel_hi:[1,0]
	v_cmp_gt_f32_e32 vcc, 0, v48
	v_exp_f32_e32 v58, v58
	v_pk_fma_f32 v[54:55], v[52:53], s[74:75], v[56:57] op_sel_hi:[1,0,0]
	v_exp_f32_e32 v59, v59
	v_pk_fma_f32 v[54:55], v[52:53], v[54:55], s[86:87] op_sel_hi:[1,1,0]
	s_nop 0
	v_pk_fma_f32 v[54:55], v[52:53], v[54:55], s[0:1] op_sel_hi:[1,1,0]
	s_nop 0
	v_pk_fma_f32 v[54:55], v[52:53], v[54:55], s[4:5] op_sel_hi:[1,1,0]
	s_nop 0
	v_pk_mul_f32 v[52:53], v[52:53], v[54:55]
	v_pk_mul_f32 v[54:55], v[50:51], v[50:51]
	v_pk_mul_f32 v[52:53], v[58:59], v[52:53]
	s_nop 0
	v_pk_mul_f32 v[58:59], v[48:49], v[52:53]
	v_pk_fma_f32 v[52:53], v[48:49], v[52:53], v[48:49] neg_lo:[1,0,0] neg_hi:[1,0,0]
	v_and_b32_e32 v48, 0x7fffffff, v50
	v_cndmask_b32_e32 v58, v52, v58, vcc
	v_cmp_gt_f32_e32 vcc, 0, v49
	v_and_b32_e32 v49, 0x7fffffff, v51
	v_pk_fma_f32 v[48:49], v[48:49], s[64:65], 1.0 op_sel_hi:[1,0,0]
	v_cndmask_b32_e32 v59, v53, v59, vcc
	v_rcp_f32_e32 v48, v48
	v_rcp_f32_e32 v49, v49
	v_cmp_gt_f32_e32 vcc, 0, v50
	v_pk_fma_f32 v[52:53], v[48:49], s[74:75], v[56:57] op_sel_hi:[1,0,0]
	s_nop 0
	v_pk_fma_f32 v[52:53], v[48:49], v[52:53], s[86:87] op_sel_hi:[1,1,0]
	s_nop 0
	v_pk_fma_f32 v[52:53], v[48:49], v[52:53], s[0:1] op_sel_hi:[1,1,0]
	s_nop 0
	v_pk_fma_f32 v[52:53], v[48:49], v[52:53], s[4:5] op_sel_hi:[1,1,0]
	s_nop 0
	v_pk_mul_f32 v[48:49], v[48:49], v[52:53]
	v_pk_mul_f32 v[52:53], v[54:55], s[30:31] op_sel_hi:[1,0]
	s_nop 0
	v_exp_f32_e32 v52, v52
	v_exp_f32_e32 v53, v53
	s_nop 0
	v_pk_mul_f32 v[48:49], v[52:53], v[48:49]
	s_nop 0
	v_pk_mul_f32 v[52:53], v[50:51], v[48:49]
	v_pk_fma_f32 v[48:49], v[50:51], v[48:49], v[50:51] neg_lo:[1,0,0] neg_hi:[1,0,0]
	s_nop 0
	v_cndmask_b32_e32 v52, v48, v52, vcc
	v_mul_f32_e32 v48, v63, v63
	v_fmac_f32_e32 v48, v62, v62
	v_fmac_f32_e32 v48, v60, v60
	v_fmac_f32_e32 v48, v61, v61
	v_fmac_f32_e32 v48, v58, v58
	v_cmp_gt_f32_e32 vcc, 0, v51
	v_fmac_f32_e32 v48, v59, v59
	v_fmac_f32_e32 v48, v52, v52
	v_cndmask_b32_e32 v51, v49, v53, vcc
	v_fmac_f32_e32 v48, v51, v51
	v_add_f32_e32 v53, v73, v48
	v_cvt_pk_bf16_f32 v48, v62, v63
	v_cvt_pk_bf16_f32 v49, v60, v61
	v_cvt_pk_bf16_f32 v50, v58, v59
	v_cvt_pk_bf16_f32 v51, v52, v51
	global_store_dwordx4 v[66:67], v[48:51], off offset:256
	ds_bpermute_b32 v48, v133, v53
	s_waitcnt lgkmcnt(0)
	v_add_f32_e32 v48, v53, v48
	ds_bpermute_b32 v49, v134, v48
	s_and_saveexec_b64 s[30:31], s[28:29]
	s_cbranch_execz .LBB0_877
	s_waitcnt lgkmcnt(0)
	v_add_f32_e32 v48, v48, v49
	v_cvt_f64_f32_e32 v[48:49], v48
	v_ldexp_f64 v[48:49], v[48:49], 32
	v_trunc_f64_e32 v[48:49], v[48:49]
	v_ldexp_f64 v[52:53], v[48:49], s93
	v_floor_f64_e32 v[52:53], v[52:53]
	v_fmac_f64_e32 v[48:49], 0xc1f00000, v[52:53]
	v_lshl_add_u64 v[50:51], v[64:65], 3, s[18:19]
	v_cvt_u32_f64_e32 v48, v[48:49]
	v_cvt_u32_f64_e32 v49, v[52:53]
	global_atomic_add_x2 v[50:51], v[48:49], off
; __device__ __forceinline__ float rinv_st(stat_t s, float invn) { return rsqrtf((float)((double)s * (1.0 / 4294967296.0)) * invn + 1e-6f); }
;     __device__ __forceinline__ void operator()(const f32x4 (&acc)[2][2][4][2], const Unit& u, int wr, int wc, int fr, int fq) const {
;     ...
;             for (int m = 0; m < 4; ++m) {
;                 const int row = row0 + ai * HALF + m * 16; const float r = rinv_st(stats[row], 1.0f / 2048.0f);
;                 bf16_t* rowp = uv + (size_t)row * 4096 + col0; float ss = 0.f;
; #pragma unroll
;                 for (int bj = 0; bj < 2; ++bj) {
;                     const f32x4 v0 = acc[ai][bj][m][0] * r + bv[bj][0], v1 = acc[ai][bj][m][1] * r + bv[bj][1];
;                     const f32x2 a = gelu_pk((f32x2){v0[0], v0[1]}), b = gelu_pk((f32x2){v0[2], v0[3]}), c = gelu_pk((f32x2){v1[0], v1[1]}), d = gelu_pk((f32x2){v1[2], v1[3]});
.LBB0_877:
	s_or_b64 exec, exec, s[30:31]
	s_nop 1
	v_mov_b64_e32 v[50:51], v[218:219]
	s_mov_b32 s30, 0xbf38aa3b
	v_add_u32_e32 v48, 0xa0, v156
	s_waitcnt lgkmcnt(0)
	v_ashrrev_i32_e32 v49, 31, v48
	v_cvt_f64_u32_e32 v[52:53], v51
	v_ldexp_f64 v[52:53], v[52:53], 32
	v_cvt_f64_u32_e32 v[50:51], v50
	v_add_f64 v[50:51], v[52:53], v[50:51]
	v_ldexp_f64 v[50:51], v[50:51], s93
	v_cvt_f32_f64_e32 v50, v[50:51]
	v_fmamk_f32 v50, v50, 0x3a000000, v189
	v_cmp_gt_f32_e32 vcc, s78, v50
	v_mul_f32_e32 v51, 0x4b800000, v50
	s_nop 0
	v_cndmask_b32_e32 v50, v50, v51, vcc
	v_rsq_f32_e32 v50, v50
	s_nop 0
	v_mul_f32_e32 v51, 0x45800000, v50
	v_cndmask_b32_e32 v52, v50, v51, vcc
	v_pk_fma_f32 v[54:55], v[44:45], v[52:53], v[36:37] op_sel_hi:[1,0,1]
	v_pk_fma_f32 v[44:45], v[40:41], v[52:53], v[32:33] op_sel_hi:[1,0,1]
	v_and_b32_e32 v41, 0x7fffffff, v55
	v_and_b32_e32 v40, 0x7fffffff, v54
	v_pk_fma_f32 v[40:41], v[40:41], s[64:65], 1.0 op_sel_hi:[1,0,0]
	v_pk_mul_f32 v[60:61], v[54:55], v[54:55]
	v_rcp_f32_e32 v56, v40
	v_rcp_f32_e32 v57, v41
	v_mov_b64_e32 v[40:41], s[80:81]
	v_pk_mul_f32 v[60:61], v[60:61], s[30:31] op_sel_hi:[1,0]
	v_cmp_gt_f32_e32 vcc, 0, v54
	v_pk_fma_f32 v[58:59], v[56:57], s[74:75], v[40:41] op_sel_hi:[1,0,0]
	v_exp_f32_e32 v60, v60
	v_pk_fma_f32 v[58:59], v[56:57], v[58:59], s[86:87] op_sel_hi:[1,1,0]
	v_exp_f32_e32 v61, v61
	v_pk_fma_f32 v[58:59], v[56:57], v[58:59], s[0:1] op_sel_hi:[1,1,0]
	v_pk_fma_f32 v[46:47], v[46:47], v[52:53], v[38:39] op_sel_hi:[1,0,1]
	v_pk_fma_f32 v[58:59], v[56:57], v[58:59], s[4:5] op_sel_hi:[1,1,0]
	v_pk_fma_f32 v[42:43], v[42:43], v[52:53], v[34:35] op_sel_hi:[1,0,1]
	v_pk_mul_f32 v[56:57], v[56:57], v[58:59]
	v_pk_mul_f32 v[58:59], v[46:47], v[46:47]
	v_pk_mul_f32 v[56:57], v[60:61], v[56:57]
	v_pk_mul_f32 v[58:59], v[58:59], s[30:31] op_sel_hi:[1,0]
	v_pk_mul_f32 v[60:61], v[54:55], v[56:57]
	v_pk_fma_f32 v[56:57], v[54:55], v[56:57], v[54:55] neg_lo:[1,0,0] neg_hi:[1,0,0]
	v_exp_f32_e32 v58, v58
	v_cndmask_b32_e32 v53, v56, v60, vcc
	v_cmp_gt_f32_e32 vcc, 0, v55
	v_and_b32_e32 v56, 0x7fffffff, v46
	v_exp_f32_e32 v59, v59
	v_cndmask_b32_e32 v54, v57, v61, vcc
	v_and_b32_e32 v57, 0x7fffffff, v47
	v_pk_fma_f32 v[56:57], v[56:57], s[64:65], 1.0 op_sel_hi:[1,0,0]
	v_cmp_gt_f32_e32 vcc, 0, v46
	v_rcp_f32_e32 v56, v56
	v_rcp_f32_e32 v57, v57
	v_lshlrev_b64 v[50:51], 13, v[48:49]
	v_lshl_add_u64 v[50:51], s[14:15], 0, v[50:51]
	v_lshl_add_u64 v[50:51], v[154:155], 1, v[50:51]
	v_pk_fma_f32 v[60:61], v[56:57], s[74:75], v[40:41] op_sel_hi:[1,0,0]
	v_pk_fma_f32 v[28:29], v[28:29], v[52:53], v[12:13] op_sel_hi:[1,0,1]
	v_pk_fma_f32 v[60:61], v[56:57], v[60:61], s[86:87] op_sel_hi:[1,1,0]
	v_pk_fma_f32 v[30:31], v[30:31], v[52:53], v[14:15] op_sel_hi:[1,0,1]
	v_pk_fma_f32 v[60:61], v[56:57], v[60:61], s[0:1] op_sel_hi:[1,1,0]
	v_pk_fma_f32 v[24:25], v[24:25], v[52:53], v[8:9] op_sel_hi:[1,0,1]
	v_pk_fma_f32 v[60:61], v[56:57], v[60:61], s[4:5] op_sel_hi:[1,1,0]
	v_pk_fma_f32 v[26:27], v[26:27], v[52:53], v[10:11] op_sel_hi:[1,0,1]
	v_pk_mul_f32 v[56:57], v[56:57], v[60:61]
	v_pk_mul_f32 v[60:61], v[44:45], v[44:45]
	v_pk_mul_f32 v[56:57], v[58:59], v[56:57]
	v_pk_mul_f32 v[60:61], v[60:61], s[30:31] op_sel_hi:[1,0]
	v_pk_mul_f32 v[58:59], v[46:47], v[56:57]
	v_pk_fma_f32 v[56:57], v[46:47], v[56:57], v[46:47] neg_lo:[1,0,0] neg_hi:[1,0,0]
	v_exp_f32_e32 v60, v60
	v_cndmask_b32_e32 v46, v56, v58, vcc
	v_cmp_gt_f32_e32 vcc, 0, v47
	v_and_b32_e32 v56, 0x7fffffff, v44
	v_exp_f32_e32 v61, v61
	v_cndmask_b32_e32 v47, v57, v59, vcc
	v_and_b32_e32 v57, 0x7fffffff, v45
	v_pk_fma_f32 v[56:57], v[56:57], s[64:65], 1.0 op_sel_hi:[1,0,0]
	v_cmp_gt_f32_e32 vcc, 0, v44
	v_rcp_f32_e32 v56, v56
	v_rcp_f32_e32 v57, v57
	s_nop 0
	v_pk_fma_f32 v[58:59], v[56:57], s[74:75], v[40:41] op_sel_hi:[1,0,0]
	s_nop 0
	v_pk_fma_f32 v[58:59], v[56:57], v[58:59], s[86:87] op_sel_hi:[1,1,0]
	s_nop 0
	v_pk_fma_f32 v[58:59], v[56:57], v[58:59], s[0:1] op_sel_hi:[1,1,0]
	s_nop 0
	v_pk_fma_f32 v[58:59], v[56:57], v[58:59], s[4:5] op_sel_hi:[1,1,0]
	s_nop 0
	v_pk_mul_f32 v[56:57], v[56:57], v[58:59]
	v_pk_mul_f32 v[58:59], v[42:43], v[42:43]
	v_pk_mul_f32 v[56:57], v[60:61], v[56:57]
	s_nop 0
	v_pk_mul_f32 v[60:61], v[44:45], v[56:57]
	v_pk_fma_f32 v[56:57], v[44:45], v[56:57], v[44:45] neg_lo:[1,0,0] neg_hi:[1,0,0]
	v_and_b32_e32 v44, 0x7fffffff, v42
	v_cndmask_b32_e32 v55, v56, v60, vcc
	v_cmp_gt_f32_e32 vcc, 0, v45
	v_and_b32_e32 v45, 0x7fffffff, v43
	v_pk_fma_f32 v[44:45], v[44:45], s[64:65], 1.0 op_sel_hi:[1,0,0]
	v_cndmask_b32_e32 v60, v57, v61, vcc
	v_rcp_f32_e32 v44, v44
	v_rcp_f32_e32 v45, v45
	v_cmp_gt_f32_e32 vcc, 0, v42
	v_pk_fma_f32 v[56:57], v[44:45], s[74:75], v[40:41] op_sel_hi:[1,0,0]
	s_nop 0
	v_pk_fma_f32 v[56:57], v[44:45], v[56:57], s[86:87] op_sel_hi:[1,1,0]
	s_nop 0
	v_pk_fma_f32 v[56:57], v[44:45], v[56:57], s[0:1] op_sel_hi:[1,1,0]
	s_nop 0
	v_pk_fma_f32 v[56:57], v[44:45], v[56:57], s[4:5] op_sel_hi:[1,1,0]
	s_nop 0
	v_pk_mul_f32 v[44:45], v[44:45], v[56:57]
	v_pk_mul_f32 v[56:57], v[58:59], s[30:31] op_sel_hi:[1,0]
	s_nop 0
	v_exp_f32_e32 v56, v56
	v_exp_f32_e32 v57, v57
	s_nop 0
	v_pk_mul_f32 v[44:45], v[56:57], v[44:45]
	s_nop 0
	v_pk_mul_f32 v[56:57], v[42:43], v[44:45]
	v_pk_fma_f32 v[44:45], v[42:43], v[44:45], v[42:43] neg_lo:[1,0,0] neg_hi:[1,0,0]
	v_cvt_pk_bf16_f32 v42, v53, v54
	s_nop 0
	v_cndmask_b32_e32 v56, v44, v56, vcc
	v_cmp_gt_f32_e32 vcc, 0, v43
	v_cvt_pk_bf16_f32 v43, v46, v47
	v_cvt_pk_bf16_f32 v44, v55, v60
	s_nop 1
	v_cndmask_b32_e32 v45, v45, v57, vcc
	v_mul_f32_e32 v57, v54, v54
	v_fmac_f32_e32 v57, v53, v53
	v_fmac_f32_e32 v57, v46, v46
	v_fmac_f32_e32 v57, v47, v47
	v_fmac_f32_e32 v57, v55, v55
; __device__ __forceinline__ unsigned cvt_pk_bf16(float lo, float hi) { unsigned r; asm volatile("v_cvt_pk_bf16_f32 %0, %1, %2" : "=v"(r) : "v"(lo), "v"(hi)); return r; }
; __device__ __forceinline__ void stat_add(stat_t* p, float ss) { __hip_atomic_fetch_add(p, (stat_t)((double)ss * 4294967296.0), __ATOMIC_RELAXED, __HIP_MEMORY_SCOPE_AGENT); }
;     __device__ __forceinline__ void operator()(const f32x4 (&acc)[2][2][4][2], const Unit& u, int wr, int wc, int fr, int fq) const {
;     ...
;                 for (int bj = 0; bj < 2; ++bj) {
;                     const f32x4 v0 = acc[ai][bj][m][0] * r + bv[bj][0], v1 = acc[ai][bj][m][1] * r + bv[bj][1];
;                     const f32x2 a = gelu_pk((f32x2){v0[0], v0[1]}), b = gelu_pk((f32x2){v0[2], v0[3]}), c = gelu_pk((f32x2){v1[0], v1[1]}), d = gelu_pk((f32x2){v1[2], v1[3]});
;                     ss += a.x * a.x + a.y * a.y + b.x * b.x + b.y * b.y + c.x * c.x + c.y * c.y + d.x * d.x + d.y * d.y;
;                     u32x4 w; w.x = cvt_pk_bf16(a.x, a.y); w.y = cvt_pk_bf16(b.x, b.y); w.z = cvt_pk_bf16(c.x, c.y); w.w = cvt_pk_bf16(d.x, d.y);
;                     *(u32x4*)(rowp + bj * HALF) = w;
;                 }
;                 ss += __shfl_xor(ss, 16); ss += __shfl_xor(ss, 32);
;                 if (isv && fq == 0) stat_add(stats_v + row, ss);
	v_fmac_f32_e32 v57, v60, v60
	v_fmac_f32_e32 v57, v56, v56
	v_fmac_f32_e32 v57, v45, v45
	v_cvt_pk_bf16_f32 v45, v56, v45
	global_store_dwordx4 v[50:51], v[42:45], off
	v_pk_mul_f32 v[46:47], v[28:29], v[28:29]
	v_cmp_gt_f32_e32 vcc, 0, v28
	v_and_b32_e32 v43, 0x7fffffff, v29
	v_and_b32_e32 v42, 0x7fffffff, v28
	v_pk_fma_f32 v[42:43], v[42:43], s[64:65], 1.0 op_sel_hi:[1,0,0]
	v_pk_mul_f32 v[46:47], v[46:47], s[30:31] op_sel_hi:[1,0]
	v_rcp_f32_e32 v42, v42
	v_rcp_f32_e32 v43, v43
	v_exp_f32_e32 v46, v46
	v_exp_f32_e32 v47, v47
	v_pk_fma_f32 v[44:45], v[42:43], s[74:75], v[40:41] op_sel_hi:[1,0,0]
	s_nop 0
	v_pk_fma_f32 v[44:45], v[42:43], v[44:45], s[86:87] op_sel_hi:[1,1,0]
	s_nop 0
	v_pk_fma_f32 v[44:45], v[42:43], v[44:45], s[0:1] op_sel_hi:[1,1,0]
	s_nop 0
	v_pk_fma_f32 v[44:45], v[42:43], v[44:45], s[4:5] op_sel_hi:[1,1,0]
	s_nop 0
	v_pk_mul_f32 v[42:43], v[42:43], v[44:45]
	v_pk_mul_f32 v[44:45], v[30:31], v[30:31]
	v_pk_mul_f32 v[42:43], v[46:47], v[42:43]
	s_nop 0
	v_pk_mul_f32 v[46:47], v[28:29], v[42:43]
	v_pk_fma_f32 v[42:43], v[28:29], v[42:43], v[28:29] neg_lo:[1,0,0] neg_hi:[1,0,0]
	v_and_b32_e32 v28, 0x7fffffff, v30
	v_cndmask_b32_e32 v46, v42, v46, vcc
	v_cmp_gt_f32_e32 vcc, 0, v29
	v_and_b32_e32 v29, 0x7fffffff, v31
	v_pk_fma_f32 v[28:29], v[28:29], s[64:65], 1.0 op_sel_hi:[1,0,0]
	v_cndmask_b32_e32 v47, v43, v47, vcc
	v_rcp_f32_e32 v28, v28
	v_rcp_f32_e32 v29, v29
	v_cmp_gt_f32_e32 vcc, 0, v30
	v_pk_fma_f32 v[42:43], v[28:29], s[74:75], v[40:41] op_sel_hi:[1,0,0]
	s_nop 0
	v_pk_fma_f32 v[42:43], v[28:29], v[42:43], s[86:87] op_sel_hi:[1,1,0]
	s_nop 0
	v_pk_fma_f32 v[42:43], v[28:29], v[42:43], s[0:1] op_sel_hi:[1,1,0]
	s_nop 0
	v_pk_fma_f32 v[42:43], v[28:29], v[42:43], s[4:5] op_sel_hi:[1,1,0]
	s_nop 0
	v_pk_mul_f32 v[28:29], v[28:29], v[42:43]
	v_pk_mul_f32 v[42:43], v[44:45], s[30:31] op_sel_hi:[1,0]
	s_nop 0
	v_exp_f32_e32 v42, v42
	v_exp_f32_e32 v43, v43
	s_nop 0
	v_pk_mul_f32 v[28:29], v[42:43], v[28:29]
	s_nop 0
	v_pk_mul_f32 v[42:43], v[30:31], v[28:29]
	v_pk_fma_f32 v[28:29], v[30:31], v[28:29], v[30:31] neg_lo:[1,0,0] neg_hi:[1,0,0]
	s_nop 0
	v_cndmask_b32_e32 v44, v28, v42, vcc
	v_cmp_gt_f32_e32 vcc, 0, v31
	v_and_b32_e32 v28, 0x7fffffff, v24
	s_nop 0
	v_cndmask_b32_e32 v45, v29, v43, vcc
	v_and_b32_e32 v29, 0x7fffffff, v25
	v_pk_fma_f32 v[28:29], v[28:29], s[64:65], 1.0 op_sel_hi:[1,0,0]
	v_pk_mul_f32 v[42:43], v[24:25], v[24:25]
	v_rcp_f32_e32 v28, v28
	v_rcp_f32_e32 v29, v29
	v_pk_mul_f32 v[42:43], v[42:43], s[30:31] op_sel_hi:[1,0]
	v_cmp_gt_f32_e32 vcc, 0, v24
	v_exp_f32_e32 v42, v42
	v_pk_fma_f32 v[30:31], v[28:29], s[74:75], v[40:41] op_sel_hi:[1,0,0]
	v_exp_f32_e32 v43, v43
	v_pk_fma_f32 v[30:31], v[28:29], v[30:31], s[86:87] op_sel_hi:[1,1,0]
	s_nop 0
	v_pk_fma_f32 v[30:31], v[28:29], v[30:31], s[0:1] op_sel_hi:[1,1,0]
	s_nop 0
	v_pk_fma_f32 v[30:31], v[28:29], v[30:31], s[4:5] op_sel_hi:[1,1,0]
	s_nop 0
	v_pk_mul_f32 v[28:29], v[28:29], v[30:31]
	v_pk_mul_f32 v[30:31], v[26:27], v[26:27]
	v_pk_mul_f32 v[28:29], v[42:43], v[28:29]
	s_nop 0
	v_pk_mul_f32 v[42:43], v[24:25], v[28:29]
	v_pk_fma_f32 v[28:29], v[24:25], v[28:29], v[24:25] neg_lo:[1,0,0] neg_hi:[1,0,0]
	v_and_b32_e32 v24, 0x7fffffff, v26
	v_cndmask_b32_e32 v42, v28, v42, vcc
	v_cmp_gt_f32_e32 vcc, 0, v25
	v_and_b32_e32 v25, 0x7fffffff, v27
	v_pk_fma_f32 v[24:25], v[24:25], s[64:65], 1.0 op_sel_hi:[1,0,0]
	v_cndmask_b32_e32 v43, v29, v43, vcc
	v_rcp_f32_e32 v24, v24
	v_rcp_f32_e32 v25, v25
	v_cmp_gt_f32_e32 vcc, 0, v26
	v_pk_fma_f32 v[28:29], v[24:25], s[74:75], v[40:41] op_sel_hi:[1,0,0]
	s_nop 0
	v_pk_fma_f32 v[28:29], v[24:25], v[28:29], s[86:87] op_sel_hi:[1,1,0]
	s_nop 0
	v_pk_fma_f32 v[28:29], v[24:25], v[28:29], s[0:1] op_sel_hi:[1,1,0]
	s_nop 0
	v_pk_fma_f32 v[28:29], v[24:25], v[28:29], s[4:5] op_sel_hi:[1,1,0]
	s_nop 0
	v_pk_mul_f32 v[24:25], v[24:25], v[28:29]
	v_pk_mul_f32 v[28:29], v[30:31], s[30:31] op_sel_hi:[1,0]
	s_nop 0
	v_exp_f32_e32 v28, v28
	v_exp_f32_e32 v29, v29
	s_nop 0
	v_pk_mul_f32 v[24:25], v[28:29], v[24:25]
	s_nop 0
	v_pk_mul_f32 v[28:29], v[26:27], v[24:25]
	v_pk_fma_f32 v[24:25], v[26:27], v[24:25], v[26:27] neg_lo:[1,0,0] neg_hi:[1,0,0]
	s_nop 0
	v_cndmask_b32_e32 v28, v24, v28, vcc
	v_mul_f32_e32 v24, v47, v47
	v_fmac_f32_e32 v24, v46, v46
	v_fmac_f32_e32 v24, v44, v44
	v_fmac_f32_e32 v24, v45, v45
	v_fmac_f32_e32 v24, v42, v42
	v_cmp_gt_f32_e32 vcc, 0, v27
	v_fmac_f32_e32 v24, v43, v43
	v_fmac_f32_e32 v24, v28, v28
	v_cndmask_b32_e32 v27, v25, v29, vcc
	v_fmac_f32_e32 v24, v27, v27
	v_add_f32_e32 v29, v57, v24
	v_cvt_pk_bf16_f32 v24, v46, v47
	v_cvt_pk_bf16_f32 v25, v44, v45
	v_cvt_pk_bf16_f32 v26, v42, v43
	v_cvt_pk_bf16_f32 v27, v28, v27
	global_store_dwordx4 v[50:51], v[24:27], off offset:256
	ds_bpermute_b32 v24, v133, v29
	s_waitcnt lgkmcnt(0)
	v_add_f32_e32 v24, v29, v24
	ds_bpermute_b32 v25, v134, v24
	s_and_saveexec_b64 s[30:31], s[28:29]
	s_cbranch_execz .LBB0_879
	s_waitcnt lgkmcnt(0)
	v_add_f32_e32 v24, v24, v25
	v_cvt_f64_f32_e32 v[24:25], v24
	v_ldexp_f64 v[24:25], v[24:25], 32
	v_trunc_f64_e32 v[24:25], v[24:25]
	v_ldexp_f64 v[28:29], v[24:25], s93
	v_floor_f64_e32 v[28:29], v[28:29]
	v_fmac_f64_e32 v[24:25], 0xc1f00000, v[28:29]
	v_lshl_add_u64 v[26:27], v[48:49], 3, s[18:19]
	v_cvt_u32_f64_e32 v24, v[24:25]
	v_cvt_u32_f64_e32 v25, v[28:29]
	global_atomic_add_x2 v[26:27], v[24:25], off
; __device__ __forceinline__ float rinv_st(stat_t s, float invn) { return rsqrtf((float)((double)s * (1.0 / 4294967296.0)) * invn + 1e-6f); }
;     __device__ __forceinline__ void operator()(const f32x4 (&acc)[2][2][4][2], const Unit& u, int wr, int wc, int fr, int fq) const {
;     ...
;             for (int m = 0; m < 4; ++m) {
;                 const int row = row0 + ai * HALF + m * 16; const float r = rinv_st(stats[row], 1.0f / 2048.0f);
;                 bf16_t* rowp = uv + (size_t)row * 4096 + col0; float ss = 0.f;
; #pragma unroll
;                 for (int bj = 0; bj < 2; ++bj) {
;                     const f32x4 v0 = acc[ai][bj][m][0] * r + bv[bj][0], v1 = acc[ai][bj][m][1] * r + bv[bj][1];
;                     const f32x2 a = gelu_pk((f32x2){v0[0], v0[1]}), b = gelu_pk((f32x2){v0[2], v0[3]}), c = gelu_pk((f32x2){v1[0], v1[1]}), d = gelu_pk((f32x2){v1[2], v1[3]});
.LBB0_879:
	s_or_b64 exec, exec, s[30:31]
	s_nop 1
	v_mov_b64_e32 v[26:27], v[220:221]
	s_mov_b32 s30, 0xbf38aa3b
	v_add_u32_e32 v24, 0xb0, v156
	s_waitcnt lgkmcnt(0)
	v_ashrrev_i32_e32 v25, 31, v24
	v_cvt_f64_u32_e32 v[28:29], v27
	v_ldexp_f64 v[28:29], v[28:29], 32
	v_cvt_f64_u32_e32 v[26:27], v26
	v_add_f64 v[26:27], v[28:29], v[26:27]
	v_ldexp_f64 v[26:27], v[26:27], s93
	v_cvt_f32_f64_e32 v26, v[26:27]
	v_fmamk_f32 v26, v26, 0x3a000000, v189
	v_cmp_gt_f32_e32 vcc, s78, v26
	v_mul_f32_e32 v27, 0x4b800000, v26
	s_nop 0
	v_cndmask_b32_e32 v26, v26, v27, vcc
	v_rsq_f32_e32 v26, v26
	s_nop 0
	v_mul_f32_e32 v27, 0x45800000, v26
	v_cndmask_b32_e32 v28, v26, v27, vcc
	v_pk_fma_f32 v[30:31], v[20:21], v[28:29], v[36:37] op_sel_hi:[1,0,1]
	v_pk_fma_f32 v[20:21], v[16:17], v[28:29], v[32:33] op_sel_hi:[1,0,1]
	v_and_b32_e32 v17, 0x7fffffff, v31
	v_and_b32_e32 v16, 0x7fffffff, v30
	v_pk_fma_f32 v[16:17], v[16:17], s[64:65], 1.0 op_sel_hi:[1,0,0]
	v_pk_mul_f32 v[36:37], v[30:31], v[30:31]
	v_rcp_f32_e32 v32, v16
	v_rcp_f32_e32 v33, v17
	v_mov_b64_e32 v[16:17], s[80:81]
	v_pk_fma_f32 v[18:19], v[18:19], v[28:29], v[34:35] op_sel_hi:[1,0,1]
	v_pk_mul_f32 v[36:37], v[36:37], s[30:31] op_sel_hi:[1,0]
	v_pk_fma_f32 v[34:35], v[32:33], s[74:75], v[16:17] op_sel_hi:[1,0,0]
	v_exp_f32_e32 v36, v36
	v_pk_fma_f32 v[34:35], v[32:33], v[34:35], s[86:87] op_sel_hi:[1,1,0]
	v_exp_f32_e32 v37, v37
	v_pk_fma_f32 v[34:35], v[32:33], v[34:35], s[0:1] op_sel_hi:[1,1,0]
	v_cmp_gt_f32_e32 vcc, 0, v30
	v_pk_fma_f32 v[34:35], v[32:33], v[34:35], s[4:5] op_sel_hi:[1,1,0]
	v_pk_fma_f32 v[22:23], v[22:23], v[28:29], v[38:39] op_sel_hi:[1,0,1]
	v_pk_mul_f32 v[32:33], v[32:33], v[34:35]
	v_pk_mul_f32 v[34:35], v[22:23], v[22:23]
	v_pk_mul_f32 v[32:33], v[36:37], v[32:33]
	v_pk_mul_f32 v[34:35], v[34:35], s[30:31] op_sel_hi:[1,0]
	v_pk_mul_f32 v[36:37], v[30:31], v[32:33]
	v_pk_fma_f32 v[32:33], v[30:31], v[32:33], v[30:31] neg_lo:[1,0,0] neg_hi:[1,0,0]
	v_exp_f32_e32 v34, v34
	v_cndmask_b32_e32 v29, v32, v36, vcc
	v_cmp_gt_f32_e32 vcc, 0, v31
	v_and_b32_e32 v32, 0x7fffffff, v22
	v_exp_f32_e32 v35, v35
	v_cndmask_b32_e32 v30, v33, v37, vcc
	v_and_b32_e32 v33, 0x7fffffff, v23
	v_pk_fma_f32 v[32:33], v[32:33], s[64:65], 1.0 op_sel_hi:[1,0,0]
	v_cmp_gt_f32_e32 vcc, 0, v22
	v_rcp_f32_e32 v32, v32
	v_rcp_f32_e32 v33, v33
	v_pk_fma_f32 v[4:5], v[4:5], v[28:29], v[12:13] op_sel_hi:[1,0,1]
	v_pk_fma_f32 v[0:1], v[0:1], v[28:29], v[8:9] op_sel_hi:[1,0,1]
	v_and_b32_e32 v9, 0x7fffffff, v5
	v_pk_fma_f32 v[36:37], v[32:33], s[74:75], v[16:17] op_sel_hi:[1,0,0]
	v_and_b32_e32 v8, 0x7fffffff, v4
	v_pk_fma_f32 v[36:37], v[32:33], v[36:37], s[86:87] op_sel_hi:[1,1,0]
	v_pk_fma_f32 v[8:9], v[8:9], s[64:65], 1.0 op_sel_hi:[1,0,0]
	v_pk_fma_f32 v[36:37], v[32:33], v[36:37], s[0:1] op_sel_hi:[1,1,0]
	v_rcp_f32_e32 v8, v8
	v_pk_fma_f32 v[36:37], v[32:33], v[36:37], s[4:5] op_sel_hi:[1,1,0]
	v_rcp_f32_e32 v9, v9
	v_pk_mul_f32 v[32:33], v[32:33], v[36:37]
	v_pk_mul_f32 v[36:37], v[20:21], v[20:21]
	v_pk_mul_f32 v[32:33], v[34:35], v[32:33]
	v_pk_mul_f32 v[36:37], v[36:37], s[30:31] op_sel_hi:[1,0]
	v_pk_mul_f32 v[34:35], v[22:23], v[32:33]
	v_pk_fma_f32 v[32:33], v[22:23], v[32:33], v[22:23] neg_lo:[1,0,0] neg_hi:[1,0,0]
	v_exp_f32_e32 v36, v36
	v_cndmask_b32_e32 v22, v32, v34, vcc
	v_cmp_gt_f32_e32 vcc, 0, v23
	v_and_b32_e32 v32, 0x7fffffff, v20
	v_exp_f32_e32 v37, v37
	v_cndmask_b32_e32 v23, v33, v35, vcc
	v_and_b32_e32 v33, 0x7fffffff, v21
	v_pk_fma_f32 v[32:33], v[32:33], s[64:65], 1.0 op_sel_hi:[1,0,0]
	v_cmp_gt_f32_e32 vcc, 0, v20
	v_rcp_f32_e32 v32, v32
	v_rcp_f32_e32 v33, v33
	v_pk_mul_f32 v[12:13], v[4:5], v[4:5]
	v_pk_fma_f32 v[2:3], v[2:3], v[28:29], v[10:11] op_sel_hi:[1,0,1]
	v_pk_fma_f32 v[10:11], v[8:9], s[74:75], v[16:17] op_sel_hi:[1,0,0]
	v_pk_fma_f32 v[34:35], v[32:33], s[74:75], v[16:17] op_sel_hi:[1,0,0]
	v_pk_mul_f32 v[12:13], v[12:13], s[30:31] op_sel_hi:[1,0]
	v_pk_fma_f32 v[34:35], v[32:33], v[34:35], s[86:87] op_sel_hi:[1,1,0]
	v_pk_fma_f32 v[10:11], v[8:9], v[10:11], s[86:87] op_sel_hi:[1,1,0]
	v_pk_fma_f32 v[34:35], v[32:33], v[34:35], s[0:1] op_sel_hi:[1,1,0]
	v_exp_f32_e32 v12, v12
	v_pk_fma_f32 v[34:35], v[32:33], v[34:35], s[4:5] op_sel_hi:[1,1,0]
	v_exp_f32_e32 v13, v13
	v_pk_mul_f32 v[32:33], v[32:33], v[34:35]
	v_pk_mul_f32 v[34:35], v[18:19], v[18:19]
	v_pk_mul_f32 v[32:33], v[36:37], v[32:33]
	v_pk_fma_f32 v[10:11], v[8:9], v[10:11], s[0:1] op_sel_hi:[1,1,0]
	v_pk_mul_f32 v[36:37], v[20:21], v[32:33]
	v_pk_fma_f32 v[32:33], v[20:21], v[32:33], v[20:21] neg_lo:[1,0,0] neg_hi:[1,0,0]
	v_and_b32_e32 v20, 0x7fffffff, v18
	v_cndmask_b32_e32 v31, v32, v36, vcc
	v_cmp_gt_f32_e32 vcc, 0, v21
	v_and_b32_e32 v21, 0x7fffffff, v19
	v_pk_fma_f32 v[20:21], v[20:21], s[64:65], 1.0 op_sel_hi:[1,0,0]
	v_cndmask_b32_e32 v36, v33, v37, vcc
	v_rcp_f32_e32 v20, v20
	v_rcp_f32_e32 v21, v21
	v_pk_fma_f32 v[10:11], v[8:9], v[10:11], s[4:5] op_sel_hi:[1,1,0]
	v_cmp_gt_f32_e32 vcc, 0, v18
	v_pk_mul_f32 v[8:9], v[8:9], v[10:11]
	v_pk_fma_f32 v[32:33], v[20:21], s[74:75], v[16:17] op_sel_hi:[1,0,0]
	v_pk_mul_f32 v[8:9], v[12:13], v[8:9]
	v_pk_fma_f32 v[32:33], v[20:21], v[32:33], s[86:87] op_sel_hi:[1,1,0]
	v_pk_fma_f32 v[6:7], v[6:7], v[28:29], v[14:15] op_sel_hi:[1,0,1]
; __device__ __forceinline__ unsigned cvt_pk_bf16(float lo, float hi) { unsigned r; asm volatile("v_cvt_pk_bf16_f32 %0, %1, %2" : "=v"(r) : "v"(lo), "v"(hi)); return r; }
; __device__ __forceinline__ float rinv_st(stat_t s, float invn) { return rsqrtf((float)((double)s * (1.0 / 4294967296.0)) * invn + 1e-6f); }
; __device__ __forceinline__ void stat_add(stat_t* p, float ss) { __hip_atomic_fetch_add(p, (stat_t)((double)ss * 4294967296.0), __ATOMIC_RELAXED, __HIP_MEMORY_SCOPE_AGENT); }
; __device__ __forceinline__ f32x2 gelu_pk(f32x2 v) {
;     const f32x2 av = __builtin_elementwise_abs(v), d = av * 0.2316418882f + 1.0f;
;     f32x2 t; t.x = __builtin_amdgcn_rcpf(d.x); t.y = __builtin_amdgcn_rcpf(d.y);
;     f32x2 q = t * 0.5307027145f + (-0.7265760135f); q = q * t + 0.7107068705f; q = q * t + (-0.142248368f); q = q * t + 0.127414796f; q = q * t;
;     const f32x2 s = (v * v) * (-0.72134752044f);
;     f32x2 e; e.x = __builtin_amdgcn_exp2f(s.x); e.y = __builtin_amdgcn_exp2f(s.y);
;     const f32x2 m = v * (q * e), r = v - m;
;     f32x2 o; o.x = v.x < 0.f ? m.x : r.x; o.y = v.y < 0.f ? m.y : r.y; return o;
;     __device__ __forceinline__ void operator()(const f32x4 (&acc)[2][2][4][2], const Unit& u, int wr, int wc, int fr, int fq) const {
;     ...
;                 const int row = row0 + ai * HALF + m * 16; const float r = rinv_st(stats[row], 1.0f / 2048.0f);
;                 bf16_t* rowp = uv + (size_t)row * 4096 + col0; float ss = 0.f;
; #pragma unroll
;                 for (int bj = 0; bj < 2; ++bj) {
;                     const f32x4 v0 = acc[ai][bj][m][0] * r + bv[bj][0], v1 = acc[ai][bj][m][1] * r + bv[bj][1];
;                     const f32x2 a = gelu_pk((f32x2){v0[0], v0[1]}), b = gelu_pk((f32x2){v0[2], v0[3]}), c = gelu_pk((f32x2){v1[0], v1[1]}), d = gelu_pk((f32x2){v1[2], v1[3]});
;                     ss += a.x * a.x + a.y * a.y + b.x * b.x + b.y * b.y + c.x * c.x + c.y * c.y + d.x * d.x + d.y * d.y;
;                     u32x4 w; w.x = cvt_pk_bf16(a.x, a.y); w.y = cvt_pk_bf16(b.x, b.y); w.z = cvt_pk_bf16(c.x, c.y); w.w = cvt_pk_bf16(d.x, d.y);
;                     *(u32x4*)(rowp + bj * HALF) = w;
;                 }
;                 ss += __shfl_xor(ss, 16); ss += __shfl_xor(ss, 32);
;                 if (isv && fq == 0) stat_add(stats_v + row, ss);
	v_pk_fma_f32 v[32:33], v[20:21], v[32:33], s[0:1] op_sel_hi:[1,1,0]
	v_pk_mul_f32 v[12:13], v[4:5], v[8:9]
	v_pk_fma_f32 v[32:33], v[20:21], v[32:33], s[4:5] op_sel_hi:[1,1,0]
	v_pk_fma_f32 v[8:9], v[4:5], v[8:9], v[4:5] neg_lo:[1,0,0] neg_hi:[1,0,0]
	v_pk_mul_f32 v[20:21], v[20:21], v[32:33]
	v_pk_mul_f32 v[32:33], v[34:35], s[30:31] op_sel_hi:[1,0]
	v_pk_mul_f32 v[10:11], v[6:7], v[6:7]
	v_exp_f32_e32 v32, v32
	v_exp_f32_e32 v33, v33
	v_lshlrev_b64 v[26:27], 13, v[24:25]
	v_lshl_add_u64 v[26:27], s[14:15], 0, v[26:27]
	v_lshl_add_u64 v[26:27], v[154:155], 1, v[26:27]
	v_pk_mul_f32 v[20:21], v[32:33], v[20:21]
	s_nop 0
	v_pk_mul_f32 v[32:33], v[18:19], v[20:21]
	v_pk_fma_f32 v[20:21], v[18:19], v[20:21], v[18:19] neg_lo:[1,0,0] neg_hi:[1,0,0]
	v_cvt_pk_bf16_f32 v18, v29, v30
	s_nop 0
	v_cndmask_b32_e32 v32, v20, v32, vcc
	v_cmp_gt_f32_e32 vcc, 0, v19
	v_cvt_pk_bf16_f32 v19, v22, v23
	v_cvt_pk_bf16_f32 v20, v31, v36
	s_nop 1
	v_cndmask_b32_e32 v21, v21, v33, vcc
	v_cmp_gt_f32_e32 vcc, 0, v4
	v_and_b32_e32 v4, 0x7fffffff, v6
	v_mul_f32_e32 v33, v30, v30
	v_cndmask_b32_e32 v12, v8, v12, vcc
	v_cmp_gt_f32_e32 vcc, 0, v5
	v_and_b32_e32 v5, 0x7fffffff, v7
	v_pk_fma_f32 v[4:5], v[4:5], s[64:65], 1.0 op_sel_hi:[1,0,0]
	v_cndmask_b32_e32 v13, v9, v13, vcc
	v_rcp_f32_e32 v4, v4
	v_rcp_f32_e32 v5, v5
	v_cmp_gt_f32_e32 vcc, 0, v6
	v_fmac_f32_e32 v33, v29, v29
	v_fmac_f32_e32 v33, v22, v22
	v_pk_fma_f32 v[8:9], v[4:5], s[74:75], v[16:17] op_sel_hi:[1,0,0]
	v_fmac_f32_e32 v33, v23, v23
	v_pk_fma_f32 v[8:9], v[4:5], v[8:9], s[86:87] op_sel_hi:[1,1,0]
	v_fmac_f32_e32 v33, v31, v31
	v_pk_fma_f32 v[8:9], v[4:5], v[8:9], s[0:1] op_sel_hi:[1,1,0]
	v_fmac_f32_e32 v33, v36, v36
	v_pk_fma_f32 v[8:9], v[4:5], v[8:9], s[4:5] op_sel_hi:[1,1,0]
	v_fmac_f32_e32 v33, v32, v32
	v_pk_mul_f32 v[4:5], v[4:5], v[8:9]
	v_pk_mul_f32 v[8:9], v[10:11], s[30:31] op_sel_hi:[1,0]
	v_fmac_f32_e32 v33, v21, v21
	v_exp_f32_e32 v8, v8
	v_exp_f32_e32 v9, v9
	v_cvt_pk_bf16_f32 v21, v32, v21
	global_store_dwordx4 v[26:27], v[18:21], off
	v_pk_mul_f32 v[4:5], v[8:9], v[4:5]
	s_nop 0
	v_pk_mul_f32 v[8:9], v[6:7], v[4:5]
	v_pk_fma_f32 v[4:5], v[6:7], v[4:5], v[6:7] neg_lo:[1,0,0] neg_hi:[1,0,0]
	s_nop 0
	v_cndmask_b32_e32 v10, v4, v8, vcc
	v_cmp_gt_f32_e32 vcc, 0, v7
	v_and_b32_e32 v4, 0x7fffffff, v0
	s_nop 0
	v_cndmask_b32_e32 v11, v5, v9, vcc
	v_and_b32_e32 v5, 0x7fffffff, v1
	v_pk_fma_f32 v[4:5], v[4:5], s[64:65], 1.0 op_sel_hi:[1,0,0]
	v_pk_mul_f32 v[8:9], v[0:1], v[0:1]
	v_rcp_f32_e32 v4, v4
	v_rcp_f32_e32 v5, v5
	v_pk_mul_f32 v[8:9], v[8:9], s[30:31] op_sel_hi:[1,0]
	v_cmp_gt_f32_e32 vcc, 0, v0
	v_exp_f32_e32 v8, v8
	v_pk_fma_f32 v[6:7], v[4:5], s[74:75], v[16:17] op_sel_hi:[1,0,0]
	v_exp_f32_e32 v9, v9
	v_pk_fma_f32 v[6:7], v[4:5], v[6:7], s[86:87] op_sel_hi:[1,1,0]
	s_nop 0
	v_pk_fma_f32 v[6:7], v[4:5], v[6:7], s[0:1] op_sel_hi:[1,1,0]
	s_nop 0
	v_pk_fma_f32 v[6:7], v[4:5], v[6:7], s[4:5] op_sel_hi:[1,1,0]
	s_nop 0
	v_pk_mul_f32 v[4:5], v[4:5], v[6:7]
	v_pk_mul_f32 v[6:7], v[2:3], v[2:3]
	v_pk_mul_f32 v[4:5], v[8:9], v[4:5]
	s_nop 0
	v_pk_mul_f32 v[8:9], v[0:1], v[4:5]
	v_pk_fma_f32 v[4:5], v[0:1], v[4:5], v[0:1] neg_lo:[1,0,0] neg_hi:[1,0,0]
	v_and_b32_e32 v0, 0x7fffffff, v2
	v_cndmask_b32_e32 v8, v4, v8, vcc
	v_cmp_gt_f32_e32 vcc, 0, v1
	v_and_b32_e32 v1, 0x7fffffff, v3
	v_pk_fma_f32 v[0:1], v[0:1], s[64:65], 1.0 op_sel_hi:[1,0,0]
	v_cndmask_b32_e32 v9, v5, v9, vcc
	v_rcp_f32_e32 v0, v0
	v_rcp_f32_e32 v1, v1
	v_cmp_gt_f32_e32 vcc, 0, v2
	v_pk_fma_f32 v[4:5], v[0:1], s[74:75], v[16:17] op_sel_hi:[1,0,0]
	s_nop 0
	v_pk_fma_f32 v[4:5], v[0:1], v[4:5], s[86:87] op_sel_hi:[1,1,0]
	s_nop 0
	v_pk_fma_f32 v[4:5], v[0:1], v[4:5], s[0:1] op_sel_hi:[1,1,0]
	s_nop 0
	v_pk_fma_f32 v[4:5], v[0:1], v[4:5], s[4:5] op_sel_hi:[1,1,0]
	s_nop 0
	v_pk_mul_f32 v[0:1], v[0:1], v[4:5]
	v_pk_mul_f32 v[4:5], v[6:7], s[30:31] op_sel_hi:[1,0]
	s_nop 0
	v_exp_f32_e32 v4, v4
	v_exp_f32_e32 v5, v5
	s_nop 0
	v_pk_mul_f32 v[0:1], v[4:5], v[0:1]
	s_nop 0
	v_pk_mul_f32 v[4:5], v[2:3], v[0:1]
	v_pk_fma_f32 v[0:1], v[2:3], v[0:1], v[2:3] neg_lo:[1,0,0] neg_hi:[1,0,0]
	s_nop 0
	v_cndmask_b32_e32 v4, v0, v4, vcc
	v_mul_f32_e32 v0, v13, v13
	v_fmac_f32_e32 v0, v12, v12
	v_fmac_f32_e32 v0, v10, v10
	v_fmac_f32_e32 v0, v11, v11
	v_fmac_f32_e32 v0, v8, v8
	v_cmp_gt_f32_e32 vcc, 0, v3
	v_fmac_f32_e32 v0, v9, v9
	v_fmac_f32_e32 v0, v4, v4
	v_cndmask_b32_e32 v3, v1, v5, vcc
	v_fmac_f32_e32 v0, v3, v3
	v_add_f32_e32 v5, v33, v0
	v_cvt_pk_bf16_f32 v0, v12, v13
	v_cvt_pk_bf16_f32 v1, v10, v11
	v_cvt_pk_bf16_f32 v2, v8, v9
	v_cvt_pk_bf16_f32 v3, v4, v3
	global_store_dwordx4 v[26:27], v[0:3], off offset:256
	ds_bpermute_b32 v0, v133, v5
	s_waitcnt lgkmcnt(0)
	v_add_f32_e32 v0, v5, v0
	ds_bpermute_b32 v1, v134, v0
	s_and_saveexec_b64 s[30:31], s[28:29]
	s_cbranch_execz .LBB0_856
	s_waitcnt lgkmcnt(0)
	v_add_f32_e32 v0, v0, v1
	v_cvt_f64_f32_e32 v[0:1], v0
	v_ldexp_f64 v[0:1], v[0:1], 32
	v_trunc_f64_e32 v[0:1], v[0:1]
	v_ldexp_f64 v[4:5], v[0:1], s93
	v_floor_f64_e32 v[4:5], v[4:5]
	v_fmac_f64_e32 v[0:1], 0xc1f00000, v[4:5]
	v_lshl_add_u64 v[2:3], v[24:25], 3, s[18:19]
	v_cvt_u32_f64_e32 v0, v[0:1]
	v_cvt_u32_f64_e32 v1, v[4:5]
	global_atomic_add_x2 v[2:3], v[0:1], off
	s_branch .LBB0_856

; __device__ __forceinline__ float bf_lo(unsigned v) { return __uint_as_float(v << 16); }
; __device__ __forceinline__ float bf_hi(unsigned v) { return __uint_as_float(v & 0xffff0000u); }
;     __device__ __forceinline__ void operator()(const f32x4 (&acc)[2][2][4][2], const Unit& u, int wr, int wc, int fr, int fq) const {
;     ...
;                 const int row = row0 + ai * HALF + m * 16; const size_t ro = (size_t)row * D + col0; float ss = 0.f;
; #pragma unroll
;                 for (int bj = 0; bj < 2; ++bj) {
;                     const size_t o = ro + bj * HALF;
;                     f32x4 s0, s1;
;                     if (srcf) { s0 = *(const f32x4*)(srcf + o); s1 = *(const f32x4*)(srcf + o + 4); }
;                     else { const u32x4 w = *(const u32x4*)(srcb + o); s0 = (f32x4){bf_lo(w.x), bf_hi(w.x), bf_lo(w.y), bf_hi(w.y)}; s1 = (f32x4){bf_lo(w.z), bf_hi(w.z), bf_lo(w.w), bf_hi(w.w)}; }
;                     const f32x4 v0 = acc[ai][bj][m][0] * cs[bj][0] + s0, v1 = acc[ai][bj][m][1] * cs[bj][1] + s1;
.LBB0_964:
	v_lshl_add_u32 v170, s54, 8, v197
	v_ashrrev_i32_e32 v171, 31, v170
	v_lshlrev_b64 v[144:145], 11, v[170:171]
	v_lshl_add_u64 v[172:173], v[144:145], 0, v[174:175]
	v_cndmask_b32_e64 v144, 0, 1, s[42:43]
	v_cmp_ne_u32_e64 s[12:13], 1, v144
	s_andn2_b64 vcc, exec, s[42:43]
	v_lshl_add_u64 v[180:181], v[172:173], 2, s[28:29]
	s_cbranch_vccnz .LBB0_1107
	v_lshlrev_b32_e32 v178, 2, v172
	global_load_dwordx4 v[212:215], v178, s[28:29] offset:16
	global_load_dwordx4 v[208:211], v178, s[28:29]
	global_load_dwordx4 v[220:223], v178, s[28:29] offset:528
	global_load_dwordx4 v[216:219], v178, s[28:29] offset:512
	v_add_u32_e32 v179, 0x20000, v178
	global_load_dwordx4 v[228:231], v179, s[28:29] offset:16
	global_load_dwordx4 v[224:227], v179, s[28:29]
	global_load_dwordx4 v[246:249], v179, s[28:29] offset:528
	global_load_dwordx4 v[232:235], v179, s[28:29] offset:512
	s_waitcnt vmcnt(6)
	v_mov_b64_e32 v[148:149], v[208:209]
	v_mov_b64_e32 v[150:151], v[210:211]
	v_mov_b64_e32 v[144:145], v[212:213]
	v_mov_b64_e32 v[146:147], v[214:215]
	v_add_u32_e32 v179, 0x40000, v178
	global_load_dwordx4 v[212:215], v179, s[28:29] offset:16
	global_load_dwordx4 v[208:211], v179, s[28:29]
	s_cbranch_execnz .LBB0_967

; __device__ __forceinline__ float bf_lo(unsigned v) { return __uint_as_float(v << 16); }
; __device__ __forceinline__ float bf_hi(unsigned v) { return __uint_as_float(v & 0xffff0000u); }
;     __device__ __forceinline__ void operator()(const f32x4 (&acc)[2][2][4][2], const Unit& u, int wr, int wc, int fr, int fq) const {
;     ...
;                 for (int bj = 0; bj < 2; ++bj) {
;                     const size_t o = ro + bj * HALF;
;                     f32x4 s0, s1;
;                     if (srcf) { s0 = *(const f32x4*)(srcf + o); s1 = *(const f32x4*)(srcf + o + 4); }
;                     else { const u32x4 w = *(const u32x4*)(srcb + o); s0 = (f32x4){bf_lo(w.x), bf_hi(w.x), bf_lo(w.y), bf_hi(w.y)}; s1 = (f32x4){bf_lo(w.z), bf_hi(w.z), bf_lo(w.w), bf_hi(w.w)}; }
;                     const f32x4 v0 = acc[ai][bj][m][0] * cs[bj][0] + s0, v1 = acc[ai][bj][m][1] * cs[bj][1] + s1;
.LBB0_971:
	s_and_b64 vcc, exec, s[12:13]
	s_cbranch_vccnz .LBB0_1108
	s_waitcnt vmcnt(7)
	v_mov_b64_e32 v[148:149], v[216:217]
	v_mov_b64_e32 v[150:151], v[218:219]
	v_mov_b64_e32 v[144:145], v[220:221]
	v_mov_b64_e32 v[146:147], v[222:223]
	v_add_u32_e32 v179, 0x40000, v178
	global_load_dwordx4 v[220:223], v179, s[28:29] offset:528
	global_load_dwordx4 v[216:219], v179, s[28:29] offset:512
	s_cbranch_execnz .LBB0_974

; __device__ __forceinline__ float bf_lo(unsigned v) { return __uint_as_float(v << 16); }
; __device__ __forceinline__ float bf_hi(unsigned v) { return __uint_as_float(v & 0xffff0000u); }
;     __device__ __forceinline__ void operator()(const f32x4 (&acc)[2][2][4][2], const Unit& u, int wr, int wc, int fr, int fq) const {
;     ...
;                 const int row = row0 + ai * HALF + m * 16; const size_t ro = (size_t)row * D + col0; float ss = 0.f;
; #pragma unroll
;                 for (int bj = 0; bj < 2; ++bj) {
;                     const size_t o = ro + bj * HALF;
;                     f32x4 s0, s1;
;                     if (srcf) { s0 = *(const f32x4*)(srcf + o); s1 = *(const f32x4*)(srcf + o + 4); }
;                     else { const u32x4 w = *(const u32x4*)(srcb + o); s0 = (f32x4){bf_lo(w.x), bf_hi(w.x), bf_lo(w.y), bf_hi(w.y)}; s1 = (f32x4){bf_lo(w.z), bf_hi(w.z), bf_lo(w.w), bf_hi(w.w)}; }
;                     const f32x4 v0 = acc[ai][bj][m][0] * cs[bj][0] + s0, v1 = acc[ai][bj][m][1] * cs[bj][1] + s1;
.LBB0_982:
	v_or_b32_e32 v128, 16, v170
	s_waitcnt lgkmcnt(0)
	v_ashrrev_i32_e32 v129, 31, v128
	v_lshlrev_b64 v[128:129], 11, v[128:129]
	v_lshl_add_u64 v[136:137], v[128:129], 0, v[174:175]
	s_and_b64 vcc, exec, s[12:13]
	v_lshl_add_u64 v[142:143], v[136:137], 2, s[28:29]
	s_cbranch_vccnz .LBB0_1109
	s_waitcnt vmcnt(8)
	v_mov_b64_e32 v[132:133], v[224:225]
	v_mov_b64_e32 v[134:135], v[226:227]
	v_mov_b64_e32 v[128:129], v[228:229]
	v_mov_b64_e32 v[130:131], v[230:231]
	v_add_u32_e32 v179, 0x60000, v178
	global_load_dwordx4 v[228:231], v179, s[28:29] offset:16
	global_load_dwordx4 v[224:227], v179, s[28:29]
	v_lshl_add_u64 v[138:139], v[136:137], 1, s[84:85]
	s_cbranch_execnz .LBB0_985

; __device__ __forceinline__ float bf_lo(unsigned v) { return __uint_as_float(v << 16); }
; __device__ __forceinline__ float bf_hi(unsigned v) { return __uint_as_float(v & 0xffff0000u); }
;     __device__ __forceinline__ void operator()(const f32x4 (&acc)[2][2][4][2], const Unit& u, int wr, int wc, int fr, int fq) const {
;     ...
;                 for (int bj = 0; bj < 2; ++bj) {
;                     const size_t o = ro + bj * HALF;
;                     f32x4 s0, s1;
;                     if (srcf) { s0 = *(const f32x4*)(srcf + o); s1 = *(const f32x4*)(srcf + o + 4); }
;                     else { const u32x4 w = *(const u32x4*)(srcb + o); s0 = (f32x4){bf_lo(w.x), bf_hi(w.x), bf_lo(w.y), bf_hi(w.y)}; s1 = (f32x4){bf_lo(w.z), bf_hi(w.z), bf_lo(w.w), bf_hi(w.w)}; }
;                     const f32x4 v0 = acc[ai][bj][m][0] * cs[bj][0] + s0, v1 = acc[ai][bj][m][1] * cs[bj][1] + s1;
.LBB0_989:
	s_and_b64 vcc, exec, s[12:13]
	s_cbranch_vccnz .LBB0_1110
	s_waitcnt vmcnt(9)
	v_mov_b64_e32 v[132:133], v[232:233]
	v_mov_b64_e32 v[134:135], v[234:235]
	v_mov_b64_e32 v[128:129], v[246:247]
	v_mov_b64_e32 v[130:131], v[248:249]
	v_add_u32_e32 v179, 0x60000, v178
	global_load_dwordx4 v[246:249], v179, s[28:29] offset:528
	global_load_dwordx4 v[232:235], v179, s[28:29] offset:512
	s_cbranch_execnz .LBB0_992

; __device__ __forceinline__ float bf_lo(unsigned v) { return __uint_as_float(v << 16); }
; __device__ __forceinline__ float bf_hi(unsigned v) { return __uint_as_float(v & 0xffff0000u); }
;     __device__ __forceinline__ void operator()(const f32x4 (&acc)[2][2][4][2], const Unit& u, int wr, int wc, int fr, int fq) const {
;     ...
;                 const int row = row0 + ai * HALF + m * 16; const size_t ro = (size_t)row * D + col0; float ss = 0.f;
; #pragma unroll
;                 for (int bj = 0; bj < 2; ++bj) {
;                     const size_t o = ro + bj * HALF;
;                     f32x4 s0, s1;
;                     if (srcf) { s0 = *(const f32x4*)(srcf + o); s1 = *(const f32x4*)(srcf + o + 4); }
;                     else { const u32x4 w = *(const u32x4*)(srcb + o); s0 = (f32x4){bf_lo(w.x), bf_hi(w.x), bf_lo(w.y), bf_hi(w.y)}; s1 = (f32x4){bf_lo(w.z), bf_hi(w.z), bf_lo(w.w), bf_hi(w.w)}; }
;                     const f32x4 v0 = acc[ai][bj][m][0] * cs[bj][0] + s0, v1 = acc[ai][bj][m][1] * cs[bj][1] + s1;
.LBB0_1000:
	v_or_b32_e32 v112, 32, v170
	s_waitcnt lgkmcnt(0)
	v_ashrrev_i32_e32 v113, 31, v112
	v_lshlrev_b64 v[112:113], 11, v[112:113]
	v_lshl_add_u64 v[120:121], v[112:113], 0, v[174:175]
	s_and_b64 vcc, exec, s[12:13]
	v_lshl_add_u64 v[126:127], v[120:121], 2, s[28:29]
	s_cbranch_vccnz .LBB0_1111
	s_waitcnt vmcnt(10)
	v_mov_b64_e32 v[116:117], v[208:209]
	v_mov_b64_e32 v[118:119], v[210:211]
	v_mov_b64_e32 v[112:113], v[212:213]
	v_mov_b64_e32 v[114:115], v[214:215]
	v_add_u32_e32 v179, 0x100000, v178
	global_load_dwordx4 v[212:215], v179, s[28:29] offset:16
	global_load_dwordx4 v[208:211], v179, s[28:29]
	v_lshl_add_u64 v[122:123], v[120:121], 1, s[84:85]
	s_cbranch_execnz .LBB0_1003

; __device__ __forceinline__ float bf_lo(unsigned v) { return __uint_as_float(v << 16); }
; __device__ __forceinline__ float bf_hi(unsigned v) { return __uint_as_float(v & 0xffff0000u); }
;     __device__ __forceinline__ void operator()(const f32x4 (&acc)[2][2][4][2], const Unit& u, int wr, int wc, int fr, int fq) const {
;     ...
;                 for (int bj = 0; bj < 2; ++bj) {
;                     const size_t o = ro + bj * HALF;
;                     f32x4 s0, s1;
;                     if (srcf) { s0 = *(const f32x4*)(srcf + o); s1 = *(const f32x4*)(srcf + o + 4); }
;                     else { const u32x4 w = *(const u32x4*)(srcb + o); s0 = (f32x4){bf_lo(w.x), bf_hi(w.x), bf_lo(w.y), bf_hi(w.y)}; s1 = (f32x4){bf_lo(w.z), bf_hi(w.z), bf_lo(w.w), bf_hi(w.w)}; }
;                     const f32x4 v0 = acc[ai][bj][m][0] * cs[bj][0] + s0, v1 = acc[ai][bj][m][1] * cs[bj][1] + s1;
.LBB0_1007:
	s_and_b64 vcc, exec, s[12:13]
	s_cbranch_vccnz .LBB0_1112
	s_waitcnt vmcnt(10)
	v_mov_b64_e32 v[116:117], v[216:217]
	v_mov_b64_e32 v[118:119], v[218:219]
	v_mov_b64_e32 v[112:113], v[220:221]
	v_mov_b64_e32 v[114:115], v[222:223]
	v_add_u32_e32 v179, 0x100000, v178
	global_load_dwordx4 v[220:223], v179, s[28:29] offset:528
	global_load_dwordx4 v[216:219], v179, s[28:29] offset:512
	s_cbranch_execnz .LBB0_1010

; __device__ __forceinline__ float bf_lo(unsigned v) { return __uint_as_float(v << 16); }
; __device__ __forceinline__ float bf_hi(unsigned v) { return __uint_as_float(v & 0xffff0000u); }
;     __device__ __forceinline__ void operator()(const f32x4 (&acc)[2][2][4][2], const Unit& u, int wr, int wc, int fr, int fq) const {
;     ...
;                 const int row = row0 + ai * HALF + m * 16; const size_t ro = (size_t)row * D + col0; float ss = 0.f;
; #pragma unroll
;                 for (int bj = 0; bj < 2; ++bj) {
;                     const size_t o = ro + bj * HALF;
;                     f32x4 s0, s1;
;                     if (srcf) { s0 = *(const f32x4*)(srcf + o); s1 = *(const f32x4*)(srcf + o + 4); }
;                     else { const u32x4 w = *(const u32x4*)(srcb + o); s0 = (f32x4){bf_lo(w.x), bf_hi(w.x), bf_lo(w.y), bf_hi(w.y)}; s1 = (f32x4){bf_lo(w.z), bf_hi(w.z), bf_lo(w.w), bf_hi(w.w)}; }
;                     const f32x4 v0 = acc[ai][bj][m][0] * cs[bj][0] + s0, v1 = acc[ai][bj][m][1] * cs[bj][1] + s1;
.LBB0_1018:
	v_or_b32_e32 v96, 48, v170
	s_waitcnt lgkmcnt(0)
	v_ashrrev_i32_e32 v97, 31, v96
	v_lshlrev_b64 v[96:97], 11, v[96:97]
	v_lshl_add_u64 v[104:105], v[96:97], 0, v[174:175]
	s_and_b64 vcc, exec, s[12:13]
	v_lshl_add_u64 v[110:111], v[104:105], 2, s[28:29]
	s_cbranch_vccnz .LBB0_1113
	s_waitcnt vmcnt(10)
	v_mov_b64_e32 v[100:101], v[224:225]
	v_mov_b64_e32 v[102:103], v[226:227]
	v_mov_b64_e32 v[96:97], v[228:229]
	v_mov_b64_e32 v[98:99], v[230:231]
	v_add_u32_e32 v179, 0x120000, v178
	global_load_dwordx4 v[228:231], v179, s[28:29] offset:16
	global_load_dwordx4 v[224:227], v179, s[28:29]
	v_lshl_add_u64 v[106:107], v[104:105], 1, s[84:85]
	s_cbranch_execnz .LBB0_1021

; __device__ __forceinline__ float bf_lo(unsigned v) { return __uint_as_float(v << 16); }
; __device__ __forceinline__ float bf_hi(unsigned v) { return __uint_as_float(v & 0xffff0000u); }
;     __device__ __forceinline__ void operator()(const f32x4 (&acc)[2][2][4][2], const Unit& u, int wr, int wc, int fr, int fq) const {
;     ...
;                 for (int bj = 0; bj < 2; ++bj) {
;                     const size_t o = ro + bj * HALF;
;                     f32x4 s0, s1;
;                     if (srcf) { s0 = *(const f32x4*)(srcf + o); s1 = *(const f32x4*)(srcf + o + 4); }
;                     else { const u32x4 w = *(const u32x4*)(srcb + o); s0 = (f32x4){bf_lo(w.x), bf_hi(w.x), bf_lo(w.y), bf_hi(w.y)}; s1 = (f32x4){bf_lo(w.z), bf_hi(w.z), bf_lo(w.w), bf_hi(w.w)}; }
;                     const f32x4 v0 = acc[ai][bj][m][0] * cs[bj][0] + s0, v1 = acc[ai][bj][m][1] * cs[bj][1] + s1;
.LBB0_1025:
	s_and_b64 vcc, exec, s[12:13]
	s_cbranch_vccnz .LBB0_1114
	s_waitcnt vmcnt(10)
	v_mov_b64_e32 v[100:101], v[232:233]
	v_mov_b64_e32 v[102:103], v[234:235]
	v_mov_b64_e32 v[96:97], v[246:247]
	v_mov_b64_e32 v[98:99], v[248:249]
	v_add_u32_e32 v179, 0x120000, v178
	global_load_dwordx4 v[246:249], v179, s[28:29] offset:528
	global_load_dwordx4 v[232:235], v179, s[28:29] offset:512
	s_cbranch_execnz .LBB0_1028

; __device__ __forceinline__ float bf_lo(unsigned v) { return __uint_as_float(v << 16); }
; __device__ __forceinline__ float bf_hi(unsigned v) { return __uint_as_float(v & 0xffff0000u); }
;     __device__ __forceinline__ void operator()(const f32x4 (&acc)[2][2][4][2], const Unit& u, int wr, int wc, int fr, int fq) const {
;     ...
;                 const int row = row0 + ai * HALF + m * 16; const size_t ro = (size_t)row * D + col0; float ss = 0.f;
; #pragma unroll
;                 for (int bj = 0; bj < 2; ++bj) {
;                     const size_t o = ro + bj * HALF;
;                     f32x4 s0, s1;
;                     if (srcf) { s0 = *(const f32x4*)(srcf + o); s1 = *(const f32x4*)(srcf + o + 4); }
;                     else { const u32x4 w = *(const u32x4*)(srcb + o); s0 = (f32x4){bf_lo(w.x), bf_hi(w.x), bf_lo(w.y), bf_hi(w.y)}; s1 = (f32x4){bf_lo(w.z), bf_hi(w.z), bf_lo(w.w), bf_hi(w.w)}; }
;                     const f32x4 v0 = acc[ai][bj][m][0] * cs[bj][0] + s0, v1 = acc[ai][bj][m][1] * cs[bj][1] + s1;
.LBB0_1036:
	s_mov_b64 s[54:55], 0x40000
	v_lshl_add_u64 v[88:89], v[172:173], 0, s[54:55]
	s_and_b64 vcc, exec, s[12:13]
	v_lshl_add_u64 v[94:95], v[88:89], 2, s[28:29]
	s_cbranch_vccnz .LBB0_1115
	s_waitcnt lgkmcnt(0)
	s_waitcnt vmcnt(10)
	v_mov_b64_e32 v[84:85], v[208:209]
	v_mov_b64_e32 v[86:87], v[210:211]
	v_mov_b64_e32 v[80:81], v[212:213]
	v_mov_b64_e32 v[82:83], v[214:215]
	v_add_u32_e32 v179, 0x140000, v178
	global_load_dwordx4 v[212:215], v179, s[28:29] offset:16
	global_load_dwordx4 v[208:211], v179, s[28:29]
	v_lshl_add_u64 v[90:91], v[88:89], 1, s[84:85]
	s_cbranch_execnz .LBB0_1039

; __device__ __forceinline__ float bf_lo(unsigned v) { return __uint_as_float(v << 16); }
; __device__ __forceinline__ float bf_hi(unsigned v) { return __uint_as_float(v & 0xffff0000u); }
;     __device__ __forceinline__ void operator()(const f32x4 (&acc)[2][2][4][2], const Unit& u, int wr, int wc, int fr, int fq) const {
;     ...
;                 for (int bj = 0; bj < 2; ++bj) {
;                     const size_t o = ro + bj * HALF;
;                     f32x4 s0, s1;
;                     if (srcf) { s0 = *(const f32x4*)(srcf + o); s1 = *(const f32x4*)(srcf + o + 4); }
;                     else { const u32x4 w = *(const u32x4*)(srcb + o); s0 = (f32x4){bf_lo(w.x), bf_hi(w.x), bf_lo(w.y), bf_hi(w.y)}; s1 = (f32x4){bf_lo(w.z), bf_hi(w.z), bf_lo(w.w), bf_hi(w.w)}; }
;                     const f32x4 v0 = acc[ai][bj][m][0] * cs[bj][0] + s0, v1 = acc[ai][bj][m][1] * cs[bj][1] + s1;
.LBB0_1043:
	s_and_b64 vcc, exec, s[12:13]
	s_cbranch_vccnz .LBB0_1116
	s_waitcnt vmcnt(10)
	v_mov_b64_e32 v[84:85], v[216:217]
	v_mov_b64_e32 v[86:87], v[218:219]
	v_mov_b64_e32 v[80:81], v[220:221]
	v_mov_b64_e32 v[82:83], v[222:223]
	v_add_u32_e32 v179, 0x140000, v178
	global_load_dwordx4 v[220:223], v179, s[28:29] offset:528
	global_load_dwordx4 v[216:219], v179, s[28:29] offset:512
	s_cbranch_execnz .LBB0_1046

; __device__ __forceinline__ float bf_lo(unsigned v) { return __uint_as_float(v << 16); }
; __device__ __forceinline__ float bf_hi(unsigned v) { return __uint_as_float(v & 0xffff0000u); }
;     __device__ __forceinline__ void operator()(const f32x4 (&acc)[2][2][4][2], const Unit& u, int wr, int wc, int fr, int fq) const {
;     ...
;                 const int row = row0 + ai * HALF + m * 16; const size_t ro = (size_t)row * D + col0; float ss = 0.f;
; #pragma unroll
;                 for (int bj = 0; bj < 2; ++bj) {
;                     const size_t o = ro + bj * HALF;
;                     f32x4 s0, s1;
;                     if (srcf) { s0 = *(const f32x4*)(srcf + o); s1 = *(const f32x4*)(srcf + o + 4); }
;                     else { const u32x4 w = *(const u32x4*)(srcb + o); s0 = (f32x4){bf_lo(w.x), bf_hi(w.x), bf_lo(w.y), bf_hi(w.y)}; s1 = (f32x4){bf_lo(w.z), bf_hi(w.z), bf_lo(w.w), bf_hi(w.w)}; }
;                     const f32x4 v0 = acc[ai][bj][m][0] * cs[bj][0] + s0, v1 = acc[ai][bj][m][1] * cs[bj][1] + s1;
.LBB0_1054:
	s_mov_b64 s[54:55], 0x48000
	v_lshl_add_u64 v[72:73], v[172:173], 0, s[54:55]
	s_and_b64 vcc, exec, s[12:13]
	v_lshl_add_u64 v[78:79], v[72:73], 2, s[28:29]
	s_cbranch_vccnz .LBB0_1117
	s_waitcnt lgkmcnt(0)
	s_waitcnt vmcnt(10)
	v_mov_b64_e32 v[64:65], v[224:225]
	v_mov_b64_e32 v[66:67], v[226:227]
	v_mov_b64_e32 v[56:57], v[228:229]
	v_mov_b64_e32 v[58:59], v[230:231]
	v_add_u32_e32 v179, 0x160000, v178
	global_load_dwordx4 v[228:231], v179, s[28:29] offset:16
	global_load_dwordx4 v[224:227], v179, s[28:29]
	v_lshl_add_u64 v[74:75], v[72:73], 1, s[84:85]
	s_cbranch_execnz .LBB0_1057

; __device__ __forceinline__ float bf_lo(unsigned v) { return __uint_as_float(v << 16); }
; __device__ __forceinline__ float bf_hi(unsigned v) { return __uint_as_float(v & 0xffff0000u); }
;     __device__ __forceinline__ void operator()(const f32x4 (&acc)[2][2][4][2], const Unit& u, int wr, int wc, int fr, int fq) const {
;     ...
;                 for (int bj = 0; bj < 2; ++bj) {
;                     const size_t o = ro + bj * HALF;
;                     f32x4 s0, s1;
;                     if (srcf) { s0 = *(const f32x4*)(srcf + o); s1 = *(const f32x4*)(srcf + o + 4); }
;                     else { const u32x4 w = *(const u32x4*)(srcb + o); s0 = (f32x4){bf_lo(w.x), bf_hi(w.x), bf_lo(w.y), bf_hi(w.y)}; s1 = (f32x4){bf_lo(w.z), bf_hi(w.z), bf_lo(w.w), bf_hi(w.w)}; }
;                     const f32x4 v0 = acc[ai][bj][m][0] * cs[bj][0] + s0, v1 = acc[ai][bj][m][1] * cs[bj][1] + s1;
.LBB0_1061:
	s_and_b64 vcc, exec, s[12:13]
	s_cbranch_vccnz .LBB0_1118
	s_waitcnt vmcnt(10)
	v_mov_b64_e32 v[64:65], v[232:233]
	v_mov_b64_e32 v[66:67], v[234:235]
	v_mov_b64_e32 v[56:57], v[246:247]
	v_mov_b64_e32 v[58:59], v[248:249]
	v_add_u32_e32 v179, 0x160000, v178
	global_load_dwordx4 v[246:249], v179, s[28:29] offset:528
	global_load_dwordx4 v[232:235], v179, s[28:29] offset:512
	s_cbranch_execnz .LBB0_1064

; __device__ __forceinline__ float bf_lo(unsigned v) { return __uint_as_float(v << 16); }
; __device__ __forceinline__ float bf_hi(unsigned v) { return __uint_as_float(v & 0xffff0000u); }
;     __device__ __forceinline__ void operator()(const f32x4 (&acc)[2][2][4][2], const Unit& u, int wr, int wc, int fr, int fq) const {
;     ...
;                 const int row = row0 + ai * HALF + m * 16; const size_t ro = (size_t)row * D + col0; float ss = 0.f;
; #pragma unroll
;                 for (int bj = 0; bj < 2; ++bj) {
;                     const size_t o = ro + bj * HALF;
;                     f32x4 s0, s1;
;                     if (srcf) { s0 = *(const f32x4*)(srcf + o); s1 = *(const f32x4*)(srcf + o + 4); }
;                     else { const u32x4 w = *(const u32x4*)(srcb + o); s0 = (f32x4){bf_lo(w.x), bf_hi(w.x), bf_lo(w.y), bf_hi(w.y)}; s1 = (f32x4){bf_lo(w.z), bf_hi(w.z), bf_lo(w.w), bf_hi(w.w)}; }
;                     const f32x4 v0 = acc[ai][bj][m][0] * cs[bj][0] + s0, v1 = acc[ai][bj][m][1] * cs[bj][1] + s1;
.LBB0_1072:
	s_mov_b64 s[54:55], 0x50000
	v_lshl_add_u64 v[40:41], v[172:173], 0, s[54:55]
	s_and_b64 vcc, exec, s[12:13]
	v_lshl_add_u64 v[46:47], v[40:41], 2, s[28:29]
	s_cbranch_vccnz .LBB0_1119
	s_waitcnt lgkmcnt(0)
	s_waitcnt vmcnt(10)
	v_mov_b64_e32 v[36:37], v[208:209]
	v_mov_b64_e32 v[38:39], v[210:211]
	v_mov_b64_e32 v[32:33], v[212:213]
	v_mov_b64_e32 v[34:35], v[214:215]
	v_lshl_add_u64 v[42:43], v[40:41], 1, s[84:85]
	s_cbranch_execnz .LBB0_1075

; __device__ __forceinline__ float bf_lo(unsigned v) { return __uint_as_float(v << 16); }
; __device__ __forceinline__ float bf_hi(unsigned v) { return __uint_as_float(v & 0xffff0000u); }
;     __device__ __forceinline__ void operator()(const f32x4 (&acc)[2][2][4][2], const Unit& u, int wr, int wc, int fr, int fq) const {
;     ...
;                 for (int bj = 0; bj < 2; ++bj) {
;                     const size_t o = ro + bj * HALF;
;                     f32x4 s0, s1;
;                     if (srcf) { s0 = *(const f32x4*)(srcf + o); s1 = *(const f32x4*)(srcf + o + 4); }
;                     else { const u32x4 w = *(const u32x4*)(srcb + o); s0 = (f32x4){bf_lo(w.x), bf_hi(w.x), bf_lo(w.y), bf_hi(w.y)}; s1 = (f32x4){bf_lo(w.z), bf_hi(w.z), bf_lo(w.w), bf_hi(w.w)}; }
;                     const f32x4 v0 = acc[ai][bj][m][0] * cs[bj][0] + s0, v1 = acc[ai][bj][m][1] * cs[bj][1] + s1;
.LBB0_1079:
	s_and_b64 vcc, exec, s[12:13]
	s_cbranch_vccnz .LBB0_1120
	s_waitcnt vmcnt(8)
	v_mov_b64_e32 v[36:37], v[216:217]
	v_mov_b64_e32 v[38:39], v[218:219]
	v_mov_b64_e32 v[32:33], v[220:221]
	v_mov_b64_e32 v[34:35], v[222:223]
	s_cbranch_execnz .LBB0_1082

; __device__ __forceinline__ float bf_lo(unsigned v) { return __uint_as_float(v << 16); }
; __device__ __forceinline__ float bf_hi(unsigned v) { return __uint_as_float(v & 0xffff0000u); }
;     __device__ __forceinline__ void operator()(const f32x4 (&acc)[2][2][4][2], const Unit& u, int wr, int wc, int fr, int fq) const {
;     ...
;                 const int row = row0 + ai * HALF + m * 16; const size_t ro = (size_t)row * D + col0; float ss = 0.f;
; #pragma unroll
;                 for (int bj = 0; bj < 2; ++bj) {
;                     const size_t o = ro + bj * HALF;
;                     f32x4 s0, s1;
;                     if (srcf) { s0 = *(const f32x4*)(srcf + o); s1 = *(const f32x4*)(srcf + o + 4); }
;                     else { const u32x4 w = *(const u32x4*)(srcb + o); s0 = (f32x4){bf_lo(w.x), bf_hi(w.x), bf_lo(w.y), bf_hi(w.y)}; s1 = (f32x4){bf_lo(w.z), bf_hi(w.z), bf_lo(w.w), bf_hi(w.w)}; }
;                     const f32x4 v0 = acc[ai][bj][m][0] * cs[bj][0] + s0, v1 = acc[ai][bj][m][1] * cs[bj][1] + s1;
.LBB0_1090:
	s_mov_b64 s[54:55], 0x58000
	v_lshl_add_u64 v[24:25], v[172:173], 0, s[54:55]
	s_and_b64 vcc, exec, s[12:13]
	v_lshl_add_u64 v[30:31], v[24:25], 2, s[28:29]
	s_cbranch_vccnz .LBB0_1121
	s_waitcnt lgkmcnt(0)
	s_waitcnt vmcnt(6)
	v_mov_b64_e32 v[20:21], v[224:225]
	v_mov_b64_e32 v[22:23], v[226:227]
	v_mov_b64_e32 v[16:17], v[228:229]
	v_mov_b64_e32 v[18:19], v[230:231]
	v_lshl_add_u64 v[26:27], v[24:25], 1, s[84:85]
	s_cbranch_execnz .LBB0_1093

; __device__ __forceinline__ float bf_lo(unsigned v) { return __uint_as_float(v << 16); }
; __device__ __forceinline__ float bf_hi(unsigned v) { return __uint_as_float(v & 0xffff0000u); }
;     __device__ __forceinline__ void operator()(const f32x4 (&acc)[2][2][4][2], const Unit& u, int wr, int wc, int fr, int fq) const {
;     ...
;                 for (int bj = 0; bj < 2; ++bj) {
;                     const size_t o = ro + bj * HALF;
;                     f32x4 s0, s1;
;                     if (srcf) { s0 = *(const f32x4*)(srcf + o); s1 = *(const f32x4*)(srcf + o + 4); }
;                     else { const u32x4 w = *(const u32x4*)(srcb + o); s0 = (f32x4){bf_lo(w.x), bf_hi(w.x), bf_lo(w.y), bf_hi(w.y)}; s1 = (f32x4){bf_lo(w.z), bf_hi(w.z), bf_lo(w.w), bf_hi(w.w)}; }
;                     const f32x4 v0 = acc[ai][bj][m][0] * cs[bj][0] + s0, v1 = acc[ai][bj][m][1] * cs[bj][1] + s1;
.LBB0_1097:
	s_and_b64 vcc, exec, s[12:13]
	s_cbranch_vccnz .LBB0_1122
	s_waitcnt vmcnt(4)
	v_mov_b64_e32 v[20:21], v[232:233]
	v_mov_b64_e32 v[22:23], v[234:235]
	v_mov_b64_e32 v[16:17], v[246:247]
	v_mov_b64_e32 v[18:19], v[248:249]
	s_cbranch_execnz .LBB0_1100
